# EpiRes epilogues (FFN down, W_out, cross out): the 16 residual-tile loads issued together at K-loop exit instead of one round trip each
# baseline (speedup 1.0000x reference)
; #define PG8_STAGE(bufoff, gbase, voff) do { _Pragma("unroll") for (int _i = 0; _i < 2; ++_i) \
;         __builtin_amdgcn_global_load_lds((const unsigned*)((const char*)(gbase) + (voff)[_i]), (PG8_LAS unsigned*)(lds + (bufoff) + ldsw + _i * 8192), 16, 0, 0); } while (0)
; #define PG8_LDA(dst, b, h) do { _Pragma("unroll") for (int m = 0; m < 4; ++m) _Pragma("unroll") for (int k = 0; k < 2; ++k) dst[m][k] = *(const PG8_LAS bf16x8*)(lds + PG8_SA(b, h) + aoff + m * 2048 + k * 1024); } while (0)
; #define PG8_LDB(dst, b, h) do { _Pragma("unroll") for (int n = 0; n < 2; ++n) _Pragma("unroll") for (int k = 0; k < 2; ++k) dst[n][k] = *(const PG8_LAS bf16x8*)(lds + PG8_SB(b, h) + boff + n * 2048 + k * 1024); } while (0)
; #define PG8_MMA(ai, bj, At, Bt) do { __builtin_amdgcn_s_setprio(1); _Pragma("unroll") for (int m = 0; m < 4; ++m) _Pragma("unroll") for (int n = 0; n < 2; ++n) _Pragma("unroll") for (int k = 0; k < 2; ++k) \
;         acc[ai][bj][m][n] = __builtin_amdgcn_mfma_f32_16x16x32_bf16(Bt[n][k], At[m][k], acc[ai][bj][m][n], 0, 0, 0); __builtin_amdgcn_s_setprio(0); } while (0)
; #define PG8_WAIT_V(n) asm volatile("s_waitcnt vmcnt(" #n ")" ::: "memory")
; #define PG8_WAIT_L(n) asm volatile("s_waitcnt lgkmcnt(" #n ")" ::: "memory")
; #define PG8_BAR __builtin_amdgcn_s_barrier()
; #define PG8_SCHED __builtin_amdgcn_sched_barrier(0)
; template <class Epi, class Sched, bool ALIGN_EPI = false, bool SP2 = false>
; __device__ __forceinline__ void gemm_phase(PG8_LAS unsigned char* lds, const Gemm g, const Sched& S, const Epi& E) {
;     ...
;             PG8_LDB(B0, 0, 0); PG8_LDB(B1, 0, 1); PG8_SCHED; PG8_LDA(At, 0, 0); PG8_STAGE(PG8_SA(1, 1), a1 + hstepA, voffA);
;             PG8_WAIT_V(8); PG8_WAIT_L(0); PG8_BAR; PG8_MMA(0, 0, At, B0); PG8_MMA(0, 1, At, B1); PG8_BAR; PG8_SCHED;
;             PG8_LDA(At, 0, 1); PG8_STAGE(PG8_SB(0, 0), b2, voffB); PG8_STAGE(PG8_SB(0, 1), b2 + hstepB, voffB); PG8_STAGE(PG8_SA(0, 0), a2, voffA);
;             PG8_WAIT_V(8); PG8_WAIT_L(0); PG8_BAR; PG8_MMA(1, 0, At, B0); PG8_MMA(1, 1, At, B1); PG8_BAR; PG8_SCHED;
.LBB0_278:
	v_add_u32_e32 v142, s35, v145
	ds_read_b128 v[138:141], v142
	ds_read_b128 v[148:151], v142 offset:1024
	ds_read_b128 v[152:155], v142 offset:2048
	ds_read_b128 v[156:159], v142 offset:3072
	v_add_u32_e32 v142, s38, v145
	ds_read_b128 v[160:163], v142
	ds_read_b128 v[164:167], v142 offset:1024
	ds_read_b128 v[168:171], v142 offset:2048
	ds_read_b128 v[172:175], v142 offset:3072
	s_add_u32 s22, s20, 0x100
	s_addc_u32 s23, s21, 0
	s_cmp_eq_u32 s78, 40
	s_cselect_b32 s27, s9, s23
	s_cselect_b32 s26, s8, s22
	s_cselect_b32 s25, s19, s75
	s_cselect_b32 s24, s18, s74
	v_lshl_add_u64 v[142:143], s[20:21], 0, v[136:137]
	s_add_i32 m0, s41, 0xc000
	ds_read_b128 v[176:179], v147
	ds_read_b128 v[180:183], v147 offset:1024
	ds_read_b128 v[184:187], v147 offset:2048
	ds_read_b128 v[188:191], v147 offset:3072
	ds_read_b128 v[204:207], v147 offset:4096
	ds_read_b128 v[208:211], v147 offset:5120
	ds_read_b128 v[218:221], v147 offset:6144
	ds_read_b128 v[222:225], v147 offset:7168
	global_load_lds_dwordx4 v[142:143], off
	v_lshl_add_u64 v[142:143], s[20:21], 0, v[134:135]
	s_add_i32 m0, s41, 0xe000
	s_nop 0
	global_load_lds_dwordx4 v[142:143], off
	s_waitcnt vmcnt(8)
	s_waitcnt lgkmcnt(0)
	s_barrier
	s_setprio 1
	s_waitcnt lgkmcnt(0)
	v_mfma_f32_16x16x32_bf16 v[124:127], v[138:141], v[176:179], v[124:127]
	v_mfma_f32_16x16x32_bf16 v[120:123], v[152:155], v[176:179], v[120:123]
	v_mfma_f32_16x16x32_bf16 v[108:111], v[138:141], v[184:187], v[108:111]
	v_mfma_f32_16x16x32_bf16 v[104:107], v[152:155], v[184:187], v[104:107]
	v_mfma_f32_16x16x32_bf16 v[92:95], v[138:141], v[204:207], v[92:95]
	v_mfma_f32_16x16x32_bf16 v[88:91], v[152:155], v[204:207], v[88:91]
	v_mfma_f32_16x16x32_bf16 v[76:79], v[138:141], v[218:221], v[76:79]
	v_mfma_f32_16x16x32_bf16 v[72:75], v[152:155], v[218:221], v[72:75]
	v_mfma_f32_16x16x32_bf16 v[124:127], v[148:151], v[180:183], v[124:127]
	v_mfma_f32_16x16x32_bf16 v[120:123], v[156:159], v[180:183], v[120:123]
	v_mfma_f32_16x16x32_bf16 v[108:111], v[148:151], v[188:191], v[108:111]
	v_mfma_f32_16x16x32_bf16 v[104:107], v[156:159], v[188:191], v[104:107]
	v_mfma_f32_16x16x32_bf16 v[92:95], v[148:151], v[208:211], v[92:95]
	v_mfma_f32_16x16x32_bf16 v[88:91], v[156:159], v[208:211], v[88:91]
	v_mfma_f32_16x16x32_bf16 v[76:79], v[148:151], v[222:225], v[76:79]
	v_mfma_f32_16x16x32_bf16 v[72:75], v[156:159], v[222:225], v[72:75]
	s_setprio 0
	s_setprio 1
	v_mfma_f32_16x16x32_bf16 v[116:119], v[160:163], v[176:179], v[116:119]
	v_mfma_f32_16x16x32_bf16 v[112:115], v[168:171], v[176:179], v[112:115]
	v_mfma_f32_16x16x32_bf16 v[100:103], v[160:163], v[184:187], v[100:103]
	v_mfma_f32_16x16x32_bf16 v[96:99], v[168:171], v[184:187], v[96:99]
	v_mfma_f32_16x16x32_bf16 v[84:87], v[160:163], v[204:207], v[84:87]
	v_mfma_f32_16x16x32_bf16 v[80:83], v[168:171], v[204:207], v[80:83]
	v_mfma_f32_16x16x32_bf16 v[68:71], v[160:163], v[218:221], v[68:71]
	v_mfma_f32_16x16x32_bf16 v[64:67], v[168:171], v[218:221], v[64:67]
	v_mfma_f32_16x16x32_bf16 v[116:119], v[164:167], v[180:183], v[116:119]
	v_mfma_f32_16x16x32_bf16 v[112:115], v[172:175], v[180:183], v[112:115]
	v_mfma_f32_16x16x32_bf16 v[100:103], v[164:167], v[188:191], v[100:103]
	v_mfma_f32_16x16x32_bf16 v[96:99], v[172:175], v[188:191], v[96:99]
	v_mfma_f32_16x16x32_bf16 v[84:87], v[164:167], v[208:211], v[84:87]
	v_mfma_f32_16x16x32_bf16 v[80:83], v[172:175], v[208:211], v[80:83]
	v_mfma_f32_16x16x32_bf16 v[68:71], v[164:167], v[222:225], v[68:71]
	v_mfma_f32_16x16x32_bf16 v[64:67], v[172:175], v[222:225], v[64:67]
	s_setprio 0
	s_barrier
	s_mov_b32 m0, s36
	v_lshl_add_u64 v[142:143], s[24:25], 0, v[192:193]
	s_add_u32 s20, s24, 0xb0000
	ds_read_b128 v[176:179], v147 offset:16384
	ds_read_b128 v[180:183], v147 offset:17408
	ds_read_b128 v[184:187], v147 offset:18432
	ds_read_b128 v[188:191], v147 offset:19456
	ds_read_b128 v[204:207], v147 offset:20480
	ds_read_b128 v[208:211], v147 offset:21504
	ds_read_b128 v[218:221], v147 offset:22528
	ds_read_b128 v[222:225], v147 offset:23552
	global_load_lds_dwordx4 v[142:143], off
	v_lshl_add_u64 v[226:227], s[24:25], 0, v[132:133]
	s_mov_b32 m0, s37
	s_addc_u32 s21, s25, 0
	global_load_lds_dwordx4 v[226:227], off
	v_lshl_add_u64 v[228:229], s[20:21], 0, v[192:193]
	s_mov_b32 m0, s39
	v_lshl_add_u64 v[230:231], s[26:27], 0, v[130:131]
	global_load_lds_dwordx4 v[228:229], off
	v_lshl_add_u64 v[228:229], s[20:21], 0, v[132:133]
	s_mov_b32 m0, s40
	s_nop 0
	global_load_lds_dwordx4 v[228:229], off
	v_lshl_add_u64 v[228:229], s[26:27], 0, v[128:129]
	s_mov_b32 m0, s41
	s_nop 0
	global_load_lds_dwordx4 v[228:229], off
	s_mov_b32 m0, s42
	s_nop 0
	global_load_lds_dwordx4 v[230:231], off
	s_waitcnt vmcnt(8)
	s_waitcnt lgkmcnt(0)
	s_barrier
; #define PG8_STAGE(bufoff, gbase, voff) do { _Pragma("unroll") for (int _i = 0; _i < 2; ++_i) \
;         __builtin_amdgcn_global_load_lds((const unsigned*)((const char*)(gbase) + (voff)[_i]), (PG8_LAS unsigned*)(lds + (bufoff) + ldsw + _i * 8192), 16, 0, 0); } while (0)
; #define PG8_LDA(dst, b, h) do { _Pragma("unroll") for (int m = 0; m < 4; ++m) _Pragma("unroll") for (int k = 0; k < 2; ++k) dst[m][k] = *(const PG8_LAS bf16x8*)(lds + PG8_SA(b, h) + aoff + m * 2048 + k * 1024); } while (0)
; #define PG8_LDB(dst, b, h) do { _Pragma("unroll") for (int n = 0; n < 2; ++n) _Pragma("unroll") for (int k = 0; k < 2; ++k) dst[n][k] = *(const PG8_LAS bf16x8*)(lds + PG8_SB(b, h) + boff + n * 2048 + k * 1024); } while (0)
; #define PG8_MMA(ai, bj, At, Bt) do { __builtin_amdgcn_s_setprio(1); _Pragma("unroll") for (int m = 0; m < 4; ++m) _Pragma("unroll") for (int n = 0; n < 2; ++n) _Pragma("unroll") for (int k = 0; k < 2; ++k) \
;         acc[ai][bj][m][n] = __builtin_amdgcn_mfma_f32_16x16x32_bf16(Bt[n][k], At[m][k], acc[ai][bj][m][n], 0, 0, 0); __builtin_amdgcn_s_setprio(0); } while (0)
; #define PG8_WAIT_V(n) asm volatile("s_waitcnt vmcnt(" #n ")" ::: "memory")
; #define PG8_WAIT_L(n) asm volatile("s_waitcnt lgkmcnt(" #n ")" ::: "memory")
; #define PG8_BAR __builtin_amdgcn_s_barrier()
; #define PG8_SCHED __builtin_amdgcn_sched_barrier(0)
; template <class Epi, class Sched, bool ALIGN_EPI = false, bool SP2 = false>
; __device__ __forceinline__ void gemm_phase(PG8_LAS unsigned char* lds, const Gemm g, const Sched& S, const Epi& E) {
;     ...
;             PG8_WAIT_V(8); PG8_WAIT_L(0); PG8_BAR; PG8_MMA(1, 0, At, B0); PG8_MMA(1, 1, At, B1); PG8_BAR; PG8_SCHED;
;             PG8_LDB(B0, 1, 0); PG8_LDB(B1, 1, 1); PG8_SCHED; PG8_LDA(At, 1, 0); PG8_STAGE(PG8_SA(0, 1), a2 + hstepA, voffA);
;             PG8_WAIT_V(8); PG8_WAIT_L(0); PG8_BAR; PG8_MMA(0, 0, At, B0); PG8_MMA(0, 1, At, B1); PG8_BAR; PG8_SCHED;
	s_setprio 1
	s_waitcnt lgkmcnt(0)
	v_mfma_f32_16x16x32_bf16 v[60:63], v[138:141], v[176:179], v[60:63]
	v_mfma_f32_16x16x32_bf16 v[56:59], v[152:155], v[176:179], v[56:59]
	v_mfma_f32_16x16x32_bf16 v[44:47], v[138:141], v[184:187], v[44:47]
	v_mfma_f32_16x16x32_bf16 v[40:43], v[152:155], v[184:187], v[40:43]
	v_mfma_f32_16x16x32_bf16 v[28:31], v[138:141], v[204:207], v[28:31]
	v_mfma_f32_16x16x32_bf16 v[24:27], v[152:155], v[204:207], v[24:27]
	v_mfma_f32_16x16x32_bf16 v[12:15], v[138:141], v[218:221], v[12:15]
	v_mfma_f32_16x16x32_bf16 v[8:11], v[152:155], v[218:221], v[8:11]
	v_mfma_f32_16x16x32_bf16 v[60:63], v[148:151], v[180:183], v[60:63]
	v_mfma_f32_16x16x32_bf16 v[56:59], v[156:159], v[180:183], v[56:59]
	v_mfma_f32_16x16x32_bf16 v[44:47], v[148:151], v[188:191], v[44:47]
	v_mfma_f32_16x16x32_bf16 v[40:43], v[156:159], v[188:191], v[40:43]
	v_mfma_f32_16x16x32_bf16 v[28:31], v[148:151], v[208:211], v[28:31]
	v_mfma_f32_16x16x32_bf16 v[24:27], v[156:159], v[208:211], v[24:27]
	v_mfma_f32_16x16x32_bf16 v[12:15], v[148:151], v[222:225], v[12:15]
	v_mfma_f32_16x16x32_bf16 v[8:11], v[156:159], v[222:225], v[8:11]
	s_setprio 0
	s_setprio 1
	v_mfma_f32_16x16x32_bf16 v[52:55], v[160:163], v[176:179], v[52:55]
	v_mfma_f32_16x16x32_bf16 v[48:51], v[168:171], v[176:179], v[48:51]
	v_mfma_f32_16x16x32_bf16 v[36:39], v[160:163], v[184:187], v[36:39]
	v_mfma_f32_16x16x32_bf16 v[32:35], v[168:171], v[184:187], v[32:35]
	v_mfma_f32_16x16x32_bf16 v[20:23], v[160:163], v[204:207], v[20:23]
	v_mfma_f32_16x16x32_bf16 v[16:19], v[168:171], v[204:207], v[16:19]
	v_mfma_f32_16x16x32_bf16 v[4:7], v[160:163], v[218:221], v[4:7]
	v_mfma_f32_16x16x32_bf16 v[0:3], v[168:171], v[218:221], v[0:3]
	v_mfma_f32_16x16x32_bf16 v[52:55], v[164:167], v[180:183], v[52:55]
	v_mfma_f32_16x16x32_bf16 v[48:51], v[172:175], v[180:183], v[48:51]
	v_mfma_f32_16x16x32_bf16 v[36:39], v[164:167], v[188:191], v[36:39]
	v_mfma_f32_16x16x32_bf16 v[32:35], v[172:175], v[188:191], v[32:35]
	v_mfma_f32_16x16x32_bf16 v[20:23], v[164:167], v[208:211], v[20:23]
	v_mfma_f32_16x16x32_bf16 v[16:19], v[172:175], v[208:211], v[16:19]
	v_mfma_f32_16x16x32_bf16 v[4:7], v[164:167], v[222:225], v[4:7]
	v_mfma_f32_16x16x32_bf16 v[0:3], v[172:175], v[222:225], v[0:3]
	s_setprio 0
	s_barrier
	v_add_u32_e32 v156, s48, v145
	v_add_u32_e32 v172, s61, v145
	ds_read_b128 v[138:141], v156
	ds_read_b128 v[148:151], v156 offset:1024
	ds_read_b128 v[152:155], v156 offset:2048
	ds_read_b128 v[156:159], v156 offset:3072
	ds_read_b128 v[160:163], v172
	ds_read_b128 v[164:167], v172 offset:1024
	ds_read_b128 v[168:171], v172 offset:2048
	ds_read_b128 v[172:175], v172 offset:3072
	s_add_u32 s20, s26, 0xb0000
	s_addc_u32 s21, s27, 0
	s_mov_b32 m0, s43
	v_lshl_add_u64 v[232:233], s[20:21], 0, v[128:129]
	ds_read_b128 v[176:179], v147 offset:32768
	ds_read_b128 v[180:183], v147 offset:33792
	ds_read_b128 v[184:187], v147 offset:34816
	ds_read_b128 v[188:191], v147 offset:35840
	ds_read_b128 v[204:207], v147 offset:36864
	ds_read_b128 v[208:211], v147 offset:37888
	ds_read_b128 v[218:221], v147 offset:38912
	ds_read_b128 v[222:225], v147 offset:39936
	global_load_lds_dwordx4 v[232:233], off
	v_lshl_add_u64 v[232:233], s[20:21], 0, v[130:131]
	s_mov_b32 m0, s44
	s_nop 0
	global_load_lds_dwordx4 v[232:233], off
	s_waitcnt vmcnt(8)
	s_waitcnt lgkmcnt(0)
	s_barrier
	s_setprio 1
	s_waitcnt lgkmcnt(0)
	v_mfma_f32_16x16x32_bf16 v[124:127], v[138:141], v[176:179], v[124:127]
	v_mfma_f32_16x16x32_bf16 v[120:123], v[152:155], v[176:179], v[120:123]
	v_mfma_f32_16x16x32_bf16 v[108:111], v[138:141], v[184:187], v[108:111]
	v_mfma_f32_16x16x32_bf16 v[104:107], v[152:155], v[184:187], v[104:107]
	v_mfma_f32_16x16x32_bf16 v[92:95], v[138:141], v[204:207], v[92:95]
	v_mfma_f32_16x16x32_bf16 v[88:91], v[152:155], v[204:207], v[88:91]
	v_mfma_f32_16x16x32_bf16 v[76:79], v[138:141], v[218:221], v[76:79]
	v_mfma_f32_16x16x32_bf16 v[72:75], v[152:155], v[218:221], v[72:75]
	v_mfma_f32_16x16x32_bf16 v[124:127], v[148:151], v[180:183], v[124:127]
	v_mfma_f32_16x16x32_bf16 v[120:123], v[156:159], v[180:183], v[120:123]
	v_mfma_f32_16x16x32_bf16 v[108:111], v[148:151], v[188:191], v[108:111]
	v_mfma_f32_16x16x32_bf16 v[104:107], v[156:159], v[188:191], v[104:107]
	v_mfma_f32_16x16x32_bf16 v[92:95], v[148:151], v[208:211], v[92:95]
	v_mfma_f32_16x16x32_bf16 v[88:91], v[156:159], v[208:211], v[88:91]
	v_mfma_f32_16x16x32_bf16 v[76:79], v[148:151], v[222:225], v[76:79]
	v_mfma_f32_16x16x32_bf16 v[72:75], v[156:159], v[222:225], v[72:75]
	s_setprio 0
	s_setprio 1
	v_mfma_f32_16x16x32_bf16 v[116:119], v[160:163], v[176:179], v[116:119]
	v_mfma_f32_16x16x32_bf16 v[112:115], v[168:171], v[176:179], v[112:115]
	v_mfma_f32_16x16x32_bf16 v[100:103], v[160:163], v[184:187], v[100:103]
	v_mfma_f32_16x16x32_bf16 v[96:99], v[168:171], v[184:187], v[96:99]
	v_mfma_f32_16x16x32_bf16 v[84:87], v[160:163], v[204:207], v[84:87]
	v_mfma_f32_16x16x32_bf16 v[80:83], v[168:171], v[204:207], v[80:83]
	v_mfma_f32_16x16x32_bf16 v[68:71], v[160:163], v[218:221], v[68:71]
	v_mfma_f32_16x16x32_bf16 v[64:67], v[168:171], v[218:221], v[64:67]
	v_mfma_f32_16x16x32_bf16 v[116:119], v[164:167], v[180:183], v[116:119]
	v_mfma_f32_16x16x32_bf16 v[112:115], v[172:175], v[180:183], v[112:115]
	v_mfma_f32_16x16x32_bf16 v[100:103], v[164:167], v[188:191], v[100:103]
	v_mfma_f32_16x16x32_bf16 v[96:99], v[172:175], v[188:191], v[96:99]
	v_mfma_f32_16x16x32_bf16 v[84:87], v[164:167], v[208:211], v[84:87]
	v_mfma_f32_16x16x32_bf16 v[80:83], v[172:175], v[208:211], v[80:83]
	v_mfma_f32_16x16x32_bf16 v[68:71], v[164:167], v[222:225], v[68:71]
	v_mfma_f32_16x16x32_bf16 v[64:67], v[172:175], v[222:225], v[64:67]
	s_setprio 0
	s_barrier
; #define PG8_STAGE(bufoff, gbase, voff) do { _Pragma("unroll") for (int _i = 0; _i < 2; ++_i) \
;         __builtin_amdgcn_global_load_lds((const unsigned*)((const char*)(gbase) + (voff)[_i]), (PG8_LAS unsigned*)(lds + (bufoff) + ldsw + _i * 8192), 16, 0, 0); } while (0)
; #define PG8_LDA(dst, b, h) do { _Pragma("unroll") for (int m = 0; m < 4; ++m) _Pragma("unroll") for (int k = 0; k < 2; ++k) dst[m][k] = *(const PG8_LAS bf16x8*)(lds + PG8_SA(b, h) + aoff + m * 2048 + k * 1024); } while (0)
; #define PG8_MMA(ai, bj, At, Bt) do { __builtin_amdgcn_s_setprio(1); _Pragma("unroll") for (int m = 0; m < 4; ++m) _Pragma("unroll") for (int n = 0; n < 2; ++n) _Pragma("unroll") for (int k = 0; k < 2; ++k) \
;         acc[ai][bj][m][n] = __builtin_amdgcn_mfma_f32_16x16x32_bf16(Bt[n][k], At[m][k], acc[ai][bj][m][n], 0, 0, 0); __builtin_amdgcn_s_setprio(0); } while (0)
; #define PG8_WAIT_V(n) asm volatile("s_waitcnt vmcnt(" #n ")" ::: "memory")
; #define PG8_WAIT_L(n) asm volatile("s_waitcnt lgkmcnt(" #n ")" ::: "memory")
; #define PG8_BAR __builtin_amdgcn_s_barrier()
; #define PG8_SCHED __builtin_amdgcn_sched_barrier(0)
; template <class Epi, class Sched, bool ALIGN_EPI = false, bool SP2 = false>
; __device__ __forceinline__ void gemm_phase(PG8_LAS unsigned char* lds, const Gemm g, const Sched& S, const Epi& E) {
;     ...
;             PG8_WAIT_V(8); PG8_WAIT_L(0); PG8_BAR; PG8_MMA(0, 0, At, B0); PG8_MMA(0, 1, At, B1); PG8_BAR; PG8_SCHED;
;             PG8_LDA(At, 1, 1); PG8_STAGE(PG8_SB(1, 0), b3, voffB); PG8_STAGE(PG8_SB(1, 1), b3 + hstepB, voffB); PG8_STAGE(PG8_SA(1, 0), a3, voffA);
;             PG8_WAIT_V(8); PG8_WAIT_L(0); PG8_BAR; PG8_MMA(1, 0, At, B0); PG8_MMA(1, 1, At, B1); PG8_BAR; PG8_SCHED;
;     __device__ __forceinline__ void operator()(const f32x4 (&acc)[2][2][4][2], const pg8::Unit& u, int wr, int wc, int fr, int fq) const {
;     ...
;                     const size_t off = (size_t)row * DM + col0 + bj * 128;
;                     const v4u b = *(const v4u*)(xb + off);
	s_mov_b32 m0, s49
	v_lshl_add_u64 v[142:143], v[142:143], 0, s[76:77]
	s_add_u32 s20, s24, 0xb0080
	ds_read_b128 v[176:179], v147 offset:49152
	ds_read_b128 v[180:183], v147 offset:50176
	ds_read_b128 v[184:187], v147 offset:51200
	ds_read_b128 v[188:191], v147 offset:52224
	ds_read_b128 v[204:207], v147 offset:53248
	ds_read_b128 v[208:211], v147 offset:54272
	ds_read_b128 v[218:221], v147 offset:55296
	ds_read_b128 v[222:225], v147 offset:56320
	global_load_lds_dwordx4 v[142:143], off
	v_lshl_add_u64 v[142:143], v[226:227], 0, s[76:77]
	s_mov_b32 m0, s50
	s_addc_u32 s21, s25, 0
	global_load_lds_dwordx4 v[142:143], off
	v_lshl_add_u64 v[142:143], s[20:21], 0, v[192:193]
	s_mov_b32 m0, s64
	s_nop 0
	global_load_lds_dwordx4 v[142:143], off
	v_lshl_add_u64 v[142:143], s[20:21], 0, v[132:133]
	s_mov_b32 m0, s65
	s_nop 0
	global_load_lds_dwordx4 v[142:143], off
	v_lshl_add_u64 v[142:143], v[228:229], 0, s[76:77]
	s_mov_b32 m0, s51
	s_nop 0
	global_load_lds_dwordx4 v[142:143], off
	v_lshl_add_u64 v[142:143], v[230:231], 0, s[76:77]
	s_mov_b32 m0, s60
	s_nop 0
	global_load_lds_dwordx4 v[142:143], off
	s_waitcnt vmcnt(8)
	s_waitcnt lgkmcnt(0)
	s_barrier
	s_setprio 1
	s_waitcnt lgkmcnt(0)
	v_mfma_f32_16x16x32_bf16 v[60:63], v[138:141], v[176:179], v[60:63]
	v_mfma_f32_16x16x32_bf16 v[56:59], v[152:155], v[176:179], v[56:59]
	v_mfma_f32_16x16x32_bf16 v[44:47], v[138:141], v[184:187], v[44:47]
	v_mfma_f32_16x16x32_bf16 v[40:43], v[152:155], v[184:187], v[40:43]
	v_mfma_f32_16x16x32_bf16 v[28:31], v[138:141], v[204:207], v[28:31]
	v_mfma_f32_16x16x32_bf16 v[24:27], v[152:155], v[204:207], v[24:27]
	v_mfma_f32_16x16x32_bf16 v[12:15], v[138:141], v[218:221], v[12:15]
	v_mfma_f32_16x16x32_bf16 v[8:11], v[152:155], v[218:221], v[8:11]
	v_mfma_f32_16x16x32_bf16 v[60:63], v[148:151], v[180:183], v[60:63]
	v_mfma_f32_16x16x32_bf16 v[56:59], v[156:159], v[180:183], v[56:59]
	v_mfma_f32_16x16x32_bf16 v[44:47], v[148:151], v[188:191], v[44:47]
	v_mfma_f32_16x16x32_bf16 v[40:43], v[156:159], v[188:191], v[40:43]
	v_mfma_f32_16x16x32_bf16 v[28:31], v[148:151], v[208:211], v[28:31]
	v_mfma_f32_16x16x32_bf16 v[24:27], v[156:159], v[208:211], v[24:27]
	v_mfma_f32_16x16x32_bf16 v[12:15], v[148:151], v[222:225], v[12:15]
	v_mfma_f32_16x16x32_bf16 v[8:11], v[156:159], v[222:225], v[8:11]
	s_setprio 0
	s_setprio 1
	v_mfma_f32_16x16x32_bf16 v[52:55], v[160:163], v[176:179], v[52:55]
	v_mfma_f32_16x16x32_bf16 v[48:51], v[168:171], v[176:179], v[48:51]
	v_mfma_f32_16x16x32_bf16 v[36:39], v[160:163], v[184:187], v[36:39]
	v_mfma_f32_16x16x32_bf16 v[32:35], v[168:171], v[184:187], v[32:35]
	v_mfma_f32_16x16x32_bf16 v[20:23], v[160:163], v[204:207], v[20:23]
	v_mfma_f32_16x16x32_bf16 v[16:19], v[168:171], v[204:207], v[16:19]
	v_mfma_f32_16x16x32_bf16 v[4:7], v[160:163], v[218:221], v[4:7]
	v_mfma_f32_16x16x32_bf16 v[0:3], v[168:171], v[218:221], v[0:3]
	v_mfma_f32_16x16x32_bf16 v[52:55], v[164:167], v[180:183], v[52:55]
	v_mfma_f32_16x16x32_bf16 v[48:51], v[172:175], v[180:183], v[48:51]
	v_mfma_f32_16x16x32_bf16 v[36:39], v[164:167], v[188:191], v[36:39]
	v_mfma_f32_16x16x32_bf16 v[32:35], v[172:175], v[188:191], v[32:35]
	v_mfma_f32_16x16x32_bf16 v[20:23], v[164:167], v[208:211], v[20:23]
	v_mfma_f32_16x16x32_bf16 v[16:19], v[172:175], v[208:211], v[16:19]
	v_mfma_f32_16x16x32_bf16 v[4:7], v[164:167], v[222:225], v[4:7]
	v_mfma_f32_16x16x32_bf16 v[0:3], v[172:175], v[222:225], v[0:3]
	s_setprio 0
	s_barrier
	s_add_i32 s78, s78, 2
	s_add_u32 s74, s74, 0x100
	s_addc_u32 s75, s75, 0
	s_cmp_gt_u32 s78, 41
	s_mov_b64 s[20:21], s[22:23]
	s_cbranch_scc0 .LBB0_278
	v_lshl_add_u32 v159, s68, 8, v144
	v_lshl_or_b32 v158, s34, 8, v146
	v_lshlrev_b32_e32 v159, 11, v159
	v_lshl_add_u32 v159, v158, 1, v159
	v_add_u32_e32 v218, 0x8000, v159
	v_add_u32_e32 v219, 0x10000, v159
	v_add_u32_e32 v240, 0x18000, v159
	v_add_u32_e32 v241, 0x40000, v159
	v_add_u32_e32 v245, 0x48000, v159
	v_add_u32_e32 v246, 0x50000, v159
	v_add_u32_e32 v247, 0x58000, v159
	global_load_dwordx4 v[160:163], v159, s[12:13]
	global_load_dwordx4 v[164:167], v159, s[12:13] offset:256
	global_load_dwordx4 v[168:171], v218, s[12:13]
	global_load_dwordx4 v[172:175], v218, s[12:13] offset:256
	global_load_dwordx4 v[176:179], v219, s[12:13]
	global_load_dwordx4 v[180:183], v219, s[12:13] offset:256
	global_load_dwordx4 v[184:187], v240, s[12:13]
	global_load_dwordx4 v[188:191], v240, s[12:13] offset:256
	global_load_dwordx4 v[204:207], v241, s[12:13]
	global_load_dwordx4 v[208:211], v241, s[12:13] offset:256
	global_load_dwordx4 v[220:223], v245, s[12:13]
	global_load_dwordx4 v[224:227], v245, s[12:13] offset:256
	global_load_dwordx4 v[228:231], v246, s[12:13]
	global_load_dwordx4 v[232:235], v246, s[12:13] offset:256
	global_load_dwordx4 v[236:239], v247, s[12:13]
	global_load_dwordx4 v[248:251], v247, s[12:13] offset:256
	s_and_b64 vcc, exec, s[16:17]
	s_cbranch_vccz .LBB0_281
	s_barrier
; __device__ __forceinline__ float bflo(unsigned w) { return __uint_as_float(w << 16); }
; __device__ __forceinline__ float bfhi(unsigned w) { return __uint_as_float(w & 0xffff0000u); }
; __device__ __forceinline__ v4u pack8(const f32x4 a, const f32x4 b) { v4u w; w.x = cvt_pk_bf16(a[0], a[1]); w.y = cvt_pk_bf16(a[2], a[3]); w.z = cvt_pk_bf16(b[0], b[1]); w.w = cvt_pk_bf16(b[2], b[3]); return w; }
;     __device__ __forceinline__ void operator()(const f32x4 (&acc)[2][2][4][2], const pg8::Unit& u, int wr, int wc, int fr, int fq) const {
;     ...
; #pragma unroll
;         for (int ai = 0; ai < 2; ++ai)
; #pragma unroll
;             for (int m = 0; m < 4; ++m) {
;                 const int row = row0 + ai * 128 + m * 16; float ss = 0.f;
; #pragma unroll
;                 for (int bj = 0; bj < 2; ++bj) {
;                     const size_t off = (size_t)row * DM + col0 + bj * 128;
;                     const v4u b = *(const v4u*)(xb + off);
;                     f32x4 v0, v1; v0[0] = bflo(b.x); v0[1] = bfhi(b.x); v0[2] = bflo(b.y); v0[3] = bfhi(b.y); v1[0] = bflo(b.z); v1[1] = bfhi(b.z); v1[2] = bflo(b.w); v1[3] = bfhi(b.w);
;                     v0 = v0 + alpha * acc[ai][bj][m][0]; v1 = v1 + alpha * acc[ai][bj][m][1];
;                     const v4u w = pack8(v0, v1); *(v4u*)(xb + off) = w;
;                     const float r0 = bflo(w.x), r1 = bfhi(w.x), r2 = bflo(w.y), r3 = bfhi(w.y), r4 = bflo(w.z), r5 = bfhi(w.z), r6 = bflo(w.w), r7 = bfhi(w.w);
;                     ss += (r0 * r0 + r1 * r1) + (r2 * r2 + r3 * r3) + (r4 * r4 + r5 * r5) + (r6 * r6 + r7 * r7);
;                 }
;                 ss += __shfl_xor(ss, 16); ss += __shfl_xor(ss, 32);
;                 if (fq == 0) ssq[(size_t)row * 16 + u.pn * 4 + wc] = ss;
.LBB0_281:
	v_and_b32_e32 v142, 64, v215
	v_xor_b32_e32 v141, 16, v215
	v_add_u32_e32 v142, 64, v142
	v_cmp_lt_i32_e32 vcc, v141, v142
	v_lshl_add_u32 v140, s68, 8, v144
	v_lshl_or_b32 v138, s34, 8, v146
	v_cndmask_b32_e32 v141, v215, v141, vcc
	v_lshlrev_b32_e32 v148, 2, v141
	v_xor_b32_e32 v141, 32, v215
	v_cmp_lt_i32_e32 vcc, v141, v142
	v_ashrrev_i32_e32 v139, 31, v138
	s_nop 0
	v_cndmask_b32_e32 v141, v215, v141, vcc
	v_lshlrev_b32_e32 v149, 2, v141
	v_ashrrev_i32_e32 v141, 31, v140
	v_lshlrev_b64 v[142:143], 11, v[140:141]
	v_lshl_add_u64 v[142:143], s[12:13], 0, v[142:143]
	v_lshl_add_u64 v[142:143], v[138:139], 1, v[142:143]
	s_waitcnt vmcnt(15)
	v_lshlrev_b32_e32 v154, 16, v160
	v_and_b32_e32 v155, 0xffff0000, v160
	v_lshlrev_b32_e32 v150, 16, v161
	v_and_b32_e32 v151, 0xffff0000, v161
	v_lshlrev_b32_e32 v156, 16, v162
	v_and_b32_e32 v157, 0xffff0000, v162
	v_lshlrev_b32_e32 v152, 16, v163
	v_and_b32_e32 v153, 0xffff0000, v163
	v_pk_fma_f32 v[126:127], v[126:127], 0.5, v[150:151] op_sel_hi:[1,0,1]
	v_pk_fma_f32 v[124:125], v[124:125], 0.5, v[154:155] op_sel_hi:[1,0,1]
	v_pk_fma_f32 v[150:151], v[122:123], 0.5, v[152:153] op_sel_hi:[1,0,1]
	v_pk_fma_f32 v[122:123], v[120:121], 0.5, v[156:157] op_sel_hi:[1,0,1]
	v_cvt_pk_bf16_f32 v120, v124, v125
	v_cvt_pk_bf16_f32 v121, v126, v127
	v_cvt_pk_bf16_f32 v122, v122, v123
	v_cvt_pk_bf16_f32 v123, v150, v151
	global_store_dwordx4 v[142:143], v[120:123], off
	v_lshlrev_b32_e32 v124, 16, v120
	v_lshlrev_b32_e32 v125, 16, v121
	v_and_b32_e32 v120, 0xffff0000, v120
	v_and_b32_e32 v121, 0xffff0000, v121
	v_mul_f32_e32 v120, v120, v120
	v_mul_f32_e32 v121, v121, v121
	v_lshlrev_b32_e32 v126, 16, v122
	v_and_b32_e32 v122, 0xffff0000, v122
	v_fmac_f32_e32 v120, v124, v124
	v_fmac_f32_e32 v121, v125, v125
	v_add_f32_e32 v120, v120, v121
	v_mul_f32_e32 v121, v122, v122
	v_lshlrev_b32_e32 v127, 16, v123
	v_and_b32_e32 v123, 0xffff0000, v123
	v_fmac_f32_e32 v121, v126, v126
	v_add_f32_e32 v120, v121, v120
	v_mul_f32_e32 v121, v123, v123
	v_fmac_f32_e32 v121, v127, v127
	v_add_f32_e32 v150, v121, v120
	s_waitcnt vmcnt(15)
	v_lshlrev_b32_e32 v124, 16, v164
	v_and_b32_e32 v125, 0xffff0000, v164
	v_lshlrev_b32_e32 v120, 16, v165
	v_and_b32_e32 v121, 0xffff0000, v165
	v_lshlrev_b32_e32 v126, 16, v166
	v_and_b32_e32 v127, 0xffff0000, v166
	v_lshlrev_b32_e32 v122, 16, v167
	v_and_b32_e32 v123, 0xffff0000, v167
	v_pk_fma_f32 v[118:119], v[118:119], 0.5, v[120:121] op_sel_hi:[1,0,1]
	v_pk_fma_f32 v[116:117], v[116:117], 0.5, v[124:125] op_sel_hi:[1,0,1]
	v_pk_fma_f32 v[120:121], v[114:115], 0.5, v[122:123] op_sel_hi:[1,0,1]
	v_pk_fma_f32 v[114:115], v[112:113], 0.5, v[126:127] op_sel_hi:[1,0,1]
	v_cvt_pk_bf16_f32 v112, v116, v117
	v_cvt_pk_bf16_f32 v113, v118, v119
	v_cvt_pk_bf16_f32 v114, v114, v115
	v_cvt_pk_bf16_f32 v115, v120, v121
	global_store_dwordx4 v[142:143], v[112:115], off offset:256
	v_lshlrev_b32_e32 v116, 16, v112
	v_lshlrev_b32_e32 v117, 16, v113
	v_and_b32_e32 v112, 0xffff0000, v112
	v_and_b32_e32 v113, 0xffff0000, v113
	v_mul_f32_e32 v112, v112, v112
	v_mul_f32_e32 v113, v113, v113
	v_lshlrev_b32_e32 v118, 16, v114
	v_and_b32_e32 v114, 0xffff0000, v114
	v_fmac_f32_e32 v112, v116, v116
	v_fmac_f32_e32 v113, v117, v117
	v_add_f32_e32 v112, v112, v113
	v_mul_f32_e32 v113, v114, v114
	v_lshlrev_b32_e32 v119, 16, v115
	v_and_b32_e32 v115, 0xffff0000, v115
	v_fmac_f32_e32 v113, v118, v118
	v_add_f32_e32 v112, v113, v112
	v_mul_f32_e32 v113, v115, v115
	v_fmac_f32_e32 v113, v119, v119
	v_add_f32_e32 v112, v113, v112
	v_add_f32_e32 v112, v150, v112
	ds_bpermute_b32 v113, v148, v112
	s_waitcnt lgkmcnt(0)
	v_add_f32_e32 v112, v112, v113
	ds_bpermute_b32 v113, v149, v112
	s_and_saveexec_b64 s[20:21], s[4:5]
	s_cbranch_execz .LBB0_283
	s_waitcnt lgkmcnt(0)
	v_add_f32_e32 v114, v112, v113
	s_lshl_b32 s22, s34, 2
	v_lshlrev_b64 v[112:113], 6, v[140:141]
	s_ashr_i32 s23, s22, 31
	v_lshl_add_u64 v[112:113], s[14:15], 0, v[112:113]
	v_lshl_add_u64 v[112:113], s[22:23], 2, v[112:113]
	s_lshl_b32 s68, s45, 2
	v_lshl_add_u64 v[112:113], v[112:113], 0, s[68:69]
	global_store_dword v[112:113], v114, off
.LBB0_283:
	s_or_b64 exec, exec, s[20:21]
	v_or_b32_e32 v112, 16, v140
	s_waitcnt lgkmcnt(0)
	v_ashrrev_i32_e32 v113, 31, v112
	v_lshlrev_b64 v[114:115], 11, v[112:113]
	v_lshl_add_u64 v[114:115], s[12:13], 0, v[114:115]
	v_lshl_add_u64 v[114:115], v[138:139], 1, v[114:115]
	s_waitcnt vmcnt(15)
	v_lshlrev_b32_e32 v120, 16, v168
	v_and_b32_e32 v121, 0xffff0000, v168
	v_lshlrev_b32_e32 v116, 16, v169
	v_and_b32_e32 v117, 0xffff0000, v169
	v_lshlrev_b32_e32 v122, 16, v170
	v_and_b32_e32 v123, 0xffff0000, v170
	v_lshlrev_b32_e32 v118, 16, v171
	v_and_b32_e32 v119, 0xffff0000, v171
	v_pk_fma_f32 v[110:111], v[110:111], 0.5, v[116:117] op_sel_hi:[1,0,1]
	v_pk_fma_f32 v[108:109], v[108:109], 0.5, v[120:121] op_sel_hi:[1,0,1]
	v_pk_fma_f32 v[116:117], v[106:107], 0.5, v[118:119] op_sel_hi:[1,0,1]
	v_pk_fma_f32 v[106:107], v[104:105], 0.5, v[122:123] op_sel_hi:[1,0,1]
	v_cvt_pk_bf16_f32 v104, v108, v109
	v_cvt_pk_bf16_f32 v105, v110, v111
	v_cvt_pk_bf16_f32 v106, v106, v107
	v_cvt_pk_bf16_f32 v107, v116, v117
	global_store_dwordx4 v[114:115], v[104:107], off
	v_lshlrev_b32_e32 v108, 16, v104
	v_lshlrev_b32_e32 v109, 16, v105
	v_and_b32_e32 v104, 0xffff0000, v104
	v_and_b32_e32 v105, 0xffff0000, v105
	v_mul_f32_e32 v104, v104, v104
	v_mul_f32_e32 v105, v105, v105
	v_lshlrev_b32_e32 v110, 16, v106
	v_and_b32_e32 v106, 0xffff0000, v106
	v_fmac_f32_e32 v104, v108, v108
	v_fmac_f32_e32 v105, v109, v109
	v_add_f32_e32 v104, v104, v105
	v_mul_f32_e32 v105, v106, v106
	v_lshlrev_b32_e32 v111, 16, v107
	v_and_b32_e32 v107, 0xffff0000, v107
	v_fmac_f32_e32 v105, v110, v110
	v_add_f32_e32 v104, v105, v104
	v_mul_f32_e32 v105, v107, v107
	v_fmac_f32_e32 v105, v111, v111
	v_add_f32_e32 v116, v105, v104
	s_waitcnt vmcnt(15)
; __device__ __forceinline__ float bflo(unsigned w) { return __uint_as_float(w << 16); }
; __device__ __forceinline__ float bfhi(unsigned w) { return __uint_as_float(w & 0xffff0000u); }
; __device__ __forceinline__ v4u pack8(const f32x4 a, const f32x4 b) { v4u w; w.x = cvt_pk_bf16(a[0], a[1]); w.y = cvt_pk_bf16(a[2], a[3]); w.z = cvt_pk_bf16(b[0], b[1]); w.w = cvt_pk_bf16(b[2], b[3]); return w; }
;     __device__ __forceinline__ void operator()(const f32x4 (&acc)[2][2][4][2], const pg8::Unit& u, int wr, int wc, int fr, int fq) const {
;     ...
; #pragma unroll
;         for (int ai = 0; ai < 2; ++ai)
; #pragma unroll
;             for (int m = 0; m < 4; ++m) {
;                 const int row = row0 + ai * 128 + m * 16; float ss = 0.f;
; #pragma unroll
;                 for (int bj = 0; bj < 2; ++bj) {
;                     const size_t off = (size_t)row * DM + col0 + bj * 128;
;                     const v4u b = *(const v4u*)(xb + off);
;                     f32x4 v0, v1; v0[0] = bflo(b.x); v0[1] = bfhi(b.x); v0[2] = bflo(b.y); v0[3] = bfhi(b.y); v1[0] = bflo(b.z); v1[1] = bfhi(b.z); v1[2] = bflo(b.w); v1[3] = bfhi(b.w);
;                     v0 = v0 + alpha * acc[ai][bj][m][0]; v1 = v1 + alpha * acc[ai][bj][m][1];
;                     const v4u w = pack8(v0, v1); *(v4u*)(xb + off) = w;
;                     const float r0 = bflo(w.x), r1 = bfhi(w.x), r2 = bflo(w.y), r3 = bfhi(w.y), r4 = bflo(w.z), r5 = bfhi(w.z), r6 = bflo(w.w), r7 = bfhi(w.w);
;                     ss += (r0 * r0 + r1 * r1) + (r2 * r2 + r3 * r3) + (r4 * r4 + r5 * r5) + (r6 * r6 + r7 * r7);
;                 }
;                 ss += __shfl_xor(ss, 16); ss += __shfl_xor(ss, 32);
;                 if (fq == 0) ssq[(size_t)row * 16 + u.pn * 4 + wc] = ss;
	v_lshlrev_b32_e32 v108, 16, v172
	v_and_b32_e32 v109, 0xffff0000, v172
	v_lshlrev_b32_e32 v104, 16, v173
	v_and_b32_e32 v105, 0xffff0000, v173
	v_lshlrev_b32_e32 v110, 16, v174
	v_and_b32_e32 v111, 0xffff0000, v174
	v_lshlrev_b32_e32 v106, 16, v175
	v_and_b32_e32 v107, 0xffff0000, v175
	v_pk_fma_f32 v[102:103], v[102:103], 0.5, v[104:105] op_sel_hi:[1,0,1]
	v_pk_fma_f32 v[100:101], v[100:101], 0.5, v[108:109] op_sel_hi:[1,0,1]
	v_pk_fma_f32 v[104:105], v[98:99], 0.5, v[106:107] op_sel_hi:[1,0,1]
	v_pk_fma_f32 v[98:99], v[96:97], 0.5, v[110:111] op_sel_hi:[1,0,1]
	v_cvt_pk_bf16_f32 v96, v100, v101
	v_cvt_pk_bf16_f32 v97, v102, v103
	v_cvt_pk_bf16_f32 v98, v98, v99
	v_cvt_pk_bf16_f32 v99, v104, v105
	global_store_dwordx4 v[114:115], v[96:99], off offset:256
	v_lshlrev_b32_e32 v100, 16, v96
	v_lshlrev_b32_e32 v101, 16, v97
	v_and_b32_e32 v96, 0xffff0000, v96
	v_and_b32_e32 v97, 0xffff0000, v97
	v_mul_f32_e32 v96, v96, v96
	v_mul_f32_e32 v97, v97, v97
	v_lshlrev_b32_e32 v102, 16, v98
	v_and_b32_e32 v98, 0xffff0000, v98
	v_fmac_f32_e32 v96, v100, v100
	v_fmac_f32_e32 v97, v101, v101
	v_add_f32_e32 v96, v96, v97
	v_mul_f32_e32 v97, v98, v98
	v_lshlrev_b32_e32 v103, 16, v99
	v_and_b32_e32 v99, 0xffff0000, v99
	v_fmac_f32_e32 v97, v102, v102
	v_add_f32_e32 v96, v97, v96
	v_mul_f32_e32 v97, v99, v99
	v_fmac_f32_e32 v97, v103, v103
	v_add_f32_e32 v96, v97, v96
	v_add_f32_e32 v96, v116, v96
	ds_bpermute_b32 v97, v148, v96
	s_waitcnt lgkmcnt(0)
	v_add_f32_e32 v96, v96, v97
	ds_bpermute_b32 v97, v149, v96
	s_and_saveexec_b64 s[20:21], s[4:5]
	s_cbranch_execz .LBB0_285
	s_waitcnt lgkmcnt(0)
	v_add_f32_e32 v98, v96, v97
	s_lshl_b32 s22, s34, 2
	v_lshlrev_b64 v[96:97], 6, v[112:113]
	s_ashr_i32 s23, s22, 31
	v_lshl_add_u64 v[96:97], s[14:15], 0, v[96:97]
	v_lshl_add_u64 v[96:97], s[22:23], 2, v[96:97]
	s_lshl_b32 s68, s45, 2
	v_lshl_add_u64 v[96:97], v[96:97], 0, s[68:69]
	global_store_dword v[96:97], v98, off
.LBB0_285:
	s_or_b64 exec, exec, s[20:21]
	v_or_b32_e32 v96, 32, v140
	s_waitcnt lgkmcnt(0)
	v_ashrrev_i32_e32 v97, 31, v96
	v_lshlrev_b64 v[98:99], 11, v[96:97]
	v_lshl_add_u64 v[98:99], s[12:13], 0, v[98:99]
	v_lshl_add_u64 v[98:99], v[138:139], 1, v[98:99]
	s_waitcnt vmcnt(15)
	v_lshlrev_b32_e32 v104, 16, v176
	v_and_b32_e32 v105, 0xffff0000, v176
	v_lshlrev_b32_e32 v100, 16, v177
	v_and_b32_e32 v101, 0xffff0000, v177
	v_lshlrev_b32_e32 v106, 16, v178
	v_and_b32_e32 v107, 0xffff0000, v178
	v_lshlrev_b32_e32 v102, 16, v179
	v_and_b32_e32 v103, 0xffff0000, v179
	v_pk_fma_f32 v[94:95], v[94:95], 0.5, v[100:101] op_sel_hi:[1,0,1]
	v_pk_fma_f32 v[92:93], v[92:93], 0.5, v[104:105] op_sel_hi:[1,0,1]
	v_pk_fma_f32 v[100:101], v[90:91], 0.5, v[102:103] op_sel_hi:[1,0,1]
	v_pk_fma_f32 v[90:91], v[88:89], 0.5, v[106:107] op_sel_hi:[1,0,1]
	v_cvt_pk_bf16_f32 v88, v92, v93
	v_cvt_pk_bf16_f32 v89, v94, v95
	v_cvt_pk_bf16_f32 v90, v90, v91
	v_cvt_pk_bf16_f32 v91, v100, v101
	global_store_dwordx4 v[98:99], v[88:91], off
	v_lshlrev_b32_e32 v92, 16, v88
	v_lshlrev_b32_e32 v93, 16, v89
	v_and_b32_e32 v88, 0xffff0000, v88
	v_and_b32_e32 v89, 0xffff0000, v89
	v_mul_f32_e32 v88, v88, v88
	v_mul_f32_e32 v89, v89, v89
	v_lshlrev_b32_e32 v94, 16, v90
	v_and_b32_e32 v90, 0xffff0000, v90
	v_fmac_f32_e32 v88, v92, v92
	v_fmac_f32_e32 v89, v93, v93
	v_add_f32_e32 v88, v88, v89
	v_mul_f32_e32 v89, v90, v90
	v_lshlrev_b32_e32 v95, 16, v91
	v_and_b32_e32 v91, 0xffff0000, v91
	v_fmac_f32_e32 v89, v94, v94
	v_add_f32_e32 v88, v89, v88
	v_mul_f32_e32 v89, v91, v91
	v_fmac_f32_e32 v89, v95, v95
	v_add_f32_e32 v100, v89, v88
	s_waitcnt vmcnt(15)
	v_lshlrev_b32_e32 v92, 16, v180
	v_and_b32_e32 v93, 0xffff0000, v180
	v_lshlrev_b32_e32 v88, 16, v181
	v_and_b32_e32 v89, 0xffff0000, v181
	v_lshlrev_b32_e32 v94, 16, v182
	v_and_b32_e32 v95, 0xffff0000, v182
	v_lshlrev_b32_e32 v90, 16, v183
	v_and_b32_e32 v91, 0xffff0000, v183
	v_pk_fma_f32 v[86:87], v[86:87], 0.5, v[88:89] op_sel_hi:[1,0,1]
	v_pk_fma_f32 v[84:85], v[84:85], 0.5, v[92:93] op_sel_hi:[1,0,1]
	v_pk_fma_f32 v[88:89], v[82:83], 0.5, v[90:91] op_sel_hi:[1,0,1]
	v_pk_fma_f32 v[82:83], v[80:81], 0.5, v[94:95] op_sel_hi:[1,0,1]
	v_cvt_pk_bf16_f32 v80, v84, v85
	v_cvt_pk_bf16_f32 v81, v86, v87
	v_cvt_pk_bf16_f32 v82, v82, v83
	v_cvt_pk_bf16_f32 v83, v88, v89
	global_store_dwordx4 v[98:99], v[80:83], off offset:256
	v_lshlrev_b32_e32 v84, 16, v80
	v_lshlrev_b32_e32 v85, 16, v81
	v_and_b32_e32 v80, 0xffff0000, v80
	v_and_b32_e32 v81, 0xffff0000, v81
	v_mul_f32_e32 v80, v80, v80
	v_mul_f32_e32 v81, v81, v81
	v_lshlrev_b32_e32 v86, 16, v82
	v_and_b32_e32 v82, 0xffff0000, v82
	v_fmac_f32_e32 v80, v84, v84
	v_fmac_f32_e32 v81, v85, v85
	v_add_f32_e32 v80, v80, v81
	v_mul_f32_e32 v81, v82, v82
	v_lshlrev_b32_e32 v87, 16, v83
	v_and_b32_e32 v83, 0xffff0000, v83
	v_fmac_f32_e32 v81, v86, v86
	v_add_f32_e32 v80, v81, v80
	v_mul_f32_e32 v81, v83, v83
	v_fmac_f32_e32 v81, v87, v87
	v_add_f32_e32 v80, v81, v80
	v_add_f32_e32 v80, v100, v80
	ds_bpermute_b32 v81, v148, v80
	s_waitcnt lgkmcnt(0)
	v_add_f32_e32 v80, v80, v81
	ds_bpermute_b32 v81, v149, v80
	s_and_saveexec_b64 s[20:21], s[4:5]
	s_cbranch_execz .LBB0_287
	s_waitcnt lgkmcnt(0)
	v_add_f32_e32 v82, v80, v81
	s_lshl_b32 s22, s34, 2
	v_lshlrev_b64 v[80:81], 6, v[96:97]
	s_ashr_i32 s23, s22, 31
	v_lshl_add_u64 v[80:81], s[14:15], 0, v[80:81]
	v_lshl_add_u64 v[80:81], s[22:23], 2, v[80:81]
	s_lshl_b32 s68, s45, 2
	v_lshl_add_u64 v[80:81], v[80:81], 0, s[68:69]
	global_store_dword v[80:81], v82, off
; __device__ __forceinline__ float bflo(unsigned w) { return __uint_as_float(w << 16); }
; __device__ __forceinline__ float bfhi(unsigned w) { return __uint_as_float(w & 0xffff0000u); }
; __device__ __forceinline__ v4u pack8(const f32x4 a, const f32x4 b) { v4u w; w.x = cvt_pk_bf16(a[0], a[1]); w.y = cvt_pk_bf16(a[2], a[3]); w.z = cvt_pk_bf16(b[0], b[1]); w.w = cvt_pk_bf16(b[2], b[3]); return w; }
;     __device__ __forceinline__ void operator()(const f32x4 (&acc)[2][2][4][2], const pg8::Unit& u, int wr, int wc, int fr, int fq) const {
;     ...
; #pragma unroll
;         for (int ai = 0; ai < 2; ++ai)
; #pragma unroll
;             for (int m = 0; m < 4; ++m) {
;                 const int row = row0 + ai * 128 + m * 16; float ss = 0.f;
; #pragma unroll
;                 for (int bj = 0; bj < 2; ++bj) {
;                     const size_t off = (size_t)row * DM + col0 + bj * 128;
;                     const v4u b = *(const v4u*)(xb + off);
;                     f32x4 v0, v1; v0[0] = bflo(b.x); v0[1] = bfhi(b.x); v0[2] = bflo(b.y); v0[3] = bfhi(b.y); v1[0] = bflo(b.z); v1[1] = bfhi(b.z); v1[2] = bflo(b.w); v1[3] = bfhi(b.w);
;                     v0 = v0 + alpha * acc[ai][bj][m][0]; v1 = v1 + alpha * acc[ai][bj][m][1];
;                     const v4u w = pack8(v0, v1); *(v4u*)(xb + off) = w;
;                     const float r0 = bflo(w.x), r1 = bfhi(w.x), r2 = bflo(w.y), r3 = bfhi(w.y), r4 = bflo(w.z), r5 = bfhi(w.z), r6 = bflo(w.w), r7 = bfhi(w.w);
;                     ss += (r0 * r0 + r1 * r1) + (r2 * r2 + r3 * r3) + (r4 * r4 + r5 * r5) + (r6 * r6 + r7 * r7);
;                 }
;                 ss += __shfl_xor(ss, 16); ss += __shfl_xor(ss, 32);
;                 if (fq == 0) ssq[(size_t)row * 16 + u.pn * 4 + wc] = ss;
.LBB0_287:
	s_or_b64 exec, exec, s[20:21]
	v_or_b32_e32 v80, 48, v140
	s_waitcnt lgkmcnt(0)
	v_ashrrev_i32_e32 v81, 31, v80
	v_lshlrev_b64 v[82:83], 11, v[80:81]
	v_lshl_add_u64 v[82:83], s[12:13], 0, v[82:83]
	v_lshl_add_u64 v[82:83], v[138:139], 1, v[82:83]
	s_waitcnt vmcnt(15)
	v_lshlrev_b32_e32 v88, 16, v184
	v_and_b32_e32 v89, 0xffff0000, v184
	v_lshlrev_b32_e32 v84, 16, v185
	v_and_b32_e32 v85, 0xffff0000, v185
	v_lshlrev_b32_e32 v90, 16, v186
	v_and_b32_e32 v91, 0xffff0000, v186
	v_lshlrev_b32_e32 v86, 16, v187
	v_and_b32_e32 v87, 0xffff0000, v187
	v_pk_fma_f32 v[78:79], v[78:79], 0.5, v[84:85] op_sel_hi:[1,0,1]
	v_pk_fma_f32 v[76:77], v[76:77], 0.5, v[88:89] op_sel_hi:[1,0,1]
	v_pk_fma_f32 v[84:85], v[74:75], 0.5, v[86:87] op_sel_hi:[1,0,1]
	v_pk_fma_f32 v[74:75], v[72:73], 0.5, v[90:91] op_sel_hi:[1,0,1]
	v_cvt_pk_bf16_f32 v72, v76, v77
	v_cvt_pk_bf16_f32 v73, v78, v79
	v_cvt_pk_bf16_f32 v74, v74, v75
	v_cvt_pk_bf16_f32 v75, v84, v85
	global_store_dwordx4 v[82:83], v[72:75], off
	v_lshlrev_b32_e32 v76, 16, v72
	v_lshlrev_b32_e32 v77, 16, v73
	v_and_b32_e32 v72, 0xffff0000, v72
	v_and_b32_e32 v73, 0xffff0000, v73
	v_mul_f32_e32 v72, v72, v72
	v_mul_f32_e32 v73, v73, v73
	v_lshlrev_b32_e32 v78, 16, v74
	v_and_b32_e32 v74, 0xffff0000, v74
	v_fmac_f32_e32 v72, v76, v76
	v_fmac_f32_e32 v73, v77, v77
	v_add_f32_e32 v72, v72, v73
	v_mul_f32_e32 v73, v74, v74
	v_lshlrev_b32_e32 v79, 16, v75
	v_and_b32_e32 v75, 0xffff0000, v75
	v_fmac_f32_e32 v73, v78, v78
	v_add_f32_e32 v72, v73, v72
	v_mul_f32_e32 v73, v75, v75
	v_fmac_f32_e32 v73, v79, v79
	v_add_f32_e32 v84, v73, v72
	s_waitcnt vmcnt(15)
	v_lshlrev_b32_e32 v76, 16, v188
	v_and_b32_e32 v77, 0xffff0000, v188
	v_lshlrev_b32_e32 v72, 16, v189
	v_and_b32_e32 v73, 0xffff0000, v189
	v_lshlrev_b32_e32 v78, 16, v190
	v_and_b32_e32 v79, 0xffff0000, v190
	v_lshlrev_b32_e32 v74, 16, v191
	v_and_b32_e32 v75, 0xffff0000, v191
	v_pk_fma_f32 v[70:71], v[70:71], 0.5, v[72:73] op_sel_hi:[1,0,1]
	v_pk_fma_f32 v[68:69], v[68:69], 0.5, v[76:77] op_sel_hi:[1,0,1]
	v_pk_fma_f32 v[72:73], v[66:67], 0.5, v[74:75] op_sel_hi:[1,0,1]
	v_pk_fma_f32 v[66:67], v[64:65], 0.5, v[78:79] op_sel_hi:[1,0,1]
	v_cvt_pk_bf16_f32 v64, v68, v69
	v_cvt_pk_bf16_f32 v65, v70, v71
	v_cvt_pk_bf16_f32 v66, v66, v67
	v_cvt_pk_bf16_f32 v67, v72, v73
	global_store_dwordx4 v[82:83], v[64:67], off offset:256
	v_lshlrev_b32_e32 v68, 16, v64
	v_lshlrev_b32_e32 v69, 16, v65
	v_and_b32_e32 v64, 0xffff0000, v64
	v_and_b32_e32 v65, 0xffff0000, v65
	v_mul_f32_e32 v64, v64, v64
	v_mul_f32_e32 v65, v65, v65
	v_lshlrev_b32_e32 v70, 16, v66
	v_and_b32_e32 v66, 0xffff0000, v66
	v_fmac_f32_e32 v64, v68, v68
	v_fmac_f32_e32 v65, v69, v69
	v_add_f32_e32 v64, v64, v65
	v_mul_f32_e32 v65, v66, v66
	v_lshlrev_b32_e32 v71, 16, v67
	v_and_b32_e32 v67, 0xffff0000, v67
	v_fmac_f32_e32 v65, v70, v70
	v_add_f32_e32 v64, v65, v64
	v_mul_f32_e32 v65, v67, v67
	v_fmac_f32_e32 v65, v71, v71
	v_add_f32_e32 v64, v65, v64
	v_add_f32_e32 v64, v84, v64
	ds_bpermute_b32 v65, v148, v64
	s_waitcnt lgkmcnt(0)
	v_add_f32_e32 v64, v64, v65
	ds_bpermute_b32 v65, v149, v64
	s_and_saveexec_b64 s[20:21], s[4:5]
	s_cbranch_execz .LBB0_289
	s_waitcnt lgkmcnt(0)
	v_add_f32_e32 v66, v64, v65
	s_lshl_b32 s22, s34, 2
	v_lshlrev_b64 v[64:65], 6, v[80:81]
	s_ashr_i32 s23, s22, 31
	v_lshl_add_u64 v[64:65], s[14:15], 0, v[64:65]
	v_lshl_add_u64 v[64:65], s[22:23], 2, v[64:65]
	s_lshl_b32 s68, s45, 2
	v_lshl_add_u64 v[64:65], v[64:65], 0, s[68:69]
	global_store_dword v[64:65], v66, off
.LBB0_289:
	s_or_b64 exec, exec, s[20:21]
	v_add_u32_e32 v64, 0x80, v140
	s_waitcnt lgkmcnt(0)
	v_ashrrev_i32_e32 v65, 31, v64
	v_lshlrev_b64 v[66:67], 11, v[64:65]
	v_lshl_add_u64 v[66:67], s[12:13], 0, v[66:67]
	v_lshl_add_u64 v[66:67], v[138:139], 1, v[66:67]
	s_waitcnt vmcnt(15)
	v_lshlrev_b32_e32 v72, 16, v204
	v_and_b32_e32 v73, 0xffff0000, v204
	v_lshlrev_b32_e32 v68, 16, v205
	v_and_b32_e32 v69, 0xffff0000, v205
	v_lshlrev_b32_e32 v74, 16, v206
	v_and_b32_e32 v75, 0xffff0000, v206
	v_lshlrev_b32_e32 v70, 16, v207
	v_and_b32_e32 v71, 0xffff0000, v207
	v_pk_fma_f32 v[62:63], v[62:63], 0.5, v[68:69] op_sel_hi:[1,0,1]
	v_pk_fma_f32 v[60:61], v[60:61], 0.5, v[72:73] op_sel_hi:[1,0,1]
	v_pk_fma_f32 v[68:69], v[58:59], 0.5, v[70:71] op_sel_hi:[1,0,1]
	v_pk_fma_f32 v[58:59], v[56:57], 0.5, v[74:75] op_sel_hi:[1,0,1]
	v_cvt_pk_bf16_f32 v56, v60, v61
	v_cvt_pk_bf16_f32 v57, v62, v63
	v_cvt_pk_bf16_f32 v58, v58, v59
	v_cvt_pk_bf16_f32 v59, v68, v69
	global_store_dwordx4 v[66:67], v[56:59], off
	v_lshlrev_b32_e32 v60, 16, v56
	v_lshlrev_b32_e32 v61, 16, v57
	v_and_b32_e32 v56, 0xffff0000, v56
	v_and_b32_e32 v57, 0xffff0000, v57
	v_mul_f32_e32 v56, v56, v56
	v_mul_f32_e32 v57, v57, v57
	v_lshlrev_b32_e32 v62, 16, v58
	v_and_b32_e32 v58, 0xffff0000, v58
	v_fmac_f32_e32 v56, v60, v60
	v_fmac_f32_e32 v57, v61, v61
	v_add_f32_e32 v56, v56, v57
	v_mul_f32_e32 v57, v58, v58
	v_lshlrev_b32_e32 v63, 16, v59
	v_and_b32_e32 v59, 0xffff0000, v59
	v_fmac_f32_e32 v57, v62, v62
	v_add_f32_e32 v56, v57, v56
	v_mul_f32_e32 v57, v59, v59
	v_fmac_f32_e32 v57, v63, v63
	v_add_f32_e32 v68, v57, v56
	s_waitcnt vmcnt(15)
	v_lshlrev_b32_e32 v60, 16, v208
	v_and_b32_e32 v61, 0xffff0000, v208
	v_lshlrev_b32_e32 v56, 16, v209
	v_and_b32_e32 v57, 0xffff0000, v209
	v_lshlrev_b32_e32 v62, 16, v210
	v_and_b32_e32 v63, 0xffff0000, v210
	v_lshlrev_b32_e32 v58, 16, v211
	v_and_b32_e32 v59, 0xffff0000, v211
	v_pk_fma_f32 v[54:55], v[54:55], 0.5, v[56:57] op_sel_hi:[1,0,1]
	v_pk_fma_f32 v[52:53], v[52:53], 0.5, v[60:61] op_sel_hi:[1,0,1]
	v_pk_fma_f32 v[56:57], v[50:51], 0.5, v[58:59] op_sel_hi:[1,0,1]
	v_pk_fma_f32 v[50:51], v[48:49], 0.5, v[62:63] op_sel_hi:[1,0,1]
	v_cvt_pk_bf16_f32 v48, v52, v53
	v_cvt_pk_bf16_f32 v49, v54, v55
	v_cvt_pk_bf16_f32 v50, v50, v51
	v_cvt_pk_bf16_f32 v51, v56, v57
	global_store_dwordx4 v[66:67], v[48:51], off offset:256
	v_lshlrev_b32_e32 v52, 16, v48
	v_lshlrev_b32_e32 v53, 16, v49
	v_and_b32_e32 v48, 0xffff0000, v48
	v_and_b32_e32 v49, 0xffff0000, v49
	v_mul_f32_e32 v48, v48, v48
	v_mul_f32_e32 v49, v49, v49
	v_lshlrev_b32_e32 v54, 16, v50
	v_and_b32_e32 v50, 0xffff0000, v50
	v_fmac_f32_e32 v48, v52, v52
	v_fmac_f32_e32 v49, v53, v53
	v_add_f32_e32 v48, v48, v49
	v_mul_f32_e32 v49, v50, v50
	v_lshlrev_b32_e32 v55, 16, v51
	v_and_b32_e32 v51, 0xffff0000, v51
	v_fmac_f32_e32 v49, v54, v54
	v_add_f32_e32 v48, v49, v48
	v_mul_f32_e32 v49, v51, v51
	v_fmac_f32_e32 v49, v55, v55
	v_add_f32_e32 v48, v49, v48
	v_add_f32_e32 v48, v68, v48
	ds_bpermute_b32 v49, v148, v48
	s_waitcnt lgkmcnt(0)
	v_add_f32_e32 v48, v48, v49
	ds_bpermute_b32 v49, v149, v48
	s_and_saveexec_b64 s[20:21], s[4:5]
	s_cbranch_execz .LBB0_291
	s_waitcnt lgkmcnt(0)
	v_add_f32_e32 v50, v48, v49
	s_lshl_b32 s22, s34, 2
	v_lshlrev_b64 v[48:49], 6, v[64:65]
	s_ashr_i32 s23, s22, 31
	v_lshl_add_u64 v[48:49], s[14:15], 0, v[48:49]
	v_lshl_add_u64 v[48:49], s[22:23], 2, v[48:49]
	s_lshl_b32 s68, s45, 2
	v_lshl_add_u64 v[48:49], v[48:49], 0, s[68:69]
	global_store_dword v[48:49], v50, off
; __device__ __forceinline__ float bflo(unsigned w) { return __uint_as_float(w << 16); }
; __device__ __forceinline__ float bfhi(unsigned w) { return __uint_as_float(w & 0xffff0000u); }
; __device__ __forceinline__ v4u pack8(const f32x4 a, const f32x4 b) { v4u w; w.x = cvt_pk_bf16(a[0], a[1]); w.y = cvt_pk_bf16(a[2], a[3]); w.z = cvt_pk_bf16(b[0], b[1]); w.w = cvt_pk_bf16(b[2], b[3]); return w; }
;     __device__ __forceinline__ void operator()(const f32x4 (&acc)[2][2][4][2], const pg8::Unit& u, int wr, int wc, int fr, int fq) const {
;     ...
; #pragma unroll
;         for (int ai = 0; ai < 2; ++ai)
; #pragma unroll
;             for (int m = 0; m < 4; ++m) {
;                 const int row = row0 + ai * 128 + m * 16; float ss = 0.f;
; #pragma unroll
;                 for (int bj = 0; bj < 2; ++bj) {
;                     const size_t off = (size_t)row * DM + col0 + bj * 128;
;                     const v4u b = *(const v4u*)(xb + off);
;                     f32x4 v0, v1; v0[0] = bflo(b.x); v0[1] = bfhi(b.x); v0[2] = bflo(b.y); v0[3] = bfhi(b.y); v1[0] = bflo(b.z); v1[1] = bfhi(b.z); v1[2] = bflo(b.w); v1[3] = bfhi(b.w);
;                     v0 = v0 + alpha * acc[ai][bj][m][0]; v1 = v1 + alpha * acc[ai][bj][m][1];
;                     const v4u w = pack8(v0, v1); *(v4u*)(xb + off) = w;
;                     const float r0 = bflo(w.x), r1 = bfhi(w.x), r2 = bflo(w.y), r3 = bfhi(w.y), r4 = bflo(w.z), r5 = bfhi(w.z), r6 = bflo(w.w), r7 = bfhi(w.w);
;                     ss += (r0 * r0 + r1 * r1) + (r2 * r2 + r3 * r3) + (r4 * r4 + r5 * r5) + (r6 * r6 + r7 * r7);
;                 }
;                 ss += __shfl_xor(ss, 16); ss += __shfl_xor(ss, 32);
;                 if (fq == 0) ssq[(size_t)row * 16 + u.pn * 4 + wc] = ss;
.LBB0_291:
	s_or_b64 exec, exec, s[20:21]
	v_add_u32_e32 v48, 0x90, v140
	s_waitcnt lgkmcnt(0)
	v_ashrrev_i32_e32 v49, 31, v48
	v_lshlrev_b64 v[50:51], 11, v[48:49]
	v_lshl_add_u64 v[50:51], s[12:13], 0, v[50:51]
	v_lshl_add_u64 v[50:51], v[138:139], 1, v[50:51]
	s_waitcnt vmcnt(15)
	v_lshlrev_b32_e32 v56, 16, v220
	v_and_b32_e32 v57, 0xffff0000, v220
	v_lshlrev_b32_e32 v52, 16, v221
	v_and_b32_e32 v53, 0xffff0000, v221
	v_lshlrev_b32_e32 v58, 16, v222
	v_and_b32_e32 v59, 0xffff0000, v222
	v_lshlrev_b32_e32 v54, 16, v223
	v_and_b32_e32 v55, 0xffff0000, v223
	v_pk_fma_f32 v[46:47], v[46:47], 0.5, v[52:53] op_sel_hi:[1,0,1]
	v_pk_fma_f32 v[44:45], v[44:45], 0.5, v[56:57] op_sel_hi:[1,0,1]
	v_pk_fma_f32 v[52:53], v[42:43], 0.5, v[54:55] op_sel_hi:[1,0,1]
	v_pk_fma_f32 v[42:43], v[40:41], 0.5, v[58:59] op_sel_hi:[1,0,1]
	v_cvt_pk_bf16_f32 v40, v44, v45
	v_cvt_pk_bf16_f32 v41, v46, v47
	v_cvt_pk_bf16_f32 v42, v42, v43
	v_cvt_pk_bf16_f32 v43, v52, v53
	global_store_dwordx4 v[50:51], v[40:43], off
	v_lshlrev_b32_e32 v44, 16, v40
	v_lshlrev_b32_e32 v45, 16, v41
	v_and_b32_e32 v40, 0xffff0000, v40
	v_and_b32_e32 v41, 0xffff0000, v41
	v_mul_f32_e32 v40, v40, v40
	v_mul_f32_e32 v41, v41, v41
	v_lshlrev_b32_e32 v46, 16, v42
	v_and_b32_e32 v42, 0xffff0000, v42
	v_fmac_f32_e32 v40, v44, v44
	v_fmac_f32_e32 v41, v45, v45
	v_add_f32_e32 v40, v40, v41
	v_mul_f32_e32 v41, v42, v42
	v_lshlrev_b32_e32 v47, 16, v43
	v_and_b32_e32 v43, 0xffff0000, v43
	v_fmac_f32_e32 v41, v46, v46
	v_add_f32_e32 v40, v41, v40
	v_mul_f32_e32 v41, v43, v43
	v_fmac_f32_e32 v41, v47, v47
	v_add_f32_e32 v52, v41, v40
	s_waitcnt vmcnt(15)
	v_lshlrev_b32_e32 v44, 16, v224
	v_and_b32_e32 v45, 0xffff0000, v224
	v_lshlrev_b32_e32 v40, 16, v225
	v_and_b32_e32 v41, 0xffff0000, v225
	v_lshlrev_b32_e32 v46, 16, v226
	v_and_b32_e32 v47, 0xffff0000, v226
	v_lshlrev_b32_e32 v42, 16, v227
	v_and_b32_e32 v43, 0xffff0000, v227
	v_pk_fma_f32 v[38:39], v[38:39], 0.5, v[40:41] op_sel_hi:[1,0,1]
	v_pk_fma_f32 v[36:37], v[36:37], 0.5, v[44:45] op_sel_hi:[1,0,1]
	v_pk_fma_f32 v[40:41], v[34:35], 0.5, v[42:43] op_sel_hi:[1,0,1]
	v_pk_fma_f32 v[34:35], v[32:33], 0.5, v[46:47] op_sel_hi:[1,0,1]
	v_cvt_pk_bf16_f32 v32, v36, v37
	v_cvt_pk_bf16_f32 v33, v38, v39
	v_cvt_pk_bf16_f32 v34, v34, v35
	v_cvt_pk_bf16_f32 v35, v40, v41
	global_store_dwordx4 v[50:51], v[32:35], off offset:256
	v_lshlrev_b32_e32 v36, 16, v32
	v_lshlrev_b32_e32 v37, 16, v33
	v_and_b32_e32 v32, 0xffff0000, v32
	v_and_b32_e32 v33, 0xffff0000, v33
	v_mul_f32_e32 v32, v32, v32
	v_mul_f32_e32 v33, v33, v33
	v_lshlrev_b32_e32 v38, 16, v34
	v_and_b32_e32 v34, 0xffff0000, v34
	v_fmac_f32_e32 v32, v36, v36
	v_fmac_f32_e32 v33, v37, v37
	v_add_f32_e32 v32, v32, v33
	v_mul_f32_e32 v33, v34, v34
	v_lshlrev_b32_e32 v39, 16, v35
	v_and_b32_e32 v35, 0xffff0000, v35
	v_fmac_f32_e32 v33, v38, v38
	v_add_f32_e32 v32, v33, v32
	v_mul_f32_e32 v33, v35, v35
	v_fmac_f32_e32 v33, v39, v39
	v_add_f32_e32 v32, v33, v32
	v_add_f32_e32 v32, v52, v32
	ds_bpermute_b32 v33, v148, v32
	s_waitcnt lgkmcnt(0)
	v_add_f32_e32 v32, v32, v33
	ds_bpermute_b32 v33, v149, v32
	s_and_saveexec_b64 s[20:21], s[4:5]
	s_cbranch_execz .LBB0_293
	s_waitcnt lgkmcnt(0)
	v_add_f32_e32 v34, v32, v33
	s_lshl_b32 s22, s34, 2
	v_lshlrev_b64 v[32:33], 6, v[48:49]
	s_ashr_i32 s23, s22, 31
	v_lshl_add_u64 v[32:33], s[14:15], 0, v[32:33]
	v_lshl_add_u64 v[32:33], s[22:23], 2, v[32:33]
	s_lshl_b32 s68, s45, 2
	v_lshl_add_u64 v[32:33], v[32:33], 0, s[68:69]
	global_store_dword v[32:33], v34, off
; __device__ __forceinline__ float bflo(unsigned w) { return __uint_as_float(w << 16); }
; __device__ __forceinline__ float bfhi(unsigned w) { return __uint_as_float(w & 0xffff0000u); }
; __device__ __forceinline__ v4u pack8(const f32x4 a, const f32x4 b) { v4u w; w.x = cvt_pk_bf16(a[0], a[1]); w.y = cvt_pk_bf16(a[2], a[3]); w.z = cvt_pk_bf16(b[0], b[1]); w.w = cvt_pk_bf16(b[2], b[3]); return w; }
;     __device__ __forceinline__ void operator()(const f32x4 (&acc)[2][2][4][2], const pg8::Unit& u, int wr, int wc, int fr, int fq) const {
;     ...
; #pragma unroll
;         for (int ai = 0; ai < 2; ++ai)
; #pragma unroll
;             for (int m = 0; m < 4; ++m) {
;                 const int row = row0 + ai * 128 + m * 16; float ss = 0.f;
; #pragma unroll
;                 for (int bj = 0; bj < 2; ++bj) {
;                     const size_t off = (size_t)row * DM + col0 + bj * 128;
;                     const v4u b = *(const v4u*)(xb + off);
;                     f32x4 v0, v1; v0[0] = bflo(b.x); v0[1] = bfhi(b.x); v0[2] = bflo(b.y); v0[3] = bfhi(b.y); v1[0] = bflo(b.z); v1[1] = bfhi(b.z); v1[2] = bflo(b.w); v1[3] = bfhi(b.w);
;                     v0 = v0 + alpha * acc[ai][bj][m][0]; v1 = v1 + alpha * acc[ai][bj][m][1];
;                     const v4u w = pack8(v0, v1); *(v4u*)(xb + off) = w;
;                     const float r0 = bflo(w.x), r1 = bfhi(w.x), r2 = bflo(w.y), r3 = bfhi(w.y), r4 = bflo(w.z), r5 = bfhi(w.z), r6 = bflo(w.w), r7 = bfhi(w.w);
;                     ss += (r0 * r0 + r1 * r1) + (r2 * r2 + r3 * r3) + (r4 * r4 + r5 * r5) + (r6 * r6 + r7 * r7);
;                 }
;                 ss += __shfl_xor(ss, 16); ss += __shfl_xor(ss, 32);
;                 if (fq == 0) ssq[(size_t)row * 16 + u.pn * 4 + wc] = ss;
.LBB0_293:
	s_or_b64 exec, exec, s[20:21]
	v_add_u32_e32 v32, 0xa0, v140
	s_waitcnt lgkmcnt(0)
	v_ashrrev_i32_e32 v33, 31, v32
	v_lshlrev_b64 v[34:35], 11, v[32:33]
	v_lshl_add_u64 v[34:35], s[12:13], 0, v[34:35]
	v_lshl_add_u64 v[34:35], v[138:139], 1, v[34:35]
	s_waitcnt vmcnt(15)
	v_lshlrev_b32_e32 v40, 16, v228
	v_and_b32_e32 v41, 0xffff0000, v228
	v_lshlrev_b32_e32 v36, 16, v229
	v_and_b32_e32 v37, 0xffff0000, v229
	v_lshlrev_b32_e32 v42, 16, v230
	v_and_b32_e32 v43, 0xffff0000, v230
	v_lshlrev_b32_e32 v38, 16, v231
	v_and_b32_e32 v39, 0xffff0000, v231
	v_pk_fma_f32 v[30:31], v[30:31], 0.5, v[36:37] op_sel_hi:[1,0,1]
	v_pk_fma_f32 v[28:29], v[28:29], 0.5, v[40:41] op_sel_hi:[1,0,1]
	v_pk_fma_f32 v[36:37], v[26:27], 0.5, v[38:39] op_sel_hi:[1,0,1]
	v_pk_fma_f32 v[26:27], v[24:25], 0.5, v[42:43] op_sel_hi:[1,0,1]
	v_cvt_pk_bf16_f32 v24, v28, v29
	v_cvt_pk_bf16_f32 v25, v30, v31
	v_cvt_pk_bf16_f32 v26, v26, v27
	v_cvt_pk_bf16_f32 v27, v36, v37
	global_store_dwordx4 v[34:35], v[24:27], off
	v_lshlrev_b32_e32 v28, 16, v24
	v_lshlrev_b32_e32 v29, 16, v25
	v_and_b32_e32 v24, 0xffff0000, v24
	v_and_b32_e32 v25, 0xffff0000, v25
	v_mul_f32_e32 v24, v24, v24
	v_mul_f32_e32 v25, v25, v25
	v_lshlrev_b32_e32 v30, 16, v26
	v_and_b32_e32 v26, 0xffff0000, v26
	v_fmac_f32_e32 v24, v28, v28
	v_fmac_f32_e32 v25, v29, v29
	v_add_f32_e32 v24, v24, v25
	v_mul_f32_e32 v25, v26, v26
	v_lshlrev_b32_e32 v31, 16, v27
	v_and_b32_e32 v27, 0xffff0000, v27
	v_fmac_f32_e32 v25, v30, v30
	v_add_f32_e32 v24, v25, v24
	v_mul_f32_e32 v25, v27, v27
	v_fmac_f32_e32 v25, v31, v31
	v_add_f32_e32 v36, v25, v24
	s_waitcnt vmcnt(15)
	v_lshlrev_b32_e32 v28, 16, v232
	v_and_b32_e32 v29, 0xffff0000, v232
	v_lshlrev_b32_e32 v24, 16, v233
	v_and_b32_e32 v25, 0xffff0000, v233
	v_lshlrev_b32_e32 v30, 16, v234
	v_and_b32_e32 v31, 0xffff0000, v234
	v_lshlrev_b32_e32 v26, 16, v235
	v_and_b32_e32 v27, 0xffff0000, v235
	v_pk_fma_f32 v[22:23], v[22:23], 0.5, v[24:25] op_sel_hi:[1,0,1]
	v_pk_fma_f32 v[20:21], v[20:21], 0.5, v[28:29] op_sel_hi:[1,0,1]
	v_pk_fma_f32 v[24:25], v[18:19], 0.5, v[26:27] op_sel_hi:[1,0,1]
	v_pk_fma_f32 v[18:19], v[16:17], 0.5, v[30:31] op_sel_hi:[1,0,1]
	v_cvt_pk_bf16_f32 v16, v20, v21
	v_cvt_pk_bf16_f32 v17, v22, v23
	v_cvt_pk_bf16_f32 v18, v18, v19
	v_cvt_pk_bf16_f32 v19, v24, v25
	global_store_dwordx4 v[34:35], v[16:19], off offset:256
	v_lshlrev_b32_e32 v20, 16, v16
	v_lshlrev_b32_e32 v21, 16, v17
	v_and_b32_e32 v16, 0xffff0000, v16
	v_and_b32_e32 v17, 0xffff0000, v17
	v_mul_f32_e32 v16, v16, v16
	v_mul_f32_e32 v17, v17, v17
	v_lshlrev_b32_e32 v22, 16, v18
	v_and_b32_e32 v18, 0xffff0000, v18
	v_fmac_f32_e32 v16, v20, v20
	v_fmac_f32_e32 v17, v21, v21
	v_add_f32_e32 v16, v16, v17
	v_mul_f32_e32 v17, v18, v18
	v_lshlrev_b32_e32 v23, 16, v19
	v_and_b32_e32 v19, 0xffff0000, v19
	v_fmac_f32_e32 v17, v22, v22
	v_add_f32_e32 v16, v17, v16
	v_mul_f32_e32 v17, v19, v19
	v_fmac_f32_e32 v17, v23, v23
	v_add_f32_e32 v16, v17, v16
	v_add_f32_e32 v16, v36, v16
	ds_bpermute_b32 v17, v148, v16
	s_waitcnt lgkmcnt(0)
	v_add_f32_e32 v16, v16, v17
	ds_bpermute_b32 v17, v149, v16
	s_and_saveexec_b64 s[20:21], s[4:5]
	s_cbranch_execz .LBB0_295
	s_waitcnt lgkmcnt(0)
	v_add_f32_e32 v18, v16, v17
	s_lshl_b32 s22, s34, 2
	v_lshlrev_b64 v[16:17], 6, v[32:33]
	s_ashr_i32 s23, s22, 31
	v_lshl_add_u64 v[16:17], s[14:15], 0, v[16:17]
	v_lshl_add_u64 v[16:17], s[22:23], 2, v[16:17]
	s_lshl_b32 s68, s45, 2
	v_lshl_add_u64 v[16:17], v[16:17], 0, s[68:69]
	global_store_dword v[16:17], v18, off
.LBB0_295:
	s_or_b64 exec, exec, s[20:21]
	v_add_u32_e32 v16, 0xb0, v140
	s_waitcnt lgkmcnt(0)
	v_ashrrev_i32_e32 v17, 31, v16
	v_lshlrev_b64 v[18:19], 11, v[16:17]
	v_lshl_add_u64 v[18:19], s[12:13], 0, v[18:19]
	v_lshl_add_u64 v[18:19], v[138:139], 1, v[18:19]
	s_waitcnt vmcnt(15)
	v_lshlrev_b32_e32 v24, 16, v236
	v_and_b32_e32 v25, 0xffff0000, v236
	v_lshlrev_b32_e32 v20, 16, v237
	v_and_b32_e32 v21, 0xffff0000, v237
	v_lshlrev_b32_e32 v26, 16, v238
	v_and_b32_e32 v27, 0xffff0000, v238
	v_lshlrev_b32_e32 v22, 16, v239
	v_and_b32_e32 v23, 0xffff0000, v239
	v_pk_fma_f32 v[14:15], v[14:15], 0.5, v[20:21] op_sel_hi:[1,0,1]
	v_pk_fma_f32 v[12:13], v[12:13], 0.5, v[24:25] op_sel_hi:[1,0,1]
	v_pk_fma_f32 v[20:21], v[10:11], 0.5, v[22:23] op_sel_hi:[1,0,1]
	v_pk_fma_f32 v[10:11], v[8:9], 0.5, v[26:27] op_sel_hi:[1,0,1]
	v_cvt_pk_bf16_f32 v8, v12, v13
	v_cvt_pk_bf16_f32 v9, v14, v15
	v_cvt_pk_bf16_f32 v10, v10, v11
	v_cvt_pk_bf16_f32 v11, v20, v21
	global_store_dwordx4 v[18:19], v[8:11], off
	v_lshlrev_b32_e32 v12, 16, v8
	v_lshlrev_b32_e32 v13, 16, v9
	v_and_b32_e32 v8, 0xffff0000, v8
	v_and_b32_e32 v9, 0xffff0000, v9
	v_mul_f32_e32 v8, v8, v8
	v_mul_f32_e32 v9, v9, v9
	v_lshlrev_b32_e32 v14, 16, v10
	v_and_b32_e32 v10, 0xffff0000, v10
	v_fmac_f32_e32 v8, v12, v12
	v_fmac_f32_e32 v9, v13, v13
	v_add_f32_e32 v8, v8, v9
	v_mul_f32_e32 v9, v10, v10
	v_lshlrev_b32_e32 v15, 16, v11
	v_and_b32_e32 v11, 0xffff0000, v11
	v_fmac_f32_e32 v9, v14, v14
	v_add_f32_e32 v8, v9, v8
	v_mul_f32_e32 v9, v11, v11
	v_fmac_f32_e32 v9, v15, v15
	v_add_f32_e32 v20, v9, v8
	s_waitcnt vmcnt(15)
	v_lshlrev_b32_e32 v12, 16, v248
	v_and_b32_e32 v13, 0xffff0000, v248
	v_lshlrev_b32_e32 v8, 16, v249
	v_and_b32_e32 v9, 0xffff0000, v249
	v_lshlrev_b32_e32 v14, 16, v250
	v_and_b32_e32 v15, 0xffff0000, v250
	v_lshlrev_b32_e32 v10, 16, v251
	v_and_b32_e32 v11, 0xffff0000, v251
	v_pk_fma_f32 v[6:7], v[6:7], 0.5, v[8:9] op_sel_hi:[1,0,1]
	v_pk_fma_f32 v[4:5], v[4:5], 0.5, v[12:13] op_sel_hi:[1,0,1]
	v_pk_fma_f32 v[8:9], v[2:3], 0.5, v[10:11] op_sel_hi:[1,0,1]
	v_pk_fma_f32 v[2:3], v[0:1], 0.5, v[14:15] op_sel_hi:[1,0,1]
	v_cvt_pk_bf16_f32 v0, v4, v5
	v_cvt_pk_bf16_f32 v1, v6, v7
	v_cvt_pk_bf16_f32 v2, v2, v3
	v_cvt_pk_bf16_f32 v3, v8, v9
	global_store_dwordx4 v[18:19], v[0:3], off offset:256
	v_lshlrev_b32_e32 v4, 16, v0
	v_lshlrev_b32_e32 v5, 16, v1
	v_and_b32_e32 v0, 0xffff0000, v0
	v_and_b32_e32 v1, 0xffff0000, v1
	v_mul_f32_e32 v0, v0, v0
	v_mul_f32_e32 v1, v1, v1
	v_lshlrev_b32_e32 v6, 16, v2
	v_and_b32_e32 v2, 0xffff0000, v2
	v_fmac_f32_e32 v0, v4, v4
	v_fmac_f32_e32 v1, v5, v5
	v_add_f32_e32 v0, v0, v1
	v_mul_f32_e32 v1, v2, v2
	v_lshlrev_b32_e32 v7, 16, v3
	v_and_b32_e32 v3, 0xffff0000, v3
	v_fmac_f32_e32 v1, v6, v6
	v_add_f32_e32 v0, v1, v0
	v_mul_f32_e32 v1, v3, v3
	v_fmac_f32_e32 v1, v7, v7
	v_add_f32_e32 v0, v1, v0
	v_add_f32_e32 v0, v20, v0
	ds_bpermute_b32 v1, v148, v0
	s_waitcnt lgkmcnt(0)
	v_add_f32_e32 v0, v0, v1
	ds_bpermute_b32 v1, v149, v0
	s_and_saveexec_b64 s[20:21], s[4:5]
	s_cbranch_execz .LBB0_297
	s_waitcnt lgkmcnt(0)
	v_add_f32_e32 v2, v0, v1
	s_lshl_b32 s22, s34, 2
	v_lshlrev_b64 v[0:1], 6, v[16:17]
	s_ashr_i32 s23, s22, 31
	v_lshl_add_u64 v[0:1], s[14:15], 0, v[0:1]
	v_lshl_add_u64 v[0:1], s[22:23], 2, v[0:1]
	s_lshl_b32 s68, s45, 2
	v_lshl_add_u64 v[0:1], v[0:1], 0, s[68:69]
	global_store_dword v[0:1], v2, off

; #define PG8_STAGE(bufoff, gbase, voff) do { _Pragma("unroll") for (int _i = 0; _i < 2; ++_i) \
;         __builtin_amdgcn_global_load_lds((const unsigned*)((const char*)(gbase) + (voff)[_i]), (PG8_LAS unsigned*)(lds + (bufoff) + ldsw + _i * 8192), 16, 0, 0); } while (0)
; #define PG8_LDA(dst, b, h) do { _Pragma("unroll") for (int m = 0; m < 4; ++m) _Pragma("unroll") for (int k = 0; k < 2; ++k) dst[m][k] = *(const PG8_LAS bf16x8*)(lds + PG8_SA(b, h) + aoff + m * 2048 + k * 1024); } while (0)
; #define PG8_LDB(dst, b, h) do { _Pragma("unroll") for (int n = 0; n < 2; ++n) _Pragma("unroll") for (int k = 0; k < 2; ++k) dst[n][k] = *(const PG8_LAS bf16x8*)(lds + PG8_SB(b, h) + boff + n * 2048 + k * 1024); } while (0)
; #define PG8_MMA(ai, bj, At, Bt) do { __builtin_amdgcn_s_setprio(1); _Pragma("unroll") for (int m = 0; m < 4; ++m) _Pragma("unroll") for (int n = 0; n < 2; ++n) _Pragma("unroll") for (int k = 0; k < 2; ++k) \
;         acc[ai][bj][m][n] = __builtin_amdgcn_mfma_f32_16x16x32_bf16(Bt[n][k], At[m][k], acc[ai][bj][m][n], 0, 0, 0); __builtin_amdgcn_s_setprio(0); } while (0)
; #define PG8_WAIT_V(n) asm volatile("s_waitcnt vmcnt(" #n ")" ::: "memory")
; #define PG8_WAIT_L(n) asm volatile("s_waitcnt lgkmcnt(" #n ")" ::: "memory")
; #define PG8_BAR __builtin_amdgcn_s_barrier()
; #define PG8_SCHED __builtin_amdgcn_sched_barrier(0)
; template <class Epi, class Sched, bool ALIGN_EPI = false, bool SP2 = false>
; __device__ __forceinline__ void gemm_phase(PG8_LAS unsigned char* lds, const Gemm g, const Sched& S, const Epi& E) {
;     ...
;             PG8_LDB(B0, 0, 0); PG8_LDB(B1, 0, 1); PG8_SCHED; PG8_LDA(At, 0, 0); PG8_STAGE(PG8_SA(1, 1), a1 + hstepA, voffA);
;             PG8_WAIT_V(8); PG8_WAIT_L(0); PG8_BAR; PG8_MMA(0, 0, At, B0); PG8_MMA(0, 1, At, B1); PG8_BAR; PG8_SCHED;
;             PG8_LDA(At, 0, 1); PG8_STAGE(PG8_SB(0, 0), b2, voffB); PG8_STAGE(PG8_SB(0, 1), b2 + hstepB, voffB); PG8_STAGE(PG8_SA(0, 0), a2, voffA);
;             PG8_WAIT_V(8); PG8_WAIT_L(0); PG8_BAR; PG8_MMA(1, 0, At, B0); PG8_MMA(1, 1, At, B1); PG8_BAR; PG8_SCHED;
.LBB0_885:
	v_add_u32_e32 v142, s9, v145
	ds_read_b128 v[138:141], v142
	ds_read_b128 v[148:151], v142 offset:1024
	ds_read_b128 v[152:155], v142 offset:2048
	ds_read_b128 v[156:159], v142 offset:3072
	v_add_u32_e32 v142, s42, v145
	ds_read_b128 v[160:163], v142
	ds_read_b128 v[164:167], v142 offset:1024
	ds_read_b128 v[168:171], v142 offset:2048
	ds_read_b128 v[172:175], v142 offset:3072
	s_add_u32 s2, s28, 0xfffc0080
	s_addc_u32 s30, s29, -1
	s_cmp_eq_u32 s82, 12
	s_cselect_b32 s35, s21, s30
	s_cselect_b32 s34, s27, s2
	s_cselect_b32 s31, s19, s79
	s_cselect_b32 s30, s68, s78
	v_lshl_add_u64 v[142:143], s[28:29], 0, v[136:137]
	s_add_i32 m0, s45, 0xc000
	ds_read_b128 v[176:179], v147
	ds_read_b128 v[180:183], v147 offset:1024
	ds_read_b128 v[184:187], v147 offset:2048
	ds_read_b128 v[188:191], v147 offset:3072
	ds_read_b128 v[204:207], v147 offset:4096
	ds_read_b128 v[208:211], v147 offset:5120
	ds_read_b128 v[218:221], v147 offset:6144
	ds_read_b128 v[222:225], v147 offset:7168
	global_load_lds_dwordx4 v[142:143], off
	v_lshl_add_u64 v[142:143], s[28:29], 0, v[134:135]
	s_add_i32 m0, s45, 0xe000
	s_nop 0
	global_load_lds_dwordx4 v[142:143], off
	s_waitcnt vmcnt(8)
	s_waitcnt lgkmcnt(0)
	s_barrier
	s_setprio 1
	s_waitcnt lgkmcnt(0)
	v_mfma_f32_16x16x32_bf16 v[124:127], v[138:141], v[176:179], v[124:127]
	v_mfma_f32_16x16x32_bf16 v[120:123], v[152:155], v[176:179], v[120:123]
	v_mfma_f32_16x16x32_bf16 v[108:111], v[138:141], v[184:187], v[108:111]
	v_mfma_f32_16x16x32_bf16 v[104:107], v[152:155], v[184:187], v[104:107]
	v_mfma_f32_16x16x32_bf16 v[92:95], v[138:141], v[204:207], v[92:95]
	v_mfma_f32_16x16x32_bf16 v[88:91], v[152:155], v[204:207], v[88:91]
	v_mfma_f32_16x16x32_bf16 v[76:79], v[138:141], v[218:221], v[76:79]
	v_mfma_f32_16x16x32_bf16 v[72:75], v[152:155], v[218:221], v[72:75]
	v_mfma_f32_16x16x32_bf16 v[124:127], v[148:151], v[180:183], v[124:127]
	v_mfma_f32_16x16x32_bf16 v[120:123], v[156:159], v[180:183], v[120:123]
	v_mfma_f32_16x16x32_bf16 v[108:111], v[148:151], v[188:191], v[108:111]
	v_mfma_f32_16x16x32_bf16 v[104:107], v[156:159], v[188:191], v[104:107]
	v_mfma_f32_16x16x32_bf16 v[92:95], v[148:151], v[208:211], v[92:95]
	v_mfma_f32_16x16x32_bf16 v[88:91], v[156:159], v[208:211], v[88:91]
	v_mfma_f32_16x16x32_bf16 v[76:79], v[148:151], v[222:225], v[76:79]
	v_mfma_f32_16x16x32_bf16 v[72:75], v[156:159], v[222:225], v[72:75]
	s_setprio 0
	s_setprio 1
	v_mfma_f32_16x16x32_bf16 v[116:119], v[160:163], v[176:179], v[116:119]
	v_mfma_f32_16x16x32_bf16 v[112:115], v[168:171], v[176:179], v[112:115]
	v_mfma_f32_16x16x32_bf16 v[100:103], v[160:163], v[184:187], v[100:103]
	v_mfma_f32_16x16x32_bf16 v[96:99], v[168:171], v[184:187], v[96:99]
	v_mfma_f32_16x16x32_bf16 v[84:87], v[160:163], v[204:207], v[84:87]
	v_mfma_f32_16x16x32_bf16 v[80:83], v[168:171], v[204:207], v[80:83]
	v_mfma_f32_16x16x32_bf16 v[68:71], v[160:163], v[218:221], v[68:71]
	v_mfma_f32_16x16x32_bf16 v[64:67], v[168:171], v[218:221], v[64:67]
	v_mfma_f32_16x16x32_bf16 v[116:119], v[164:167], v[180:183], v[116:119]
	v_mfma_f32_16x16x32_bf16 v[112:115], v[172:175], v[180:183], v[112:115]
	v_mfma_f32_16x16x32_bf16 v[100:103], v[164:167], v[188:191], v[100:103]
	v_mfma_f32_16x16x32_bf16 v[96:99], v[172:175], v[188:191], v[96:99]
	v_mfma_f32_16x16x32_bf16 v[84:87], v[164:167], v[208:211], v[84:87]
	v_mfma_f32_16x16x32_bf16 v[80:83], v[172:175], v[208:211], v[80:83]
	v_mfma_f32_16x16x32_bf16 v[68:71], v[164:167], v[222:225], v[68:71]
	v_mfma_f32_16x16x32_bf16 v[64:67], v[172:175], v[222:225], v[64:67]
	s_setprio 0
	s_barrier
	s_mov_b32 m0, s40
	v_lshl_add_u64 v[142:143], s[30:31], 0, v[192:193]
	s_add_u32 s84, s30, 0x40000
	ds_read_b128 v[176:179], v147 offset:16384
	ds_read_b128 v[180:183], v147 offset:17408
	ds_read_b128 v[184:187], v147 offset:18432
	ds_read_b128 v[188:191], v147 offset:19456
	ds_read_b128 v[204:207], v147 offset:20480
	ds_read_b128 v[208:211], v147 offset:21504
	ds_read_b128 v[218:221], v147 offset:22528
	ds_read_b128 v[222:225], v147 offset:23552
	global_load_lds_dwordx4 v[142:143], off
	v_lshl_add_u64 v[226:227], s[30:31], 0, v[132:133]
	s_mov_b32 m0, s41
	s_addc_u32 s85, s31, 0
	global_load_lds_dwordx4 v[226:227], off
	v_lshl_add_u64 v[228:229], s[84:85], 0, v[192:193]
	s_mov_b32 m0, s43
	v_lshl_add_u64 v[230:231], s[34:35], 0, v[130:131]
	global_load_lds_dwordx4 v[228:229], off
	v_lshl_add_u64 v[228:229], s[84:85], 0, v[132:133]
	s_mov_b32 m0, s44
	s_nop 0
	global_load_lds_dwordx4 v[228:229], off
	v_lshl_add_u64 v[228:229], s[34:35], 0, v[128:129]
	s_mov_b32 m0, s45
	s_nop 0
	global_load_lds_dwordx4 v[228:229], off
	s_mov_b32 m0, s48
	s_nop 0
	global_load_lds_dwordx4 v[230:231], off
	s_waitcnt vmcnt(8)
	s_waitcnt lgkmcnt(0)
	s_barrier
; #define PG8_STAGE(bufoff, gbase, voff) do { _Pragma("unroll") for (int _i = 0; _i < 2; ++_i) \
;         __builtin_amdgcn_global_load_lds((const unsigned*)((const char*)(gbase) + (voff)[_i]), (PG8_LAS unsigned*)(lds + (bufoff) + ldsw + _i * 8192), 16, 0, 0); } while (0)
; #define PG8_LDA(dst, b, h) do { _Pragma("unroll") for (int m = 0; m < 4; ++m) _Pragma("unroll") for (int k = 0; k < 2; ++k) dst[m][k] = *(const PG8_LAS bf16x8*)(lds + PG8_SA(b, h) + aoff + m * 2048 + k * 1024); } while (0)
; #define PG8_LDB(dst, b, h) do { _Pragma("unroll") for (int n = 0; n < 2; ++n) _Pragma("unroll") for (int k = 0; k < 2; ++k) dst[n][k] = *(const PG8_LAS bf16x8*)(lds + PG8_SB(b, h) + boff + n * 2048 + k * 1024); } while (0)
; #define PG8_MMA(ai, bj, At, Bt) do { __builtin_amdgcn_s_setprio(1); _Pragma("unroll") for (int m = 0; m < 4; ++m) _Pragma("unroll") for (int n = 0; n < 2; ++n) _Pragma("unroll") for (int k = 0; k < 2; ++k) \
;         acc[ai][bj][m][n] = __builtin_amdgcn_mfma_f32_16x16x32_bf16(Bt[n][k], At[m][k], acc[ai][bj][m][n], 0, 0, 0); __builtin_amdgcn_s_setprio(0); } while (0)
; #define PG8_WAIT_V(n) asm volatile("s_waitcnt vmcnt(" #n ")" ::: "memory")
; #define PG8_WAIT_L(n) asm volatile("s_waitcnt lgkmcnt(" #n ")" ::: "memory")
; #define PG8_BAR __builtin_amdgcn_s_barrier()
; #define PG8_SCHED __builtin_amdgcn_sched_barrier(0)
; template <class Epi, class Sched, bool ALIGN_EPI = false, bool SP2 = false>
; __device__ __forceinline__ void gemm_phase(PG8_LAS unsigned char* lds, const Gemm g, const Sched& S, const Epi& E) {
;     ...
;             PG8_WAIT_V(8); PG8_WAIT_L(0); PG8_BAR; PG8_MMA(1, 0, At, B0); PG8_MMA(1, 1, At, B1); PG8_BAR; PG8_SCHED;
;             PG8_LDB(B0, 1, 0); PG8_LDB(B1, 1, 1); PG8_SCHED; PG8_LDA(At, 1, 0); PG8_STAGE(PG8_SA(0, 1), a2 + hstepA, voffA);
;             PG8_WAIT_V(8); PG8_WAIT_L(0); PG8_BAR; PG8_MMA(0, 0, At, B0); PG8_MMA(0, 1, At, B1); PG8_BAR; PG8_SCHED;
	s_setprio 1
	s_waitcnt lgkmcnt(0)
	v_mfma_f32_16x16x32_bf16 v[60:63], v[138:141], v[176:179], v[60:63]
	v_mfma_f32_16x16x32_bf16 v[56:59], v[152:155], v[176:179], v[56:59]
	v_mfma_f32_16x16x32_bf16 v[44:47], v[138:141], v[184:187], v[44:47]
	v_mfma_f32_16x16x32_bf16 v[40:43], v[152:155], v[184:187], v[40:43]
	v_mfma_f32_16x16x32_bf16 v[28:31], v[138:141], v[204:207], v[28:31]
	v_mfma_f32_16x16x32_bf16 v[24:27], v[152:155], v[204:207], v[24:27]
	v_mfma_f32_16x16x32_bf16 v[12:15], v[138:141], v[218:221], v[12:15]
	v_mfma_f32_16x16x32_bf16 v[8:11], v[152:155], v[218:221], v[8:11]
	v_mfma_f32_16x16x32_bf16 v[60:63], v[148:151], v[180:183], v[60:63]
	v_mfma_f32_16x16x32_bf16 v[56:59], v[156:159], v[180:183], v[56:59]
	v_mfma_f32_16x16x32_bf16 v[44:47], v[148:151], v[188:191], v[44:47]
	v_mfma_f32_16x16x32_bf16 v[40:43], v[156:159], v[188:191], v[40:43]
	v_mfma_f32_16x16x32_bf16 v[28:31], v[148:151], v[208:211], v[28:31]
	v_mfma_f32_16x16x32_bf16 v[24:27], v[156:159], v[208:211], v[24:27]
	v_mfma_f32_16x16x32_bf16 v[12:15], v[148:151], v[222:225], v[12:15]
	v_mfma_f32_16x16x32_bf16 v[8:11], v[156:159], v[222:225], v[8:11]
	s_setprio 0
	s_setprio 1
	v_mfma_f32_16x16x32_bf16 v[52:55], v[160:163], v[176:179], v[52:55]
	v_mfma_f32_16x16x32_bf16 v[48:51], v[168:171], v[176:179], v[48:51]
	v_mfma_f32_16x16x32_bf16 v[36:39], v[160:163], v[184:187], v[36:39]
	v_mfma_f32_16x16x32_bf16 v[32:35], v[168:171], v[184:187], v[32:35]
	v_mfma_f32_16x16x32_bf16 v[20:23], v[160:163], v[204:207], v[20:23]
	v_mfma_f32_16x16x32_bf16 v[16:19], v[168:171], v[204:207], v[16:19]
	v_mfma_f32_16x16x32_bf16 v[4:7], v[160:163], v[218:221], v[4:7]
	v_mfma_f32_16x16x32_bf16 v[0:3], v[168:171], v[218:221], v[0:3]
	v_mfma_f32_16x16x32_bf16 v[52:55], v[164:167], v[180:183], v[52:55]
	v_mfma_f32_16x16x32_bf16 v[48:51], v[172:175], v[180:183], v[48:51]
	v_mfma_f32_16x16x32_bf16 v[36:39], v[164:167], v[188:191], v[36:39]
	v_mfma_f32_16x16x32_bf16 v[32:35], v[172:175], v[188:191], v[32:35]
	v_mfma_f32_16x16x32_bf16 v[20:23], v[164:167], v[208:211], v[20:23]
	v_mfma_f32_16x16x32_bf16 v[16:19], v[172:175], v[208:211], v[16:19]
	v_mfma_f32_16x16x32_bf16 v[4:7], v[164:167], v[222:225], v[4:7]
	v_mfma_f32_16x16x32_bf16 v[0:3], v[172:175], v[222:225], v[0:3]
	s_setprio 0
	s_barrier
	v_add_u32_e32 v156, s60, v145
	v_add_u32_e32 v172, s67, v145
	ds_read_b128 v[138:141], v156
	ds_read_b128 v[148:151], v156 offset:1024
	ds_read_b128 v[152:155], v156 offset:2048
	ds_read_b128 v[156:159], v156 offset:3072
	ds_read_b128 v[160:163], v172
	ds_read_b128 v[164:167], v172 offset:1024
	ds_read_b128 v[168:171], v172 offset:2048
	ds_read_b128 v[172:175], v172 offset:3072
	s_add_u32 s34, s34, 0x40000
	s_addc_u32 s35, s35, 0
	s_mov_b32 m0, s49
	v_lshl_add_u64 v[232:233], s[34:35], 0, v[128:129]
	ds_read_b128 v[176:179], v147 offset:32768
	ds_read_b128 v[180:183], v147 offset:33792
	ds_read_b128 v[184:187], v147 offset:34816
	ds_read_b128 v[188:191], v147 offset:35840
	ds_read_b128 v[204:207], v147 offset:36864
	ds_read_b128 v[208:211], v147 offset:37888
	ds_read_b128 v[218:221], v147 offset:38912
	ds_read_b128 v[222:225], v147 offset:39936
	global_load_lds_dwordx4 v[232:233], off
	v_lshl_add_u64 v[232:233], s[34:35], 0, v[130:131]
	s_mov_b32 m0, s50
	s_nop 0
	global_load_lds_dwordx4 v[232:233], off
	s_waitcnt vmcnt(8)
	s_waitcnt lgkmcnt(0)
	s_barrier
	s_setprio 1
	s_waitcnt lgkmcnt(0)
	v_mfma_f32_16x16x32_bf16 v[124:127], v[138:141], v[176:179], v[124:127]
	v_mfma_f32_16x16x32_bf16 v[120:123], v[152:155], v[176:179], v[120:123]
	v_mfma_f32_16x16x32_bf16 v[108:111], v[138:141], v[184:187], v[108:111]
	v_mfma_f32_16x16x32_bf16 v[104:107], v[152:155], v[184:187], v[104:107]
	v_mfma_f32_16x16x32_bf16 v[92:95], v[138:141], v[204:207], v[92:95]
	v_mfma_f32_16x16x32_bf16 v[88:91], v[152:155], v[204:207], v[88:91]
	v_mfma_f32_16x16x32_bf16 v[76:79], v[138:141], v[218:221], v[76:79]
	v_mfma_f32_16x16x32_bf16 v[72:75], v[152:155], v[218:221], v[72:75]
	v_mfma_f32_16x16x32_bf16 v[124:127], v[148:151], v[180:183], v[124:127]
	v_mfma_f32_16x16x32_bf16 v[120:123], v[156:159], v[180:183], v[120:123]
	v_mfma_f32_16x16x32_bf16 v[108:111], v[148:151], v[188:191], v[108:111]
	v_mfma_f32_16x16x32_bf16 v[104:107], v[156:159], v[188:191], v[104:107]
	v_mfma_f32_16x16x32_bf16 v[92:95], v[148:151], v[208:211], v[92:95]
	v_mfma_f32_16x16x32_bf16 v[88:91], v[156:159], v[208:211], v[88:91]
	v_mfma_f32_16x16x32_bf16 v[76:79], v[148:151], v[222:225], v[76:79]
	v_mfma_f32_16x16x32_bf16 v[72:75], v[156:159], v[222:225], v[72:75]
	s_setprio 0
	s_setprio 1
	v_mfma_f32_16x16x32_bf16 v[116:119], v[160:163], v[176:179], v[116:119]
	v_mfma_f32_16x16x32_bf16 v[112:115], v[168:171], v[176:179], v[112:115]
	v_mfma_f32_16x16x32_bf16 v[100:103], v[160:163], v[184:187], v[100:103]
	v_mfma_f32_16x16x32_bf16 v[96:99], v[168:171], v[184:187], v[96:99]
	v_mfma_f32_16x16x32_bf16 v[84:87], v[160:163], v[204:207], v[84:87]
	v_mfma_f32_16x16x32_bf16 v[80:83], v[168:171], v[204:207], v[80:83]
	v_mfma_f32_16x16x32_bf16 v[68:71], v[160:163], v[218:221], v[68:71]
	v_mfma_f32_16x16x32_bf16 v[64:67], v[168:171], v[218:221], v[64:67]
	v_mfma_f32_16x16x32_bf16 v[116:119], v[164:167], v[180:183], v[116:119]
	v_mfma_f32_16x16x32_bf16 v[112:115], v[172:175], v[180:183], v[112:115]
	v_mfma_f32_16x16x32_bf16 v[100:103], v[164:167], v[188:191], v[100:103]
	v_mfma_f32_16x16x32_bf16 v[96:99], v[172:175], v[188:191], v[96:99]
	v_mfma_f32_16x16x32_bf16 v[84:87], v[164:167], v[208:211], v[84:87]
	v_mfma_f32_16x16x32_bf16 v[80:83], v[172:175], v[208:211], v[80:83]
	v_mfma_f32_16x16x32_bf16 v[68:71], v[164:167], v[222:225], v[68:71]
	v_mfma_f32_16x16x32_bf16 v[64:67], v[172:175], v[222:225], v[64:67]
	s_setprio 0
	s_barrier
; #define PG8_STAGE(bufoff, gbase, voff) do { _Pragma("unroll") for (int _i = 0; _i < 2; ++_i) \
;         __builtin_amdgcn_global_load_lds((const unsigned*)((const char*)(gbase) + (voff)[_i]), (PG8_LAS unsigned*)(lds + (bufoff) + ldsw + _i * 8192), 16, 0, 0); } while (0)
; #define PG8_LDA(dst, b, h) do { _Pragma("unroll") for (int m = 0; m < 4; ++m) _Pragma("unroll") for (int k = 0; k < 2; ++k) dst[m][k] = *(const PG8_LAS bf16x8*)(lds + PG8_SA(b, h) + aoff + m * 2048 + k * 1024); } while (0)
; #define PG8_MMA(ai, bj, At, Bt) do { __builtin_amdgcn_s_setprio(1); _Pragma("unroll") for (int m = 0; m < 4; ++m) _Pragma("unroll") for (int n = 0; n < 2; ++n) _Pragma("unroll") for (int k = 0; k < 2; ++k) \
;         acc[ai][bj][m][n] = __builtin_amdgcn_mfma_f32_16x16x32_bf16(Bt[n][k], At[m][k], acc[ai][bj][m][n], 0, 0, 0); __builtin_amdgcn_s_setprio(0); } while (0)
; #define PG8_WAIT_V(n) asm volatile("s_waitcnt vmcnt(" #n ")" ::: "memory")
; #define PG8_WAIT_L(n) asm volatile("s_waitcnt lgkmcnt(" #n ")" ::: "memory")
; #define PG8_BAR __builtin_amdgcn_s_barrier()
; #define PG8_SCHED __builtin_amdgcn_sched_barrier(0)
; template <class Epi, class Sched, bool ALIGN_EPI = false, bool SP2 = false>
; __device__ __forceinline__ void gemm_phase(PG8_LAS unsigned char* lds, const Gemm g, const Sched& S, const Epi& E) {
;     ...
;             PG8_WAIT_V(8); PG8_WAIT_L(0); PG8_BAR; PG8_MMA(0, 0, At, B0); PG8_MMA(0, 1, At, B1); PG8_BAR; PG8_SCHED;
;             PG8_LDA(At, 1, 1); PG8_STAGE(PG8_SB(1, 0), b3, voffB); PG8_STAGE(PG8_SB(1, 1), b3 + hstepB, voffB); PG8_STAGE(PG8_SA(1, 0), a3, voffA);
;             PG8_WAIT_V(8); PG8_WAIT_L(0); PG8_BAR; PG8_MMA(1, 0, At, B0); PG8_MMA(1, 1, At, B1); PG8_BAR; PG8_SCHED;
;     __device__ __forceinline__ void operator()(const f32x4 (&acc)[2][2][4][2], const pg8::Unit& u, int wr, int wc, int fr, int fq) const {
;     ...
;                     const size_t off = (size_t)row * DM + col0 + bj * 128;
;                     const v4u b = *(const v4u*)(xb + off);
	s_mov_b32 m0, s61
	v_lshl_add_u64 v[142:143], v[142:143], 0, s[76:77]
	s_add_u32 s30, s30, 0x40080
	ds_read_b128 v[176:179], v147 offset:49152
	ds_read_b128 v[180:183], v147 offset:50176
	ds_read_b128 v[184:187], v147 offset:51200
	ds_read_b128 v[188:191], v147 offset:52224
	ds_read_b128 v[204:207], v147 offset:53248
	ds_read_b128 v[208:211], v147 offset:54272
	ds_read_b128 v[218:221], v147 offset:55296
	ds_read_b128 v[222:225], v147 offset:56320
	global_load_lds_dwordx4 v[142:143], off
	v_lshl_add_u64 v[142:143], v[226:227], 0, s[76:77]
	s_mov_b32 m0, s64
	s_addc_u32 s31, s31, 0
	global_load_lds_dwordx4 v[142:143], off
	v_lshl_add_u64 v[142:143], s[30:31], 0, v[192:193]
	s_mov_b32 m0, s70
	s_nop 0
	global_load_lds_dwordx4 v[142:143], off
	v_lshl_add_u64 v[142:143], s[30:31], 0, v[132:133]
	s_mov_b32 m0, s71
	s_nop 0
	global_load_lds_dwordx4 v[142:143], off
	v_lshl_add_u64 v[142:143], v[228:229], 0, s[76:77]
	s_mov_b32 m0, s65
	s_nop 0
	global_load_lds_dwordx4 v[142:143], off
	v_lshl_add_u64 v[142:143], v[230:231], 0, s[76:77]
	s_mov_b32 m0, s66
	s_nop 0
	global_load_lds_dwordx4 v[142:143], off
	s_waitcnt vmcnt(8)
	s_waitcnt lgkmcnt(0)
	s_barrier
	s_setprio 1
	s_waitcnt lgkmcnt(0)
	v_mfma_f32_16x16x32_bf16 v[60:63], v[138:141], v[176:179], v[60:63]
	v_mfma_f32_16x16x32_bf16 v[56:59], v[152:155], v[176:179], v[56:59]
	v_mfma_f32_16x16x32_bf16 v[44:47], v[138:141], v[184:187], v[44:47]
	v_mfma_f32_16x16x32_bf16 v[40:43], v[152:155], v[184:187], v[40:43]
	v_mfma_f32_16x16x32_bf16 v[28:31], v[138:141], v[204:207], v[28:31]
	v_mfma_f32_16x16x32_bf16 v[24:27], v[152:155], v[204:207], v[24:27]
	v_mfma_f32_16x16x32_bf16 v[12:15], v[138:141], v[218:221], v[12:15]
	v_mfma_f32_16x16x32_bf16 v[8:11], v[152:155], v[218:221], v[8:11]
	v_mfma_f32_16x16x32_bf16 v[60:63], v[148:151], v[180:183], v[60:63]
	v_mfma_f32_16x16x32_bf16 v[56:59], v[156:159], v[180:183], v[56:59]
	v_mfma_f32_16x16x32_bf16 v[44:47], v[148:151], v[188:191], v[44:47]
	v_mfma_f32_16x16x32_bf16 v[40:43], v[156:159], v[188:191], v[40:43]
	v_mfma_f32_16x16x32_bf16 v[28:31], v[148:151], v[208:211], v[28:31]
	v_mfma_f32_16x16x32_bf16 v[24:27], v[156:159], v[208:211], v[24:27]
	v_mfma_f32_16x16x32_bf16 v[12:15], v[148:151], v[222:225], v[12:15]
	v_mfma_f32_16x16x32_bf16 v[8:11], v[156:159], v[222:225], v[8:11]
	s_setprio 0
	s_setprio 1
	v_mfma_f32_16x16x32_bf16 v[52:55], v[160:163], v[176:179], v[52:55]
	v_mfma_f32_16x16x32_bf16 v[48:51], v[168:171], v[176:179], v[48:51]
	v_mfma_f32_16x16x32_bf16 v[36:39], v[160:163], v[184:187], v[36:39]
	v_mfma_f32_16x16x32_bf16 v[32:35], v[168:171], v[184:187], v[32:35]
	v_mfma_f32_16x16x32_bf16 v[20:23], v[160:163], v[204:207], v[20:23]
	v_mfma_f32_16x16x32_bf16 v[16:19], v[168:171], v[204:207], v[16:19]
	v_mfma_f32_16x16x32_bf16 v[4:7], v[160:163], v[218:221], v[4:7]
	v_mfma_f32_16x16x32_bf16 v[0:3], v[168:171], v[218:221], v[0:3]
	v_mfma_f32_16x16x32_bf16 v[52:55], v[164:167], v[180:183], v[52:55]
	v_mfma_f32_16x16x32_bf16 v[48:51], v[172:175], v[180:183], v[48:51]
	v_mfma_f32_16x16x32_bf16 v[36:39], v[164:167], v[188:191], v[36:39]
	v_mfma_f32_16x16x32_bf16 v[32:35], v[172:175], v[188:191], v[32:35]
	v_mfma_f32_16x16x32_bf16 v[20:23], v[164:167], v[208:211], v[20:23]
	v_mfma_f32_16x16x32_bf16 v[16:19], v[172:175], v[208:211], v[16:19]
	v_mfma_f32_16x16x32_bf16 v[4:7], v[164:167], v[222:225], v[4:7]
	v_mfma_f32_16x16x32_bf16 v[0:3], v[172:175], v[222:225], v[0:3]
	s_setprio 0
	s_barrier
	s_add_i32 s82, s82, 2
	s_add_u32 s78, s78, 0x100
	s_addc_u32 s79, s79, 0
	s_add_u32 s28, s28, 0x100
	s_addc_u32 s29, s29, 0
	s_cmp_gt_u32 s82, 13
	s_cbranch_scc0 .LBB0_885
	v_lshl_add_u32 v159, s26, 8, v144
	v_lshl_or_b32 v158, s8, 8, v146
	v_lshlrev_b32_e32 v159, 11, v159
	v_lshl_add_u32 v159, v158, 1, v159
	v_add_u32_e32 v218, 0x8000, v159
	v_add_u32_e32 v219, 0x10000, v159
	v_add_u32_e32 v240, 0x18000, v159
	v_add_u32_e32 v241, 0x40000, v159
	v_add_u32_e32 v245, 0x48000, v159
	v_add_u32_e32 v246, 0x50000, v159
	v_add_u32_e32 v247, 0x58000, v159
	global_load_dwordx4 v[160:163], v159, s[12:13]
	global_load_dwordx4 v[164:167], v159, s[12:13] offset:256
	global_load_dwordx4 v[168:171], v218, s[12:13]
	global_load_dwordx4 v[172:175], v218, s[12:13] offset:256
	global_load_dwordx4 v[176:179], v219, s[12:13]
	global_load_dwordx4 v[180:183], v219, s[12:13] offset:256
	global_load_dwordx4 v[184:187], v240, s[12:13]
	global_load_dwordx4 v[188:191], v240, s[12:13] offset:256
	global_load_dwordx4 v[204:207], v241, s[12:13]
	global_load_dwordx4 v[208:211], v241, s[12:13] offset:256
	global_load_dwordx4 v[220:223], v245, s[12:13]
	global_load_dwordx4 v[224:227], v245, s[12:13] offset:256
	global_load_dwordx4 v[228:231], v246, s[12:13]
	global_load_dwordx4 v[232:235], v246, s[12:13] offset:256
	global_load_dwordx4 v[236:239], v247, s[12:13]
	global_load_dwordx4 v[248:251], v247, s[12:13] offset:256
	s_and_b64 vcc, exec, s[16:17]
	s_cbranch_vccz .LBB0_888
	s_barrier
; __device__ __forceinline__ float bflo(unsigned w) { return __uint_as_float(w << 16); }
; __device__ __forceinline__ float bfhi(unsigned w) { return __uint_as_float(w & 0xffff0000u); }
; __device__ __forceinline__ v4u pack8(const f32x4 a, const f32x4 b) { v4u w; w.x = cvt_pk_bf16(a[0], a[1]); w.y = cvt_pk_bf16(a[2], a[3]); w.z = cvt_pk_bf16(b[0], b[1]); w.w = cvt_pk_bf16(b[2], b[3]); return w; }
;     __device__ __forceinline__ void operator()(const f32x4 (&acc)[2][2][4][2], const pg8::Unit& u, int wr, int wc, int fr, int fq) const {
;     ...
; #pragma unroll
;         for (int ai = 0; ai < 2; ++ai)
; #pragma unroll
;             for (int m = 0; m < 4; ++m) {
;                 const int row = row0 + ai * 128 + m * 16; float ss = 0.f;
; #pragma unroll
;                 for (int bj = 0; bj < 2; ++bj) {
;                     const size_t off = (size_t)row * DM + col0 + bj * 128;
;                     const v4u b = *(const v4u*)(xb + off);
;                     f32x4 v0, v1; v0[0] = bflo(b.x); v0[1] = bfhi(b.x); v0[2] = bflo(b.y); v0[3] = bfhi(b.y); v1[0] = bflo(b.z); v1[1] = bfhi(b.z); v1[2] = bflo(b.w); v1[3] = bfhi(b.w);
;                     v0 = v0 + alpha * acc[ai][bj][m][0]; v1 = v1 + alpha * acc[ai][bj][m][1];
;                     const v4u w = pack8(v0, v1); *(v4u*)(xb + off) = w;
;                     const float r0 = bflo(w.x), r1 = bfhi(w.x), r2 = bflo(w.y), r3 = bfhi(w.y), r4 = bflo(w.z), r5 = bfhi(w.z), r6 = bflo(w.w), r7 = bfhi(w.w);
;                     ss += (r0 * r0 + r1 * r1) + (r2 * r2 + r3 * r3) + (r4 * r4 + r5 * r5) + (r6 * r6 + r7 * r7);
;                 }
;                 ss += __shfl_xor(ss, 16); ss += __shfl_xor(ss, 32);
;                 if (fq == 0) ssq[(size_t)row * 16 + u.pn * 4 + wc] = ss;
.LBB0_888:
	v_and_b32_e32 v142, 64, v215
	v_xor_b32_e32 v141, 16, v215
	v_add_u32_e32 v142, 64, v142
	v_cmp_lt_i32_e32 vcc, v141, v142
	v_lshl_add_u32 v140, s26, 8, v144
	v_lshl_or_b32 v138, s8, 8, v146
	v_cndmask_b32_e32 v141, v215, v141, vcc
	v_lshlrev_b32_e32 v148, 2, v141
	v_xor_b32_e32 v141, 32, v215
	v_cmp_lt_i32_e32 vcc, v141, v142
	v_ashrrev_i32_e32 v139, 31, v138
	s_nop 0
	v_cndmask_b32_e32 v141, v215, v141, vcc
	v_lshlrev_b32_e32 v149, 2, v141
	v_ashrrev_i32_e32 v141, 31, v140
	v_lshlrev_b64 v[142:143], 11, v[140:141]
	v_lshl_add_u64 v[142:143], s[12:13], 0, v[142:143]
	v_lshl_add_u64 v[142:143], v[138:139], 1, v[142:143]
	s_waitcnt vmcnt(15)
	v_lshlrev_b32_e32 v154, 16, v160
	v_and_b32_e32 v155, 0xffff0000, v160
	v_lshlrev_b32_e32 v150, 16, v161
	v_and_b32_e32 v151, 0xffff0000, v161
	v_lshlrev_b32_e32 v156, 16, v162
	v_and_b32_e32 v157, 0xffff0000, v162
	v_lshlrev_b32_e32 v152, 16, v163
	v_and_b32_e32 v153, 0xffff0000, v163
	v_pk_add_f32 v[126:127], v[126:127], v[150:151]
	v_pk_add_f32 v[124:125], v[124:125], v[154:155]
	v_pk_add_f32 v[150:151], v[122:123], v[152:153]
	v_pk_add_f32 v[122:123], v[120:121], v[156:157]
	v_cvt_pk_bf16_f32 v120, v124, v125
	v_cvt_pk_bf16_f32 v121, v126, v127
	v_cvt_pk_bf16_f32 v122, v122, v123
	v_cvt_pk_bf16_f32 v123, v150, v151
	global_store_dwordx4 v[142:143], v[120:123], off
	v_lshlrev_b32_e32 v124, 16, v120
	v_lshlrev_b32_e32 v125, 16, v121
	v_and_b32_e32 v120, 0xffff0000, v120
	v_and_b32_e32 v121, 0xffff0000, v121
	v_mul_f32_e32 v120, v120, v120
	v_mul_f32_e32 v121, v121, v121
	v_lshlrev_b32_e32 v126, 16, v122
	v_and_b32_e32 v122, 0xffff0000, v122
	v_fmac_f32_e32 v120, v124, v124
	v_fmac_f32_e32 v121, v125, v125
	v_add_f32_e32 v120, v120, v121
	v_mul_f32_e32 v121, v122, v122
	v_lshlrev_b32_e32 v127, 16, v123
	v_and_b32_e32 v123, 0xffff0000, v123
	v_fmac_f32_e32 v121, v126, v126
	v_add_f32_e32 v120, v121, v120
	v_mul_f32_e32 v121, v123, v123
	v_fmac_f32_e32 v121, v127, v127
	v_add_f32_e32 v150, v121, v120
	s_waitcnt vmcnt(15)
	v_lshlrev_b32_e32 v124, 16, v164
	v_and_b32_e32 v125, 0xffff0000, v164
	v_lshlrev_b32_e32 v120, 16, v165
	v_and_b32_e32 v121, 0xffff0000, v165
	v_lshlrev_b32_e32 v126, 16, v166
	v_and_b32_e32 v127, 0xffff0000, v166
	v_lshlrev_b32_e32 v122, 16, v167
	v_and_b32_e32 v123, 0xffff0000, v167
	v_pk_add_f32 v[118:119], v[118:119], v[120:121]
	v_pk_add_f32 v[116:117], v[116:117], v[124:125]
	v_pk_add_f32 v[120:121], v[114:115], v[122:123]
	v_pk_add_f32 v[114:115], v[112:113], v[126:127]
	v_cvt_pk_bf16_f32 v112, v116, v117
	v_cvt_pk_bf16_f32 v113, v118, v119
	v_cvt_pk_bf16_f32 v114, v114, v115
	v_cvt_pk_bf16_f32 v115, v120, v121
	global_store_dwordx4 v[142:143], v[112:115], off offset:256
	v_lshlrev_b32_e32 v116, 16, v112
	v_lshlrev_b32_e32 v117, 16, v113
	v_and_b32_e32 v112, 0xffff0000, v112
	v_and_b32_e32 v113, 0xffff0000, v113
	v_mul_f32_e32 v112, v112, v112
	v_mul_f32_e32 v113, v113, v113
	v_lshlrev_b32_e32 v118, 16, v114
	v_and_b32_e32 v114, 0xffff0000, v114
	v_fmac_f32_e32 v112, v116, v116
	v_fmac_f32_e32 v113, v117, v117
	v_add_f32_e32 v112, v112, v113
	v_mul_f32_e32 v113, v114, v114
	v_lshlrev_b32_e32 v119, 16, v115
	v_and_b32_e32 v115, 0xffff0000, v115
	v_fmac_f32_e32 v113, v118, v118
	v_add_f32_e32 v112, v113, v112
	v_mul_f32_e32 v113, v115, v115
	v_fmac_f32_e32 v113, v119, v119
	v_add_f32_e32 v112, v113, v112
	v_add_f32_e32 v112, v150, v112
	ds_bpermute_b32 v113, v148, v112
	s_waitcnt lgkmcnt(0)
	v_add_f32_e32 v112, v112, v113
	ds_bpermute_b32 v113, v149, v112
	s_and_saveexec_b64 s[26:27], s[4:5]
	s_cbranch_execz .LBB0_890
	s_waitcnt lgkmcnt(0)
	v_add_f32_e32 v114, v112, v113
	s_lshl_b32 s28, s8, 2
	v_lshlrev_b64 v[112:113], 6, v[140:141]
	s_ashr_i32 s29, s28, 31
	v_lshl_add_u64 v[112:113], s[14:15], 0, v[112:113]
	v_lshl_add_u64 v[112:113], s[28:29], 2, v[112:113]
	s_lshl_b32 s68, s51, 2
	v_lshl_add_u64 v[112:113], v[112:113], 0, s[68:69]
	global_store_dword v[112:113], v114, off
.LBB0_890:
	s_or_b64 exec, exec, s[26:27]
	v_or_b32_e32 v112, 16, v140
	s_waitcnt lgkmcnt(0)
	v_ashrrev_i32_e32 v113, 31, v112
	v_lshlrev_b64 v[114:115], 11, v[112:113]
	v_lshl_add_u64 v[114:115], s[12:13], 0, v[114:115]
	v_lshl_add_u64 v[114:115], v[138:139], 1, v[114:115]
	s_waitcnt vmcnt(15)
	v_lshlrev_b32_e32 v120, 16, v168
	v_and_b32_e32 v121, 0xffff0000, v168
	v_lshlrev_b32_e32 v116, 16, v169
	v_and_b32_e32 v117, 0xffff0000, v169
	v_lshlrev_b32_e32 v122, 16, v170
	v_and_b32_e32 v123, 0xffff0000, v170
	v_lshlrev_b32_e32 v118, 16, v171
	v_and_b32_e32 v119, 0xffff0000, v171
	v_pk_add_f32 v[110:111], v[110:111], v[116:117]
	v_pk_add_f32 v[108:109], v[108:109], v[120:121]
	v_pk_add_f32 v[116:117], v[106:107], v[118:119]
	v_pk_add_f32 v[106:107], v[104:105], v[122:123]
	v_cvt_pk_bf16_f32 v104, v108, v109
	v_cvt_pk_bf16_f32 v105, v110, v111
	v_cvt_pk_bf16_f32 v106, v106, v107
	v_cvt_pk_bf16_f32 v107, v116, v117
	global_store_dwordx4 v[114:115], v[104:107], off
	v_lshlrev_b32_e32 v108, 16, v104
	v_lshlrev_b32_e32 v109, 16, v105
	v_and_b32_e32 v104, 0xffff0000, v104
	v_and_b32_e32 v105, 0xffff0000, v105
	v_mul_f32_e32 v104, v104, v104
	v_mul_f32_e32 v105, v105, v105
	v_lshlrev_b32_e32 v110, 16, v106
	v_and_b32_e32 v106, 0xffff0000, v106
	v_fmac_f32_e32 v104, v108, v108
	v_fmac_f32_e32 v105, v109, v109
	v_add_f32_e32 v104, v104, v105
	v_mul_f32_e32 v105, v106, v106
	v_lshlrev_b32_e32 v111, 16, v107
	v_and_b32_e32 v107, 0xffff0000, v107
	v_fmac_f32_e32 v105, v110, v110
	v_add_f32_e32 v104, v105, v104
	v_mul_f32_e32 v105, v107, v107
	v_fmac_f32_e32 v105, v111, v111
	v_add_f32_e32 v116, v105, v104
	s_waitcnt vmcnt(15)
	v_lshlrev_b32_e32 v108, 16, v172
	v_and_b32_e32 v109, 0xffff0000, v172
	v_lshlrev_b32_e32 v104, 16, v173
	v_and_b32_e32 v105, 0xffff0000, v173
	v_lshlrev_b32_e32 v110, 16, v174
	v_and_b32_e32 v111, 0xffff0000, v174
	v_lshlrev_b32_e32 v106, 16, v175
	v_and_b32_e32 v107, 0xffff0000, v175
	v_pk_add_f32 v[102:103], v[102:103], v[104:105]
	v_pk_add_f32 v[100:101], v[100:101], v[108:109]
	v_pk_add_f32 v[104:105], v[98:99], v[106:107]
	v_pk_add_f32 v[98:99], v[96:97], v[110:111]
	v_cvt_pk_bf16_f32 v96, v100, v101
	v_cvt_pk_bf16_f32 v97, v102, v103
	v_cvt_pk_bf16_f32 v98, v98, v99
	v_cvt_pk_bf16_f32 v99, v104, v105
	global_store_dwordx4 v[114:115], v[96:99], off offset:256
	v_lshlrev_b32_e32 v100, 16, v96
	v_lshlrev_b32_e32 v101, 16, v97
	v_and_b32_e32 v96, 0xffff0000, v96
	v_and_b32_e32 v97, 0xffff0000, v97
	v_mul_f32_e32 v96, v96, v96
	v_mul_f32_e32 v97, v97, v97
	v_lshlrev_b32_e32 v102, 16, v98
	v_and_b32_e32 v98, 0xffff0000, v98
	v_fmac_f32_e32 v96, v100, v100
	v_fmac_f32_e32 v97, v101, v101
	v_add_f32_e32 v96, v96, v97
	v_mul_f32_e32 v97, v98, v98
	v_lshlrev_b32_e32 v103, 16, v99
	v_and_b32_e32 v99, 0xffff0000, v99
	v_fmac_f32_e32 v97, v102, v102
	v_add_f32_e32 v96, v97, v96
	v_mul_f32_e32 v97, v99, v99
	v_fmac_f32_e32 v97, v103, v103
	v_add_f32_e32 v96, v97, v96
	v_add_f32_e32 v96, v116, v96
	ds_bpermute_b32 v97, v148, v96
	s_waitcnt lgkmcnt(0)
	v_add_f32_e32 v96, v96, v97
	ds_bpermute_b32 v97, v149, v96
	s_and_saveexec_b64 s[26:27], s[4:5]
	s_cbranch_execz .LBB0_892
; __device__ __forceinline__ float bflo(unsigned w) { return __uint_as_float(w << 16); }
; __device__ __forceinline__ float bfhi(unsigned w) { return __uint_as_float(w & 0xffff0000u); }
; __device__ __forceinline__ v4u pack8(const f32x4 a, const f32x4 b) { v4u w; w.x = cvt_pk_bf16(a[0], a[1]); w.y = cvt_pk_bf16(a[2], a[3]); w.z = cvt_pk_bf16(b[0], b[1]); w.w = cvt_pk_bf16(b[2], b[3]); return w; }
;     __device__ __forceinline__ void operator()(const f32x4 (&acc)[2][2][4][2], const pg8::Unit& u, int wr, int wc, int fr, int fq) const {
;     ...
; #pragma unroll
;         for (int ai = 0; ai < 2; ++ai)
; #pragma unroll
;             for (int m = 0; m < 4; ++m) {
;                 const int row = row0 + ai * 128 + m * 16; float ss = 0.f;
; #pragma unroll
;                 for (int bj = 0; bj < 2; ++bj) {
;                     const size_t off = (size_t)row * DM + col0 + bj * 128;
;                     const v4u b = *(const v4u*)(xb + off);
;                     f32x4 v0, v1; v0[0] = bflo(b.x); v0[1] = bfhi(b.x); v0[2] = bflo(b.y); v0[3] = bfhi(b.y); v1[0] = bflo(b.z); v1[1] = bfhi(b.z); v1[2] = bflo(b.w); v1[3] = bfhi(b.w);
;                     v0 = v0 + alpha * acc[ai][bj][m][0]; v1 = v1 + alpha * acc[ai][bj][m][1];
;                     const v4u w = pack8(v0, v1); *(v4u*)(xb + off) = w;
;                     const float r0 = bflo(w.x), r1 = bfhi(w.x), r2 = bflo(w.y), r3 = bfhi(w.y), r4 = bflo(w.z), r5 = bfhi(w.z), r6 = bflo(w.w), r7 = bfhi(w.w);
;                     ss += (r0 * r0 + r1 * r1) + (r2 * r2 + r3 * r3) + (r4 * r4 + r5 * r5) + (r6 * r6 + r7 * r7);
;                 }
;                 ss += __shfl_xor(ss, 16); ss += __shfl_xor(ss, 32);
;                 if (fq == 0) ssq[(size_t)row * 16 + u.pn * 4 + wc] = ss;
	s_waitcnt lgkmcnt(0)
	v_add_f32_e32 v98, v96, v97
	s_lshl_b32 s28, s8, 2
	v_lshlrev_b64 v[96:97], 6, v[112:113]
	s_ashr_i32 s29, s28, 31
	v_lshl_add_u64 v[96:97], s[14:15], 0, v[96:97]
	v_lshl_add_u64 v[96:97], s[28:29], 2, v[96:97]
	s_lshl_b32 s68, s51, 2
	v_lshl_add_u64 v[96:97], v[96:97], 0, s[68:69]
	global_store_dword v[96:97], v98, off
.LBB0_892:
	s_or_b64 exec, exec, s[26:27]
	v_or_b32_e32 v96, 32, v140
	s_waitcnt lgkmcnt(0)
	v_ashrrev_i32_e32 v97, 31, v96
	v_lshlrev_b64 v[98:99], 11, v[96:97]
	v_lshl_add_u64 v[98:99], s[12:13], 0, v[98:99]
	v_lshl_add_u64 v[98:99], v[138:139], 1, v[98:99]
	s_waitcnt vmcnt(15)
	v_lshlrev_b32_e32 v104, 16, v176
	v_and_b32_e32 v105, 0xffff0000, v176
	v_lshlrev_b32_e32 v100, 16, v177
	v_and_b32_e32 v101, 0xffff0000, v177
	v_lshlrev_b32_e32 v106, 16, v178
	v_and_b32_e32 v107, 0xffff0000, v178
	v_lshlrev_b32_e32 v102, 16, v179
	v_and_b32_e32 v103, 0xffff0000, v179
	v_pk_add_f32 v[94:95], v[94:95], v[100:101]
	v_pk_add_f32 v[92:93], v[92:93], v[104:105]
	v_pk_add_f32 v[100:101], v[90:91], v[102:103]
	v_pk_add_f32 v[90:91], v[88:89], v[106:107]
	v_cvt_pk_bf16_f32 v88, v92, v93
	v_cvt_pk_bf16_f32 v89, v94, v95
	v_cvt_pk_bf16_f32 v90, v90, v91
	v_cvt_pk_bf16_f32 v91, v100, v101
	global_store_dwordx4 v[98:99], v[88:91], off
	v_lshlrev_b32_e32 v92, 16, v88
	v_lshlrev_b32_e32 v93, 16, v89
	v_and_b32_e32 v88, 0xffff0000, v88
	v_and_b32_e32 v89, 0xffff0000, v89
	v_mul_f32_e32 v88, v88, v88
	v_mul_f32_e32 v89, v89, v89
	v_lshlrev_b32_e32 v94, 16, v90
	v_and_b32_e32 v90, 0xffff0000, v90
	v_fmac_f32_e32 v88, v92, v92
	v_fmac_f32_e32 v89, v93, v93
	v_add_f32_e32 v88, v88, v89
	v_mul_f32_e32 v89, v90, v90
	v_lshlrev_b32_e32 v95, 16, v91
	v_and_b32_e32 v91, 0xffff0000, v91
	v_fmac_f32_e32 v89, v94, v94
	v_add_f32_e32 v88, v89, v88
	v_mul_f32_e32 v89, v91, v91
	v_fmac_f32_e32 v89, v95, v95
	v_add_f32_e32 v100, v89, v88
	s_waitcnt vmcnt(15)
	v_lshlrev_b32_e32 v92, 16, v180
	v_and_b32_e32 v93, 0xffff0000, v180
	v_lshlrev_b32_e32 v88, 16, v181
	v_and_b32_e32 v89, 0xffff0000, v181
	v_lshlrev_b32_e32 v94, 16, v182
	v_and_b32_e32 v95, 0xffff0000, v182
	v_lshlrev_b32_e32 v90, 16, v183
	v_and_b32_e32 v91, 0xffff0000, v183
	v_pk_add_f32 v[86:87], v[86:87], v[88:89]
	v_pk_add_f32 v[84:85], v[84:85], v[92:93]
	v_pk_add_f32 v[88:89], v[82:83], v[90:91]
	v_pk_add_f32 v[82:83], v[80:81], v[94:95]
	v_cvt_pk_bf16_f32 v80, v84, v85
	v_cvt_pk_bf16_f32 v81, v86, v87
	v_cvt_pk_bf16_f32 v82, v82, v83
	v_cvt_pk_bf16_f32 v83, v88, v89
	global_store_dwordx4 v[98:99], v[80:83], off offset:256
	v_lshlrev_b32_e32 v84, 16, v80
	v_lshlrev_b32_e32 v85, 16, v81
	v_and_b32_e32 v80, 0xffff0000, v80
	v_and_b32_e32 v81, 0xffff0000, v81
	v_mul_f32_e32 v80, v80, v80
	v_mul_f32_e32 v81, v81, v81
	v_lshlrev_b32_e32 v86, 16, v82
	v_and_b32_e32 v82, 0xffff0000, v82
	v_fmac_f32_e32 v80, v84, v84
	v_fmac_f32_e32 v81, v85, v85
	v_add_f32_e32 v80, v80, v81
	v_mul_f32_e32 v81, v82, v82
	v_lshlrev_b32_e32 v87, 16, v83
	v_and_b32_e32 v83, 0xffff0000, v83
	v_fmac_f32_e32 v81, v86, v86
	v_add_f32_e32 v80, v81, v80
	v_mul_f32_e32 v81, v83, v83
	v_fmac_f32_e32 v81, v87, v87
	v_add_f32_e32 v80, v81, v80
	v_add_f32_e32 v80, v100, v80
	ds_bpermute_b32 v81, v148, v80
	s_waitcnt lgkmcnt(0)
	v_add_f32_e32 v80, v80, v81
	ds_bpermute_b32 v81, v149, v80
	s_and_saveexec_b64 s[26:27], s[4:5]
	s_cbranch_execz .LBB0_894
	s_waitcnt lgkmcnt(0)
	v_add_f32_e32 v82, v80, v81
	s_lshl_b32 s28, s8, 2
	v_lshlrev_b64 v[80:81], 6, v[96:97]
	s_ashr_i32 s29, s28, 31
	v_lshl_add_u64 v[80:81], s[14:15], 0, v[80:81]
	v_lshl_add_u64 v[80:81], s[28:29], 2, v[80:81]
	s_lshl_b32 s68, s51, 2
	v_lshl_add_u64 v[80:81], v[80:81], 0, s[68:69]
	global_store_dword v[80:81], v82, off
.LBB0_894:
	s_or_b64 exec, exec, s[26:27]
	v_or_b32_e32 v80, 48, v140
	s_waitcnt lgkmcnt(0)
	v_ashrrev_i32_e32 v81, 31, v80
	v_lshlrev_b64 v[82:83], 11, v[80:81]
	v_lshl_add_u64 v[82:83], s[12:13], 0, v[82:83]
	v_lshl_add_u64 v[82:83], v[138:139], 1, v[82:83]
	s_waitcnt vmcnt(15)
	v_lshlrev_b32_e32 v88, 16, v184
	v_and_b32_e32 v89, 0xffff0000, v184
	v_lshlrev_b32_e32 v84, 16, v185
	v_and_b32_e32 v85, 0xffff0000, v185
	v_lshlrev_b32_e32 v90, 16, v186
	v_and_b32_e32 v91, 0xffff0000, v186
	v_lshlrev_b32_e32 v86, 16, v187
	v_and_b32_e32 v87, 0xffff0000, v187
	v_pk_add_f32 v[78:79], v[78:79], v[84:85]
	v_pk_add_f32 v[76:77], v[76:77], v[88:89]
	v_pk_add_f32 v[84:85], v[74:75], v[86:87]
	v_pk_add_f32 v[74:75], v[72:73], v[90:91]
	v_cvt_pk_bf16_f32 v72, v76, v77
	v_cvt_pk_bf16_f32 v73, v78, v79
	v_cvt_pk_bf16_f32 v74, v74, v75
	v_cvt_pk_bf16_f32 v75, v84, v85
	global_store_dwordx4 v[82:83], v[72:75], off
	v_lshlrev_b32_e32 v76, 16, v72
	v_lshlrev_b32_e32 v77, 16, v73
	v_and_b32_e32 v72, 0xffff0000, v72
	v_and_b32_e32 v73, 0xffff0000, v73
	v_mul_f32_e32 v72, v72, v72
	v_mul_f32_e32 v73, v73, v73
	v_lshlrev_b32_e32 v78, 16, v74
	v_and_b32_e32 v74, 0xffff0000, v74
	v_fmac_f32_e32 v72, v76, v76
	v_fmac_f32_e32 v73, v77, v77
	v_add_f32_e32 v72, v72, v73
	v_mul_f32_e32 v73, v74, v74
	v_lshlrev_b32_e32 v79, 16, v75
	v_and_b32_e32 v75, 0xffff0000, v75
	v_fmac_f32_e32 v73, v78, v78
	v_add_f32_e32 v72, v73, v72
	v_mul_f32_e32 v73, v75, v75
	v_fmac_f32_e32 v73, v79, v79
	v_add_f32_e32 v84, v73, v72
	s_waitcnt vmcnt(15)
	v_lshlrev_b32_e32 v76, 16, v188
	v_and_b32_e32 v77, 0xffff0000, v188
	v_lshlrev_b32_e32 v72, 16, v189
	v_and_b32_e32 v73, 0xffff0000, v189
	v_lshlrev_b32_e32 v78, 16, v190
	v_and_b32_e32 v79, 0xffff0000, v190
	v_lshlrev_b32_e32 v74, 16, v191
	v_and_b32_e32 v75, 0xffff0000, v191
	v_pk_add_f32 v[70:71], v[70:71], v[72:73]
	v_pk_add_f32 v[68:69], v[68:69], v[76:77]
	v_pk_add_f32 v[72:73], v[66:67], v[74:75]
	v_pk_add_f32 v[66:67], v[64:65], v[78:79]
	v_cvt_pk_bf16_f32 v64, v68, v69
	v_cvt_pk_bf16_f32 v65, v70, v71
	v_cvt_pk_bf16_f32 v66, v66, v67
	v_cvt_pk_bf16_f32 v67, v72, v73
	global_store_dwordx4 v[82:83], v[64:67], off offset:256
	v_lshlrev_b32_e32 v68, 16, v64
	v_lshlrev_b32_e32 v69, 16, v65
	v_and_b32_e32 v64, 0xffff0000, v64
	v_and_b32_e32 v65, 0xffff0000, v65
	v_mul_f32_e32 v64, v64, v64
	v_mul_f32_e32 v65, v65, v65
	v_lshlrev_b32_e32 v70, 16, v66
	v_and_b32_e32 v66, 0xffff0000, v66
	v_fmac_f32_e32 v64, v68, v68
	v_fmac_f32_e32 v65, v69, v69
	v_add_f32_e32 v64, v64, v65
	v_mul_f32_e32 v65, v66, v66
	v_lshlrev_b32_e32 v71, 16, v67
	v_and_b32_e32 v67, 0xffff0000, v67
	v_fmac_f32_e32 v65, v70, v70
	v_add_f32_e32 v64, v65, v64
	v_mul_f32_e32 v65, v67, v67
	v_fmac_f32_e32 v65, v71, v71
	v_add_f32_e32 v64, v65, v64
	v_add_f32_e32 v64, v84, v64
	ds_bpermute_b32 v65, v148, v64
	s_waitcnt lgkmcnt(0)
	v_add_f32_e32 v64, v64, v65
	ds_bpermute_b32 v65, v149, v64
	s_and_saveexec_b64 s[26:27], s[4:5]
	s_cbranch_execz .LBB0_896
	s_waitcnt lgkmcnt(0)
	v_add_f32_e32 v66, v64, v65
	s_lshl_b32 s28, s8, 2
	v_lshlrev_b64 v[64:65], 6, v[80:81]
	s_ashr_i32 s29, s28, 31
	v_lshl_add_u64 v[64:65], s[14:15], 0, v[64:65]
	v_lshl_add_u64 v[64:65], s[28:29], 2, v[64:65]
	s_lshl_b32 s68, s51, 2
	v_lshl_add_u64 v[64:65], v[64:65], 0, s[68:69]
	global_store_dword v[64:65], v66, off
; __device__ __forceinline__ float bflo(unsigned w) { return __uint_as_float(w << 16); }
; __device__ __forceinline__ float bfhi(unsigned w) { return __uint_as_float(w & 0xffff0000u); }
; __device__ __forceinline__ v4u pack8(const f32x4 a, const f32x4 b) { v4u w; w.x = cvt_pk_bf16(a[0], a[1]); w.y = cvt_pk_bf16(a[2], a[3]); w.z = cvt_pk_bf16(b[0], b[1]); w.w = cvt_pk_bf16(b[2], b[3]); return w; }
;     __device__ __forceinline__ void operator()(const f32x4 (&acc)[2][2][4][2], const pg8::Unit& u, int wr, int wc, int fr, int fq) const {
;     ...
; #pragma unroll
;         for (int ai = 0; ai < 2; ++ai)
; #pragma unroll
;             for (int m = 0; m < 4; ++m) {
;                 const int row = row0 + ai * 128 + m * 16; float ss = 0.f;
; #pragma unroll
;                 for (int bj = 0; bj < 2; ++bj) {
;                     const size_t off = (size_t)row * DM + col0 + bj * 128;
;                     const v4u b = *(const v4u*)(xb + off);
;                     f32x4 v0, v1; v0[0] = bflo(b.x); v0[1] = bfhi(b.x); v0[2] = bflo(b.y); v0[3] = bfhi(b.y); v1[0] = bflo(b.z); v1[1] = bfhi(b.z); v1[2] = bflo(b.w); v1[3] = bfhi(b.w);
;                     v0 = v0 + alpha * acc[ai][bj][m][0]; v1 = v1 + alpha * acc[ai][bj][m][1];
;                     const v4u w = pack8(v0, v1); *(v4u*)(xb + off) = w;
;                     const float r0 = bflo(w.x), r1 = bfhi(w.x), r2 = bflo(w.y), r3 = bfhi(w.y), r4 = bflo(w.z), r5 = bfhi(w.z), r6 = bflo(w.w), r7 = bfhi(w.w);
;                     ss += (r0 * r0 + r1 * r1) + (r2 * r2 + r3 * r3) + (r4 * r4 + r5 * r5) + (r6 * r6 + r7 * r7);
;                 }
;                 ss += __shfl_xor(ss, 16); ss += __shfl_xor(ss, 32);
;                 if (fq == 0) ssq[(size_t)row * 16 + u.pn * 4 + wc] = ss;
.LBB0_896:
	s_or_b64 exec, exec, s[26:27]
	v_add_u32_e32 v64, 0x80, v140
	s_waitcnt lgkmcnt(0)
	v_ashrrev_i32_e32 v65, 31, v64
	v_lshlrev_b64 v[66:67], 11, v[64:65]
	v_lshl_add_u64 v[66:67], s[12:13], 0, v[66:67]
	v_lshl_add_u64 v[66:67], v[138:139], 1, v[66:67]
	s_waitcnt vmcnt(15)
	v_lshlrev_b32_e32 v72, 16, v204
	v_and_b32_e32 v73, 0xffff0000, v204
	v_lshlrev_b32_e32 v68, 16, v205
	v_and_b32_e32 v69, 0xffff0000, v205
	v_lshlrev_b32_e32 v74, 16, v206
	v_and_b32_e32 v75, 0xffff0000, v206
	v_lshlrev_b32_e32 v70, 16, v207
	v_and_b32_e32 v71, 0xffff0000, v207
	v_pk_add_f32 v[62:63], v[62:63], v[68:69]
	v_pk_add_f32 v[60:61], v[60:61], v[72:73]
	v_pk_add_f32 v[68:69], v[58:59], v[70:71]
	v_pk_add_f32 v[58:59], v[56:57], v[74:75]
	v_cvt_pk_bf16_f32 v56, v60, v61
	v_cvt_pk_bf16_f32 v57, v62, v63
	v_cvt_pk_bf16_f32 v58, v58, v59
	v_cvt_pk_bf16_f32 v59, v68, v69
	global_store_dwordx4 v[66:67], v[56:59], off
	v_lshlrev_b32_e32 v60, 16, v56
	v_lshlrev_b32_e32 v61, 16, v57
	v_and_b32_e32 v56, 0xffff0000, v56
	v_and_b32_e32 v57, 0xffff0000, v57
	v_mul_f32_e32 v56, v56, v56
	v_mul_f32_e32 v57, v57, v57
	v_lshlrev_b32_e32 v62, 16, v58
	v_and_b32_e32 v58, 0xffff0000, v58
	v_fmac_f32_e32 v56, v60, v60
	v_fmac_f32_e32 v57, v61, v61
	v_add_f32_e32 v56, v56, v57
	v_mul_f32_e32 v57, v58, v58
	v_lshlrev_b32_e32 v63, 16, v59
	v_and_b32_e32 v59, 0xffff0000, v59
	v_fmac_f32_e32 v57, v62, v62
	v_add_f32_e32 v56, v57, v56
	v_mul_f32_e32 v57, v59, v59
	v_fmac_f32_e32 v57, v63, v63
	v_add_f32_e32 v68, v57, v56
	s_waitcnt vmcnt(15)
	v_lshlrev_b32_e32 v60, 16, v208
	v_and_b32_e32 v61, 0xffff0000, v208
	v_lshlrev_b32_e32 v56, 16, v209
	v_and_b32_e32 v57, 0xffff0000, v209
	v_lshlrev_b32_e32 v62, 16, v210
	v_and_b32_e32 v63, 0xffff0000, v210
	v_lshlrev_b32_e32 v58, 16, v211
	v_and_b32_e32 v59, 0xffff0000, v211
	v_pk_add_f32 v[54:55], v[54:55], v[56:57]
	v_pk_add_f32 v[52:53], v[52:53], v[60:61]
	v_pk_add_f32 v[56:57], v[50:51], v[58:59]
	v_pk_add_f32 v[50:51], v[48:49], v[62:63]
	v_cvt_pk_bf16_f32 v48, v52, v53
	v_cvt_pk_bf16_f32 v49, v54, v55
	v_cvt_pk_bf16_f32 v50, v50, v51
	v_cvt_pk_bf16_f32 v51, v56, v57
	global_store_dwordx4 v[66:67], v[48:51], off offset:256
	v_lshlrev_b32_e32 v52, 16, v48
	v_lshlrev_b32_e32 v53, 16, v49
	v_and_b32_e32 v48, 0xffff0000, v48
	v_and_b32_e32 v49, 0xffff0000, v49
	v_mul_f32_e32 v48, v48, v48
	v_mul_f32_e32 v49, v49, v49
	v_lshlrev_b32_e32 v54, 16, v50
	v_and_b32_e32 v50, 0xffff0000, v50
	v_fmac_f32_e32 v48, v52, v52
	v_fmac_f32_e32 v49, v53, v53
	v_add_f32_e32 v48, v48, v49
	v_mul_f32_e32 v49, v50, v50
	v_lshlrev_b32_e32 v55, 16, v51
	v_and_b32_e32 v51, 0xffff0000, v51
	v_fmac_f32_e32 v49, v54, v54
	v_add_f32_e32 v48, v49, v48
	v_mul_f32_e32 v49, v51, v51
	v_fmac_f32_e32 v49, v55, v55
	v_add_f32_e32 v48, v49, v48
	v_add_f32_e32 v48, v68, v48
	ds_bpermute_b32 v49, v148, v48
	s_waitcnt lgkmcnt(0)
	v_add_f32_e32 v48, v48, v49
	ds_bpermute_b32 v49, v149, v48
	s_and_saveexec_b64 s[26:27], s[4:5]
	s_cbranch_execz .LBB0_898
	s_waitcnt lgkmcnt(0)
	v_add_f32_e32 v50, v48, v49
	s_lshl_b32 s28, s8, 2
	v_lshlrev_b64 v[48:49], 6, v[64:65]
	s_ashr_i32 s29, s28, 31
	v_lshl_add_u64 v[48:49], s[14:15], 0, v[48:49]
	v_lshl_add_u64 v[48:49], s[28:29], 2, v[48:49]
	s_lshl_b32 s68, s51, 2
	v_lshl_add_u64 v[48:49], v[48:49], 0, s[68:69]
	global_store_dword v[48:49], v50, off
.LBB0_898:
	s_or_b64 exec, exec, s[26:27]
	v_add_u32_e32 v48, 0x90, v140
	s_waitcnt lgkmcnt(0)
	v_ashrrev_i32_e32 v49, 31, v48
	v_lshlrev_b64 v[50:51], 11, v[48:49]
	v_lshl_add_u64 v[50:51], s[12:13], 0, v[50:51]
	v_lshl_add_u64 v[50:51], v[138:139], 1, v[50:51]
	s_waitcnt vmcnt(15)
	v_lshlrev_b32_e32 v56, 16, v220
	v_and_b32_e32 v57, 0xffff0000, v220
	v_lshlrev_b32_e32 v52, 16, v221
	v_and_b32_e32 v53, 0xffff0000, v221
	v_lshlrev_b32_e32 v58, 16, v222
	v_and_b32_e32 v59, 0xffff0000, v222
	v_lshlrev_b32_e32 v54, 16, v223
	v_and_b32_e32 v55, 0xffff0000, v223
	v_pk_add_f32 v[46:47], v[46:47], v[52:53]
	v_pk_add_f32 v[44:45], v[44:45], v[56:57]
	v_pk_add_f32 v[52:53], v[42:43], v[54:55]
	v_pk_add_f32 v[42:43], v[40:41], v[58:59]
	v_cvt_pk_bf16_f32 v40, v44, v45
	v_cvt_pk_bf16_f32 v41, v46, v47
	v_cvt_pk_bf16_f32 v42, v42, v43
	v_cvt_pk_bf16_f32 v43, v52, v53
	global_store_dwordx4 v[50:51], v[40:43], off
	v_lshlrev_b32_e32 v44, 16, v40
	v_lshlrev_b32_e32 v45, 16, v41
	v_and_b32_e32 v40, 0xffff0000, v40
	v_and_b32_e32 v41, 0xffff0000, v41
	v_mul_f32_e32 v40, v40, v40
	v_mul_f32_e32 v41, v41, v41
	v_lshlrev_b32_e32 v46, 16, v42
	v_and_b32_e32 v42, 0xffff0000, v42
	v_fmac_f32_e32 v40, v44, v44
	v_fmac_f32_e32 v41, v45, v45
	v_add_f32_e32 v40, v40, v41
	v_mul_f32_e32 v41, v42, v42
	v_lshlrev_b32_e32 v47, 16, v43
	v_and_b32_e32 v43, 0xffff0000, v43
	v_fmac_f32_e32 v41, v46, v46
	v_add_f32_e32 v40, v41, v40
	v_mul_f32_e32 v41, v43, v43
	v_fmac_f32_e32 v41, v47, v47
	v_add_f32_e32 v52, v41, v40
	s_waitcnt vmcnt(15)
	v_lshlrev_b32_e32 v44, 16, v224
	v_and_b32_e32 v45, 0xffff0000, v224
	v_lshlrev_b32_e32 v40, 16, v225
	v_and_b32_e32 v41, 0xffff0000, v225
	v_lshlrev_b32_e32 v46, 16, v226
	v_and_b32_e32 v47, 0xffff0000, v226
	v_lshlrev_b32_e32 v42, 16, v227
	v_and_b32_e32 v43, 0xffff0000, v227
	v_pk_add_f32 v[38:39], v[38:39], v[40:41]
	v_pk_add_f32 v[36:37], v[36:37], v[44:45]
	v_pk_add_f32 v[40:41], v[34:35], v[42:43]
	v_pk_add_f32 v[34:35], v[32:33], v[46:47]
	v_cvt_pk_bf16_f32 v32, v36, v37
	v_cvt_pk_bf16_f32 v33, v38, v39
	v_cvt_pk_bf16_f32 v34, v34, v35
	v_cvt_pk_bf16_f32 v35, v40, v41
	global_store_dwordx4 v[50:51], v[32:35], off offset:256
	v_lshlrev_b32_e32 v36, 16, v32
	v_lshlrev_b32_e32 v37, 16, v33
	v_and_b32_e32 v32, 0xffff0000, v32
	v_and_b32_e32 v33, 0xffff0000, v33
	v_mul_f32_e32 v32, v32, v32
	v_mul_f32_e32 v33, v33, v33
	v_lshlrev_b32_e32 v38, 16, v34
	v_and_b32_e32 v34, 0xffff0000, v34
	v_fmac_f32_e32 v32, v36, v36
	v_fmac_f32_e32 v33, v37, v37
	v_add_f32_e32 v32, v32, v33
	v_mul_f32_e32 v33, v34, v34
	v_lshlrev_b32_e32 v39, 16, v35
	v_and_b32_e32 v35, 0xffff0000, v35
	v_fmac_f32_e32 v33, v38, v38
	v_add_f32_e32 v32, v33, v32
	v_mul_f32_e32 v33, v35, v35
	v_fmac_f32_e32 v33, v39, v39
	v_add_f32_e32 v32, v33, v32
	v_add_f32_e32 v32, v52, v32
	ds_bpermute_b32 v33, v148, v32
	s_waitcnt lgkmcnt(0)
	v_add_f32_e32 v32, v32, v33
	ds_bpermute_b32 v33, v149, v32
	s_and_saveexec_b64 s[26:27], s[4:5]
	s_cbranch_execz .LBB0_900
	s_waitcnt lgkmcnt(0)
	v_add_f32_e32 v34, v32, v33
	s_lshl_b32 s28, s8, 2
	v_lshlrev_b64 v[32:33], 6, v[48:49]
	s_ashr_i32 s29, s28, 31
	v_lshl_add_u64 v[32:33], s[14:15], 0, v[32:33]
	v_lshl_add_u64 v[32:33], s[28:29], 2, v[32:33]
	s_lshl_b32 s68, s51, 2
	v_lshl_add_u64 v[32:33], v[32:33], 0, s[68:69]
	global_store_dword v[32:33], v34, off
; __device__ __forceinline__ float bflo(unsigned w) { return __uint_as_float(w << 16); }
; __device__ __forceinline__ float bfhi(unsigned w) { return __uint_as_float(w & 0xffff0000u); }
; __device__ __forceinline__ v4u pack8(const f32x4 a, const f32x4 b) { v4u w; w.x = cvt_pk_bf16(a[0], a[1]); w.y = cvt_pk_bf16(a[2], a[3]); w.z = cvt_pk_bf16(b[0], b[1]); w.w = cvt_pk_bf16(b[2], b[3]); return w; }
;     __device__ __forceinline__ void operator()(const f32x4 (&acc)[2][2][4][2], const pg8::Unit& u, int wr, int wc, int fr, int fq) const {
;     ...
; #pragma unroll
;         for (int ai = 0; ai < 2; ++ai)
; #pragma unroll
;             for (int m = 0; m < 4; ++m) {
;                 const int row = row0 + ai * 128 + m * 16; float ss = 0.f;
; #pragma unroll
;                 for (int bj = 0; bj < 2; ++bj) {
;                     const size_t off = (size_t)row * DM + col0 + bj * 128;
;                     const v4u b = *(const v4u*)(xb + off);
;                     f32x4 v0, v1; v0[0] = bflo(b.x); v0[1] = bfhi(b.x); v0[2] = bflo(b.y); v0[3] = bfhi(b.y); v1[0] = bflo(b.z); v1[1] = bfhi(b.z); v1[2] = bflo(b.w); v1[3] = bfhi(b.w);
;                     v0 = v0 + alpha * acc[ai][bj][m][0]; v1 = v1 + alpha * acc[ai][bj][m][1];
;                     const v4u w = pack8(v0, v1); *(v4u*)(xb + off) = w;
;                     const float r0 = bflo(w.x), r1 = bfhi(w.x), r2 = bflo(w.y), r3 = bfhi(w.y), r4 = bflo(w.z), r5 = bfhi(w.z), r6 = bflo(w.w), r7 = bfhi(w.w);
;                     ss += (r0 * r0 + r1 * r1) + (r2 * r2 + r3 * r3) + (r4 * r4 + r5 * r5) + (r6 * r6 + r7 * r7);
;                 }
;                 ss += __shfl_xor(ss, 16); ss += __shfl_xor(ss, 32);
;                 if (fq == 0) ssq[(size_t)row * 16 + u.pn * 4 + wc] = ss;
.LBB0_900:
	s_or_b64 exec, exec, s[26:27]
	v_add_u32_e32 v32, 0xa0, v140
	s_waitcnt lgkmcnt(0)
	v_ashrrev_i32_e32 v33, 31, v32
	v_lshlrev_b64 v[34:35], 11, v[32:33]
	v_lshl_add_u64 v[34:35], s[12:13], 0, v[34:35]
	v_lshl_add_u64 v[34:35], v[138:139], 1, v[34:35]
	s_waitcnt vmcnt(15)
	v_lshlrev_b32_e32 v40, 16, v228
	v_and_b32_e32 v41, 0xffff0000, v228
	v_lshlrev_b32_e32 v36, 16, v229
	v_and_b32_e32 v37, 0xffff0000, v229
	v_lshlrev_b32_e32 v42, 16, v230
	v_and_b32_e32 v43, 0xffff0000, v230
	v_lshlrev_b32_e32 v38, 16, v231
	v_and_b32_e32 v39, 0xffff0000, v231
	v_pk_add_f32 v[30:31], v[30:31], v[36:37]
	v_pk_add_f32 v[28:29], v[28:29], v[40:41]
	v_pk_add_f32 v[36:37], v[26:27], v[38:39]
	v_pk_add_f32 v[26:27], v[24:25], v[42:43]
	v_cvt_pk_bf16_f32 v24, v28, v29
	v_cvt_pk_bf16_f32 v25, v30, v31
	v_cvt_pk_bf16_f32 v26, v26, v27
	v_cvt_pk_bf16_f32 v27, v36, v37
	global_store_dwordx4 v[34:35], v[24:27], off
	v_lshlrev_b32_e32 v28, 16, v24
	v_lshlrev_b32_e32 v29, 16, v25
	v_and_b32_e32 v24, 0xffff0000, v24
	v_and_b32_e32 v25, 0xffff0000, v25
	v_mul_f32_e32 v24, v24, v24
	v_mul_f32_e32 v25, v25, v25
	v_lshlrev_b32_e32 v30, 16, v26
	v_and_b32_e32 v26, 0xffff0000, v26
	v_fmac_f32_e32 v24, v28, v28
	v_fmac_f32_e32 v25, v29, v29
	v_add_f32_e32 v24, v24, v25
	v_mul_f32_e32 v25, v26, v26
	v_lshlrev_b32_e32 v31, 16, v27
	v_and_b32_e32 v27, 0xffff0000, v27
	v_fmac_f32_e32 v25, v30, v30
	v_add_f32_e32 v24, v25, v24
	v_mul_f32_e32 v25, v27, v27
	v_fmac_f32_e32 v25, v31, v31
	v_add_f32_e32 v36, v25, v24
	s_waitcnt vmcnt(15)
	v_lshlrev_b32_e32 v28, 16, v232
	v_and_b32_e32 v29, 0xffff0000, v232
	v_lshlrev_b32_e32 v24, 16, v233
	v_and_b32_e32 v25, 0xffff0000, v233
	v_lshlrev_b32_e32 v30, 16, v234
	v_and_b32_e32 v31, 0xffff0000, v234
	v_lshlrev_b32_e32 v26, 16, v235
	v_and_b32_e32 v27, 0xffff0000, v235
	v_pk_add_f32 v[22:23], v[22:23], v[24:25]
	v_pk_add_f32 v[20:21], v[20:21], v[28:29]
	v_pk_add_f32 v[24:25], v[18:19], v[26:27]
	v_pk_add_f32 v[18:19], v[16:17], v[30:31]
	v_cvt_pk_bf16_f32 v16, v20, v21
	v_cvt_pk_bf16_f32 v17, v22, v23
	v_cvt_pk_bf16_f32 v18, v18, v19
	v_cvt_pk_bf16_f32 v19, v24, v25
	global_store_dwordx4 v[34:35], v[16:19], off offset:256
	v_lshlrev_b32_e32 v20, 16, v16
	v_lshlrev_b32_e32 v21, 16, v17
	v_and_b32_e32 v16, 0xffff0000, v16
	v_and_b32_e32 v17, 0xffff0000, v17
	v_mul_f32_e32 v16, v16, v16
	v_mul_f32_e32 v17, v17, v17
	v_lshlrev_b32_e32 v22, 16, v18
	v_and_b32_e32 v18, 0xffff0000, v18
	v_fmac_f32_e32 v16, v20, v20
	v_fmac_f32_e32 v17, v21, v21
	v_add_f32_e32 v16, v16, v17
	v_mul_f32_e32 v17, v18, v18
	v_lshlrev_b32_e32 v23, 16, v19
	v_and_b32_e32 v19, 0xffff0000, v19
	v_fmac_f32_e32 v17, v22, v22
	v_add_f32_e32 v16, v17, v16
	v_mul_f32_e32 v17, v19, v19
	v_fmac_f32_e32 v17, v23, v23
	v_add_f32_e32 v16, v17, v16
	v_add_f32_e32 v16, v36, v16
	ds_bpermute_b32 v17, v148, v16
	s_waitcnt lgkmcnt(0)
	v_add_f32_e32 v16, v16, v17
	ds_bpermute_b32 v17, v149, v16
	s_and_saveexec_b64 s[26:27], s[4:5]
	s_cbranch_execz .LBB0_902
	s_waitcnt lgkmcnt(0)
	v_add_f32_e32 v18, v16, v17
	s_lshl_b32 s28, s8, 2
	v_lshlrev_b64 v[16:17], 6, v[32:33]
	s_ashr_i32 s29, s28, 31
	v_lshl_add_u64 v[16:17], s[14:15], 0, v[16:17]
	v_lshl_add_u64 v[16:17], s[28:29], 2, v[16:17]
	s_lshl_b32 s68, s51, 2
	v_lshl_add_u64 v[16:17], v[16:17], 0, s[68:69]
	global_store_dword v[16:17], v18, off
.LBB0_902:
	s_or_b64 exec, exec, s[26:27]
	v_add_u32_e32 v16, 0xb0, v140
	s_waitcnt lgkmcnt(0)
	v_ashrrev_i32_e32 v17, 31, v16
	v_lshlrev_b64 v[18:19], 11, v[16:17]
	v_lshl_add_u64 v[18:19], s[12:13], 0, v[18:19]
	v_lshl_add_u64 v[18:19], v[138:139], 1, v[18:19]
	s_waitcnt vmcnt(15)
	v_lshlrev_b32_e32 v24, 16, v236
	v_and_b32_e32 v25, 0xffff0000, v236
	v_lshlrev_b32_e32 v20, 16, v237
	v_and_b32_e32 v21, 0xffff0000, v237
	v_lshlrev_b32_e32 v26, 16, v238
	v_and_b32_e32 v27, 0xffff0000, v238
	v_lshlrev_b32_e32 v22, 16, v239
	v_and_b32_e32 v23, 0xffff0000, v239
	v_pk_add_f32 v[14:15], v[14:15], v[20:21]
	v_pk_add_f32 v[12:13], v[12:13], v[24:25]
	v_pk_add_f32 v[20:21], v[10:11], v[22:23]
	v_pk_add_f32 v[10:11], v[8:9], v[26:27]
	v_cvt_pk_bf16_f32 v8, v12, v13
	v_cvt_pk_bf16_f32 v9, v14, v15
	v_cvt_pk_bf16_f32 v10, v10, v11
	v_cvt_pk_bf16_f32 v11, v20, v21
	global_store_dwordx4 v[18:19], v[8:11], off
	v_lshlrev_b32_e32 v12, 16, v8
	v_lshlrev_b32_e32 v13, 16, v9
	v_and_b32_e32 v8, 0xffff0000, v8
	v_and_b32_e32 v9, 0xffff0000, v9
	v_mul_f32_e32 v8, v8, v8
	v_mul_f32_e32 v9, v9, v9
	v_lshlrev_b32_e32 v14, 16, v10
	v_and_b32_e32 v10, 0xffff0000, v10
	v_fmac_f32_e32 v8, v12, v12
	v_fmac_f32_e32 v9, v13, v13
	v_add_f32_e32 v8, v8, v9
	v_mul_f32_e32 v9, v10, v10
	v_lshlrev_b32_e32 v15, 16, v11
	v_and_b32_e32 v11, 0xffff0000, v11
	v_fmac_f32_e32 v9, v14, v14
	v_add_f32_e32 v8, v9, v8
	v_mul_f32_e32 v9, v11, v11
	v_fmac_f32_e32 v9, v15, v15
	v_add_f32_e32 v20, v9, v8
	s_waitcnt vmcnt(15)
	v_lshlrev_b32_e32 v12, 16, v248
	v_and_b32_e32 v13, 0xffff0000, v248
	v_lshlrev_b32_e32 v8, 16, v249
	v_and_b32_e32 v9, 0xffff0000, v249
	v_lshlrev_b32_e32 v14, 16, v250
	v_and_b32_e32 v15, 0xffff0000, v250
	v_lshlrev_b32_e32 v10, 16, v251
	v_and_b32_e32 v11, 0xffff0000, v251
	v_pk_add_f32 v[6:7], v[6:7], v[8:9]
	v_pk_add_f32 v[4:5], v[4:5], v[12:13]
	v_pk_add_f32 v[8:9], v[2:3], v[10:11]
	v_pk_add_f32 v[2:3], v[0:1], v[14:15]
	v_cvt_pk_bf16_f32 v0, v4, v5
	v_cvt_pk_bf16_f32 v1, v6, v7
	v_cvt_pk_bf16_f32 v2, v2, v3
	v_cvt_pk_bf16_f32 v3, v8, v9
	global_store_dwordx4 v[18:19], v[0:3], off offset:256
	v_lshlrev_b32_e32 v4, 16, v0
	v_lshlrev_b32_e32 v5, 16, v1
	v_and_b32_e32 v0, 0xffff0000, v0
	v_and_b32_e32 v1, 0xffff0000, v1
	v_mul_f32_e32 v0, v0, v0
	v_mul_f32_e32 v1, v1, v1
	v_lshlrev_b32_e32 v6, 16, v2
	v_and_b32_e32 v2, 0xffff0000, v2
	v_fmac_f32_e32 v0, v4, v4
	v_fmac_f32_e32 v1, v5, v5
	v_add_f32_e32 v0, v0, v1
	v_mul_f32_e32 v1, v2, v2
	v_lshlrev_b32_e32 v7, 16, v3
	v_and_b32_e32 v3, 0xffff0000, v3
	v_fmac_f32_e32 v1, v6, v6
	v_add_f32_e32 v0, v1, v0
	v_mul_f32_e32 v1, v3, v3
	v_fmac_f32_e32 v1, v7, v7
	v_add_f32_e32 v0, v1, v0
	v_add_f32_e32 v0, v20, v0
	ds_bpermute_b32 v1, v148, v0
	s_waitcnt lgkmcnt(0)
	v_add_f32_e32 v0, v0, v1
	ds_bpermute_b32 v1, v149, v0
	s_and_saveexec_b64 s[26:27], s[4:5]
	s_cbranch_execz .LBB0_904
	s_waitcnt lgkmcnt(0)
	v_add_f32_e32 v2, v0, v1
	s_lshl_b32 s28, s8, 2
	v_lshlrev_b64 v[0:1], 6, v[16:17]
	s_ashr_i32 s29, s28, 31
	v_lshl_add_u64 v[0:1], s[14:15], 0, v[0:1]
	v_lshl_add_u64 v[0:1], s[28:29], 2, v[0:1]
	s_lshl_b32 s68, s51, 2
	v_lshl_add_u64 v[0:1], v[0:1], 0, s[68:69]
	global_store_dword v[0:1], v2, off

; #define PG8_STAGE(bufoff, gbase, voff) do { _Pragma("unroll") for (int _i = 0; _i < 2; ++_i) \
;         __builtin_amdgcn_global_load_lds((const unsigned*)((const char*)(gbase) + (voff)[_i]), (PG8_LAS unsigned*)(lds + (bufoff) + ldsw + _i * 8192), 16, 0, 0); } while (0)
; #define PG8_LDA(dst, b, h) do { _Pragma("unroll") for (int m = 0; m < 4; ++m) _Pragma("unroll") for (int k = 0; k < 2; ++k) dst[m][k] = *(const PG8_LAS bf16x8*)(lds + PG8_SA(b, h) + aoff + m * 2048 + k * 1024); } while (0)
; #define PG8_LDB(dst, b, h) do { _Pragma("unroll") for (int n = 0; n < 2; ++n) _Pragma("unroll") for (int k = 0; k < 2; ++k) dst[n][k] = *(const PG8_LAS bf16x8*)(lds + PG8_SB(b, h) + boff + n * 2048 + k * 1024); } while (0)
; #define PG8_MMA(ai, bj, At, Bt) do { __builtin_amdgcn_s_setprio(1); _Pragma("unroll") for (int m = 0; m < 4; ++m) _Pragma("unroll") for (int n = 0; n < 2; ++n) _Pragma("unroll") for (int k = 0; k < 2; ++k) \
;         acc[ai][bj][m][n] = __builtin_amdgcn_mfma_f32_16x16x32_bf16(Bt[n][k], At[m][k], acc[ai][bj][m][n], 0, 0, 0); __builtin_amdgcn_s_setprio(0); } while (0)
; #define PG8_WAIT_V(n) asm volatile("s_waitcnt vmcnt(" #n ")" ::: "memory")
; #define PG8_WAIT_L(n) asm volatile("s_waitcnt lgkmcnt(" #n ")" ::: "memory")
; #define PG8_BAR __builtin_amdgcn_s_barrier()
; #define PG8_SCHED __builtin_amdgcn_sched_barrier(0)
; template <class Epi, class Sched, bool ALIGN_EPI = false, bool SP2 = false>
; __device__ __forceinline__ void gemm_phase(PG8_LAS unsigned char* lds, const Gemm g, const Sched& S, const Epi& E) {
;     ...
;             PG8_LDB(B0, 0, 0); PG8_LDB(B1, 0, 1); PG8_SCHED; PG8_LDA(At, 0, 0); PG8_STAGE(PG8_SA(1, 1), a1 + hstepA, voffA);
;             PG8_WAIT_V(8); PG8_WAIT_L(0); PG8_BAR; PG8_MMA(0, 0, At, B0); PG8_MMA(0, 1, At, B1); PG8_BAR; PG8_SCHED;
;             PG8_LDA(At, 0, 1); PG8_STAGE(PG8_SB(0, 0), b2, voffB); PG8_STAGE(PG8_SB(0, 1), b2 + hstepB, voffB); PG8_STAGE(PG8_SA(0, 0), a2, voffA);
;             PG8_WAIT_V(8); PG8_WAIT_L(0); PG8_BAR; PG8_MMA(1, 0, At, B0); PG8_MMA(1, 1, At, B1); PG8_BAR; PG8_SCHED;
.LBB0_1121:
	v_add_u32_e32 v142, s9, v145
	ds_read_b128 v[138:141], v142
	ds_read_b128 v[148:151], v142 offset:1024
	ds_read_b128 v[152:155], v142 offset:2048
	ds_read_b128 v[156:159], v142 offset:3072
	v_add_u32_e32 v142, s42, v145
	ds_read_b128 v[160:163], v142
	ds_read_b128 v[164:167], v142 offset:1024
	ds_read_b128 v[168:171], v142 offset:2048
	ds_read_b128 v[172:175], v142 offset:3072
	s_add_u32 s2, s28, 0xfffc0080
	s_addc_u32 s30, s29, -1
	s_cmp_eq_u32 s82, 12
	s_cselect_b32 s35, s21, s30
	s_cselect_b32 s34, s27, s2
	s_cselect_b32 s31, s19, s79
	s_cselect_b32 s30, s68, s78
	v_lshl_add_u64 v[142:143], s[28:29], 0, v[136:137]
	s_add_i32 m0, s45, 0xc000
	ds_read_b128 v[176:179], v147
	ds_read_b128 v[180:183], v147 offset:1024
	ds_read_b128 v[184:187], v147 offset:2048
	ds_read_b128 v[188:191], v147 offset:3072
	ds_read_b128 v[204:207], v147 offset:4096
	ds_read_b128 v[208:211], v147 offset:5120
	ds_read_b128 v[218:221], v147 offset:6144
	ds_read_b128 v[222:225], v147 offset:7168
	global_load_lds_dwordx4 v[142:143], off
	v_lshl_add_u64 v[142:143], s[28:29], 0, v[134:135]
	s_add_i32 m0, s45, 0xe000
	s_nop 0
	global_load_lds_dwordx4 v[142:143], off
	s_waitcnt vmcnt(8)
	s_waitcnt lgkmcnt(0)
	s_barrier
	s_setprio 1
	s_waitcnt lgkmcnt(0)
	v_mfma_f32_16x16x32_bf16 v[124:127], v[138:141], v[176:179], v[124:127]
	v_mfma_f32_16x16x32_bf16 v[120:123], v[152:155], v[176:179], v[120:123]
	v_mfma_f32_16x16x32_bf16 v[108:111], v[138:141], v[184:187], v[108:111]
	v_mfma_f32_16x16x32_bf16 v[104:107], v[152:155], v[184:187], v[104:107]
	v_mfma_f32_16x16x32_bf16 v[92:95], v[138:141], v[204:207], v[92:95]
	v_mfma_f32_16x16x32_bf16 v[88:91], v[152:155], v[204:207], v[88:91]
	v_mfma_f32_16x16x32_bf16 v[76:79], v[138:141], v[218:221], v[76:79]
	v_mfma_f32_16x16x32_bf16 v[72:75], v[152:155], v[218:221], v[72:75]
	v_mfma_f32_16x16x32_bf16 v[124:127], v[148:151], v[180:183], v[124:127]
	v_mfma_f32_16x16x32_bf16 v[120:123], v[156:159], v[180:183], v[120:123]
	v_mfma_f32_16x16x32_bf16 v[108:111], v[148:151], v[188:191], v[108:111]
	v_mfma_f32_16x16x32_bf16 v[104:107], v[156:159], v[188:191], v[104:107]
	v_mfma_f32_16x16x32_bf16 v[92:95], v[148:151], v[208:211], v[92:95]
	v_mfma_f32_16x16x32_bf16 v[88:91], v[156:159], v[208:211], v[88:91]
	v_mfma_f32_16x16x32_bf16 v[76:79], v[148:151], v[222:225], v[76:79]
	v_mfma_f32_16x16x32_bf16 v[72:75], v[156:159], v[222:225], v[72:75]
	s_setprio 0
	s_setprio 1
	v_mfma_f32_16x16x32_bf16 v[116:119], v[160:163], v[176:179], v[116:119]
	v_mfma_f32_16x16x32_bf16 v[112:115], v[168:171], v[176:179], v[112:115]
	v_mfma_f32_16x16x32_bf16 v[100:103], v[160:163], v[184:187], v[100:103]
	v_mfma_f32_16x16x32_bf16 v[96:99], v[168:171], v[184:187], v[96:99]
	v_mfma_f32_16x16x32_bf16 v[84:87], v[160:163], v[204:207], v[84:87]
	v_mfma_f32_16x16x32_bf16 v[80:83], v[168:171], v[204:207], v[80:83]
	v_mfma_f32_16x16x32_bf16 v[68:71], v[160:163], v[218:221], v[68:71]
	v_mfma_f32_16x16x32_bf16 v[64:67], v[168:171], v[218:221], v[64:67]
	v_mfma_f32_16x16x32_bf16 v[116:119], v[164:167], v[180:183], v[116:119]
	v_mfma_f32_16x16x32_bf16 v[112:115], v[172:175], v[180:183], v[112:115]
	v_mfma_f32_16x16x32_bf16 v[100:103], v[164:167], v[188:191], v[100:103]
	v_mfma_f32_16x16x32_bf16 v[96:99], v[172:175], v[188:191], v[96:99]
	v_mfma_f32_16x16x32_bf16 v[84:87], v[164:167], v[208:211], v[84:87]
	v_mfma_f32_16x16x32_bf16 v[80:83], v[172:175], v[208:211], v[80:83]
	v_mfma_f32_16x16x32_bf16 v[68:71], v[164:167], v[222:225], v[68:71]
	v_mfma_f32_16x16x32_bf16 v[64:67], v[172:175], v[222:225], v[64:67]
	s_setprio 0
	s_barrier
	s_mov_b32 m0, s40
	v_lshl_add_u64 v[142:143], s[30:31], 0, v[192:193]
	s_add_u32 s84, s30, 0x40000
	ds_read_b128 v[176:179], v147 offset:16384
	ds_read_b128 v[180:183], v147 offset:17408
	ds_read_b128 v[184:187], v147 offset:18432
	ds_read_b128 v[188:191], v147 offset:19456
	ds_read_b128 v[204:207], v147 offset:20480
	ds_read_b128 v[208:211], v147 offset:21504
	ds_read_b128 v[218:221], v147 offset:22528
	ds_read_b128 v[222:225], v147 offset:23552
	global_load_lds_dwordx4 v[142:143], off
	v_lshl_add_u64 v[194:195], s[30:31], 0, v[132:133]
	s_mov_b32 m0, s41
	s_addc_u32 s85, s31, 0
	global_load_lds_dwordx4 v[194:195], off
	v_lshl_add_u64 v[226:227], s[84:85], 0, v[192:193]
	s_mov_b32 m0, s43
	v_lshl_add_u64 v[228:229], s[34:35], 0, v[130:131]
	global_load_lds_dwordx4 v[226:227], off
	v_lshl_add_u64 v[226:227], s[84:85], 0, v[132:133]
	s_mov_b32 m0, s44
	s_nop 0
	global_load_lds_dwordx4 v[226:227], off
	v_lshl_add_u64 v[226:227], s[34:35], 0, v[128:129]
	s_mov_b32 m0, s45
	s_nop 0
	global_load_lds_dwordx4 v[226:227], off
	s_mov_b32 m0, s48
	s_nop 0
	global_load_lds_dwordx4 v[228:229], off
	s_waitcnt vmcnt(8)
	s_waitcnt lgkmcnt(0)
	s_barrier
; #define PG8_STAGE(bufoff, gbase, voff) do { _Pragma("unroll") for (int _i = 0; _i < 2; ++_i) \
;         __builtin_amdgcn_global_load_lds((const unsigned*)((const char*)(gbase) + (voff)[_i]), (PG8_LAS unsigned*)(lds + (bufoff) + ldsw + _i * 8192), 16, 0, 0); } while (0)
; #define PG8_LDA(dst, b, h) do { _Pragma("unroll") for (int m = 0; m < 4; ++m) _Pragma("unroll") for (int k = 0; k < 2; ++k) dst[m][k] = *(const PG8_LAS bf16x8*)(lds + PG8_SA(b, h) + aoff + m * 2048 + k * 1024); } while (0)
; #define PG8_LDB(dst, b, h) do { _Pragma("unroll") for (int n = 0; n < 2; ++n) _Pragma("unroll") for (int k = 0; k < 2; ++k) dst[n][k] = *(const PG8_LAS bf16x8*)(lds + PG8_SB(b, h) + boff + n * 2048 + k * 1024); } while (0)
; #define PG8_MMA(ai, bj, At, Bt) do { __builtin_amdgcn_s_setprio(1); _Pragma("unroll") for (int m = 0; m < 4; ++m) _Pragma("unroll") for (int n = 0; n < 2; ++n) _Pragma("unroll") for (int k = 0; k < 2; ++k) \
;         acc[ai][bj][m][n] = __builtin_amdgcn_mfma_f32_16x16x32_bf16(Bt[n][k], At[m][k], acc[ai][bj][m][n], 0, 0, 0); __builtin_amdgcn_s_setprio(0); } while (0)
; #define PG8_WAIT_V(n) asm volatile("s_waitcnt vmcnt(" #n ")" ::: "memory")
; #define PG8_WAIT_L(n) asm volatile("s_waitcnt lgkmcnt(" #n ")" ::: "memory")
; #define PG8_BAR __builtin_amdgcn_s_barrier()
; #define PG8_SCHED __builtin_amdgcn_sched_barrier(0)
; template <class Epi, class Sched, bool ALIGN_EPI = false, bool SP2 = false>
; __device__ __forceinline__ void gemm_phase(PG8_LAS unsigned char* lds, const Gemm g, const Sched& S, const Epi& E) {
;     ...
;             PG8_WAIT_V(8); PG8_WAIT_L(0); PG8_BAR; PG8_MMA(1, 0, At, B0); PG8_MMA(1, 1, At, B1); PG8_BAR; PG8_SCHED;
;             PG8_LDB(B0, 1, 0); PG8_LDB(B1, 1, 1); PG8_SCHED; PG8_LDA(At, 1, 0); PG8_STAGE(PG8_SA(0, 1), a2 + hstepA, voffA);
;             PG8_WAIT_V(8); PG8_WAIT_L(0); PG8_BAR; PG8_MMA(0, 0, At, B0); PG8_MMA(0, 1, At, B1); PG8_BAR; PG8_SCHED;
	s_setprio 1
	s_waitcnt lgkmcnt(0)
	v_mfma_f32_16x16x32_bf16 v[60:63], v[138:141], v[176:179], v[60:63]
	v_mfma_f32_16x16x32_bf16 v[56:59], v[152:155], v[176:179], v[56:59]
	v_mfma_f32_16x16x32_bf16 v[44:47], v[138:141], v[184:187], v[44:47]
	v_mfma_f32_16x16x32_bf16 v[40:43], v[152:155], v[184:187], v[40:43]
	v_mfma_f32_16x16x32_bf16 v[28:31], v[138:141], v[204:207], v[28:31]
	v_mfma_f32_16x16x32_bf16 v[24:27], v[152:155], v[204:207], v[24:27]
	v_mfma_f32_16x16x32_bf16 v[12:15], v[138:141], v[218:221], v[12:15]
	v_mfma_f32_16x16x32_bf16 v[8:11], v[152:155], v[218:221], v[8:11]
	v_mfma_f32_16x16x32_bf16 v[60:63], v[148:151], v[180:183], v[60:63]
	v_mfma_f32_16x16x32_bf16 v[56:59], v[156:159], v[180:183], v[56:59]
	v_mfma_f32_16x16x32_bf16 v[44:47], v[148:151], v[188:191], v[44:47]
	v_mfma_f32_16x16x32_bf16 v[40:43], v[156:159], v[188:191], v[40:43]
	v_mfma_f32_16x16x32_bf16 v[28:31], v[148:151], v[208:211], v[28:31]
	v_mfma_f32_16x16x32_bf16 v[24:27], v[156:159], v[208:211], v[24:27]
	v_mfma_f32_16x16x32_bf16 v[12:15], v[148:151], v[222:225], v[12:15]
	v_mfma_f32_16x16x32_bf16 v[8:11], v[156:159], v[222:225], v[8:11]
	s_setprio 0
	s_setprio 1
	v_mfma_f32_16x16x32_bf16 v[52:55], v[160:163], v[176:179], v[52:55]
	v_mfma_f32_16x16x32_bf16 v[48:51], v[168:171], v[176:179], v[48:51]
	v_mfma_f32_16x16x32_bf16 v[36:39], v[160:163], v[184:187], v[36:39]
	v_mfma_f32_16x16x32_bf16 v[32:35], v[168:171], v[184:187], v[32:35]
	v_mfma_f32_16x16x32_bf16 v[20:23], v[160:163], v[204:207], v[20:23]
	v_mfma_f32_16x16x32_bf16 v[16:19], v[168:171], v[204:207], v[16:19]
	v_mfma_f32_16x16x32_bf16 v[4:7], v[160:163], v[218:221], v[4:7]
	v_mfma_f32_16x16x32_bf16 v[0:3], v[168:171], v[218:221], v[0:3]
	v_mfma_f32_16x16x32_bf16 v[52:55], v[164:167], v[180:183], v[52:55]
	v_mfma_f32_16x16x32_bf16 v[48:51], v[172:175], v[180:183], v[48:51]
	v_mfma_f32_16x16x32_bf16 v[36:39], v[164:167], v[188:191], v[36:39]
	v_mfma_f32_16x16x32_bf16 v[32:35], v[172:175], v[188:191], v[32:35]
	v_mfma_f32_16x16x32_bf16 v[20:23], v[164:167], v[208:211], v[20:23]
	v_mfma_f32_16x16x32_bf16 v[16:19], v[172:175], v[208:211], v[16:19]
	v_mfma_f32_16x16x32_bf16 v[4:7], v[164:167], v[222:225], v[4:7]
	v_mfma_f32_16x16x32_bf16 v[0:3], v[172:175], v[222:225], v[0:3]
	s_setprio 0
	s_barrier
	v_add_u32_e32 v156, s60, v145
	v_add_u32_e32 v172, s67, v145
	ds_read_b128 v[138:141], v156
	ds_read_b128 v[148:151], v156 offset:1024
	ds_read_b128 v[152:155], v156 offset:2048
	ds_read_b128 v[156:159], v156 offset:3072
	ds_read_b128 v[160:163], v172
	ds_read_b128 v[164:167], v172 offset:1024
	ds_read_b128 v[168:171], v172 offset:2048
	ds_read_b128 v[172:175], v172 offset:3072
	s_add_u32 s34, s34, 0x40000
	s_addc_u32 s35, s35, 0
	s_mov_b32 m0, s49
	v_lshl_add_u64 v[230:231], s[34:35], 0, v[128:129]
	ds_read_b128 v[176:179], v147 offset:32768
	ds_read_b128 v[180:183], v147 offset:33792
	ds_read_b128 v[184:187], v147 offset:34816
	ds_read_b128 v[188:191], v147 offset:35840
	ds_read_b128 v[204:207], v147 offset:36864
	ds_read_b128 v[208:211], v147 offset:37888
	ds_read_b128 v[218:221], v147 offset:38912
	ds_read_b128 v[222:225], v147 offset:39936
	global_load_lds_dwordx4 v[230:231], off
	v_lshl_add_u64 v[230:231], s[34:35], 0, v[130:131]
	s_mov_b32 m0, s50
	s_nop 0
	global_load_lds_dwordx4 v[230:231], off
	s_waitcnt vmcnt(8)
	s_waitcnt lgkmcnt(0)
	s_barrier
	s_setprio 1
	s_waitcnt lgkmcnt(0)
	v_mfma_f32_16x16x32_bf16 v[124:127], v[138:141], v[176:179], v[124:127]
	v_mfma_f32_16x16x32_bf16 v[120:123], v[152:155], v[176:179], v[120:123]
	v_mfma_f32_16x16x32_bf16 v[108:111], v[138:141], v[184:187], v[108:111]
	v_mfma_f32_16x16x32_bf16 v[104:107], v[152:155], v[184:187], v[104:107]
	v_mfma_f32_16x16x32_bf16 v[92:95], v[138:141], v[204:207], v[92:95]
	v_mfma_f32_16x16x32_bf16 v[88:91], v[152:155], v[204:207], v[88:91]
	v_mfma_f32_16x16x32_bf16 v[76:79], v[138:141], v[218:221], v[76:79]
	v_mfma_f32_16x16x32_bf16 v[72:75], v[152:155], v[218:221], v[72:75]
	v_mfma_f32_16x16x32_bf16 v[124:127], v[148:151], v[180:183], v[124:127]
	v_mfma_f32_16x16x32_bf16 v[120:123], v[156:159], v[180:183], v[120:123]
	v_mfma_f32_16x16x32_bf16 v[108:111], v[148:151], v[188:191], v[108:111]
	v_mfma_f32_16x16x32_bf16 v[104:107], v[156:159], v[188:191], v[104:107]
	v_mfma_f32_16x16x32_bf16 v[92:95], v[148:151], v[208:211], v[92:95]
	v_mfma_f32_16x16x32_bf16 v[88:91], v[156:159], v[208:211], v[88:91]
	v_mfma_f32_16x16x32_bf16 v[76:79], v[148:151], v[222:225], v[76:79]
	v_mfma_f32_16x16x32_bf16 v[72:75], v[156:159], v[222:225], v[72:75]
	s_setprio 0
	s_setprio 1
	v_mfma_f32_16x16x32_bf16 v[116:119], v[160:163], v[176:179], v[116:119]
	v_mfma_f32_16x16x32_bf16 v[112:115], v[168:171], v[176:179], v[112:115]
	v_mfma_f32_16x16x32_bf16 v[100:103], v[160:163], v[184:187], v[100:103]
	v_mfma_f32_16x16x32_bf16 v[96:99], v[168:171], v[184:187], v[96:99]
	v_mfma_f32_16x16x32_bf16 v[84:87], v[160:163], v[204:207], v[84:87]
	v_mfma_f32_16x16x32_bf16 v[80:83], v[168:171], v[204:207], v[80:83]
	v_mfma_f32_16x16x32_bf16 v[68:71], v[160:163], v[218:221], v[68:71]
	v_mfma_f32_16x16x32_bf16 v[64:67], v[168:171], v[218:221], v[64:67]
	v_mfma_f32_16x16x32_bf16 v[116:119], v[164:167], v[180:183], v[116:119]
	v_mfma_f32_16x16x32_bf16 v[112:115], v[172:175], v[180:183], v[112:115]
	v_mfma_f32_16x16x32_bf16 v[100:103], v[164:167], v[188:191], v[100:103]
	v_mfma_f32_16x16x32_bf16 v[96:99], v[172:175], v[188:191], v[96:99]
	v_mfma_f32_16x16x32_bf16 v[84:87], v[164:167], v[208:211], v[84:87]
	v_mfma_f32_16x16x32_bf16 v[80:83], v[172:175], v[208:211], v[80:83]
	v_mfma_f32_16x16x32_bf16 v[68:71], v[164:167], v[222:225], v[68:71]
	v_mfma_f32_16x16x32_bf16 v[64:67], v[172:175], v[222:225], v[64:67]
	s_setprio 0
	s_barrier
; #define PG8_STAGE(bufoff, gbase, voff) do { _Pragma("unroll") for (int _i = 0; _i < 2; ++_i) \
;         __builtin_amdgcn_global_load_lds((const unsigned*)((const char*)(gbase) + (voff)[_i]), (PG8_LAS unsigned*)(lds + (bufoff) + ldsw + _i * 8192), 16, 0, 0); } while (0)
; #define PG8_LDA(dst, b, h) do { _Pragma("unroll") for (int m = 0; m < 4; ++m) _Pragma("unroll") for (int k = 0; k < 2; ++k) dst[m][k] = *(const PG8_LAS bf16x8*)(lds + PG8_SA(b, h) + aoff + m * 2048 + k * 1024); } while (0)
; template <class Epi, class Sched, bool ALIGN_EPI = false, bool SP2 = false>
; __device__ __forceinline__ void gemm_phase(PG8_LAS unsigned char* lds, const Gemm g, const Sched& S, const Epi& E) {
;     ...
;             PG8_LDB(B0, 0, 0); PG8_LDB(B1, 0, 1); PG8_SCHED; PG8_LDA(At, 0, 0); PG8_STAGE(PG8_SA(1, 1), a1 + hstepA, voffA);
;             PG8_WAIT_V(8); PG8_WAIT_L(0); PG8_BAR; PG8_MMA(0, 0, At, B0); PG8_MMA(0, 1, At, B1); PG8_BAR; PG8_SCHED;
;             PG8_LDA(At, 0, 1); PG8_STAGE(PG8_SB(0, 0), b2, voffB); PG8_STAGE(PG8_SB(0, 1), b2 + hstepB, voffB); PG8_STAGE(PG8_SA(0, 0), a2, voffA);
;             PG8_WAIT_V(8); PG8_WAIT_L(0); PG8_BAR; PG8_MMA(1, 0, At, B0); PG8_MMA(1, 1, At, B1); PG8_BAR; PG8_SCHED;
;             PG8_LDB(B0, 1, 0); PG8_LDB(B1, 1, 1); PG8_SCHED; PG8_LDA(At, 1, 0); PG8_STAGE(PG8_SA(0, 1), a2 + hstepA, voffA);
;             PG8_WAIT_V(8); PG8_WAIT_L(0); PG8_BAR; PG8_MMA(0, 0, At, B0); PG8_MMA(0, 1, At, B1); PG8_BAR; PG8_SCHED;
;             PG8_LDA(At, 1, 1); PG8_STAGE(PG8_SB(1, 0), b3, voffB); PG8_STAGE(PG8_SB(1, 1), b3 + hstepB, voffB); PG8_STAGE(PG8_SA(1, 0), a3, voffA);
;             PG8_WAIT_V(8); PG8_WAIT_L(0); PG8_BAR; PG8_MMA(1, 0, At, B0); PG8_MMA(1, 1, At, B1); PG8_BAR; PG8_SCHED;
;     __device__ __forceinline__ void operator()(const f32x4 (&acc)[2][2][4][2], const pg8::Unit& u, int wr, int wc, int fr, int fq) const {
;         const int row0 = u.pm * 256 + wr * 64 + fr, col0 = u.pn * 256 + wc * 32 + 8 * fq;
; #pragma unroll
;         for (int ai = 0; ai < 2; ++ai)
; #pragma unroll
;             for (int m = 0; m < 4; ++m) {
;                 const int row = row0 + ai * 128 + m * 16; float ss = 0.f;
; #pragma unroll
;                 for (int bj = 0; bj < 2; ++bj) {
;                     const size_t off = (size_t)row * DM + col0 + bj * 128;
;                     const v4u b = *(const v4u*)(xb + off);
	s_mov_b32 m0, s61
	v_lshl_add_u64 v[142:143], v[142:143], 0, s[76:77]
	s_add_u32 s30, s30, 0x40080
	ds_read_b128 v[176:179], v147 offset:49152
	ds_read_b128 v[180:183], v147 offset:50176
	ds_read_b128 v[184:187], v147 offset:51200
	ds_read_b128 v[188:191], v147 offset:52224
	ds_read_b128 v[204:207], v147 offset:53248
	ds_read_b128 v[208:211], v147 offset:54272
	ds_read_b128 v[218:221], v147 offset:55296
	ds_read_b128 v[222:225], v147 offset:56320
	global_load_lds_dwordx4 v[142:143], off
	v_lshl_add_u64 v[142:143], v[194:195], 0, s[76:77]
	s_mov_b32 m0, s64
	s_addc_u32 s31, s31, 0
	global_load_lds_dwordx4 v[142:143], off
	v_lshl_add_u64 v[142:143], s[30:31], 0, v[192:193]
	s_mov_b32 m0, s70
	s_nop 0
	global_load_lds_dwordx4 v[142:143], off
	v_lshl_add_u64 v[142:143], s[30:31], 0, v[132:133]
	s_mov_b32 m0, s71
	s_nop 0
	global_load_lds_dwordx4 v[142:143], off
	v_lshl_add_u64 v[142:143], v[226:227], 0, s[76:77]
	s_mov_b32 m0, s65
	s_nop 0
	global_load_lds_dwordx4 v[142:143], off
	v_lshl_add_u64 v[142:143], v[228:229], 0, s[76:77]
	s_mov_b32 m0, s66
	s_nop 0
	global_load_lds_dwordx4 v[142:143], off
	s_waitcnt vmcnt(8)
	s_waitcnt lgkmcnt(0)
	s_barrier
	s_setprio 1
	s_waitcnt lgkmcnt(0)
	v_mfma_f32_16x16x32_bf16 v[60:63], v[138:141], v[176:179], v[60:63]
	v_mfma_f32_16x16x32_bf16 v[56:59], v[152:155], v[176:179], v[56:59]
	v_mfma_f32_16x16x32_bf16 v[44:47], v[138:141], v[184:187], v[44:47]
	v_mfma_f32_16x16x32_bf16 v[40:43], v[152:155], v[184:187], v[40:43]
	v_mfma_f32_16x16x32_bf16 v[28:31], v[138:141], v[204:207], v[28:31]
	v_mfma_f32_16x16x32_bf16 v[24:27], v[152:155], v[204:207], v[24:27]
	v_mfma_f32_16x16x32_bf16 v[12:15], v[138:141], v[218:221], v[12:15]
	v_mfma_f32_16x16x32_bf16 v[8:11], v[152:155], v[218:221], v[8:11]
	v_mfma_f32_16x16x32_bf16 v[60:63], v[148:151], v[180:183], v[60:63]
	v_mfma_f32_16x16x32_bf16 v[56:59], v[156:159], v[180:183], v[56:59]
	v_mfma_f32_16x16x32_bf16 v[44:47], v[148:151], v[188:191], v[44:47]
	v_mfma_f32_16x16x32_bf16 v[40:43], v[156:159], v[188:191], v[40:43]
	v_mfma_f32_16x16x32_bf16 v[28:31], v[148:151], v[208:211], v[28:31]
	v_mfma_f32_16x16x32_bf16 v[24:27], v[156:159], v[208:211], v[24:27]
	v_mfma_f32_16x16x32_bf16 v[12:15], v[148:151], v[222:225], v[12:15]
	v_mfma_f32_16x16x32_bf16 v[8:11], v[156:159], v[222:225], v[8:11]
	s_setprio 0
	s_setprio 1
	v_mfma_f32_16x16x32_bf16 v[52:55], v[160:163], v[176:179], v[52:55]
	v_mfma_f32_16x16x32_bf16 v[48:51], v[168:171], v[176:179], v[48:51]
	v_mfma_f32_16x16x32_bf16 v[36:39], v[160:163], v[184:187], v[36:39]
	v_mfma_f32_16x16x32_bf16 v[32:35], v[168:171], v[184:187], v[32:35]
	v_mfma_f32_16x16x32_bf16 v[20:23], v[160:163], v[204:207], v[20:23]
	v_mfma_f32_16x16x32_bf16 v[16:19], v[168:171], v[204:207], v[16:19]
	v_mfma_f32_16x16x32_bf16 v[4:7], v[160:163], v[218:221], v[4:7]
	v_mfma_f32_16x16x32_bf16 v[0:3], v[168:171], v[218:221], v[0:3]
	v_mfma_f32_16x16x32_bf16 v[52:55], v[164:167], v[180:183], v[52:55]
	v_mfma_f32_16x16x32_bf16 v[48:51], v[172:175], v[180:183], v[48:51]
	v_mfma_f32_16x16x32_bf16 v[36:39], v[164:167], v[188:191], v[36:39]
	v_mfma_f32_16x16x32_bf16 v[32:35], v[172:175], v[188:191], v[32:35]
	v_mfma_f32_16x16x32_bf16 v[20:23], v[164:167], v[208:211], v[20:23]
	v_mfma_f32_16x16x32_bf16 v[16:19], v[172:175], v[208:211], v[16:19]
	v_mfma_f32_16x16x32_bf16 v[4:7], v[164:167], v[222:225], v[4:7]
	v_mfma_f32_16x16x32_bf16 v[0:3], v[172:175], v[222:225], v[0:3]
	s_setprio 0
	s_barrier
	s_add_i32 s82, s82, 2
	s_add_u32 s78, s78, 0x100
	s_addc_u32 s79, s79, 0
	s_add_u32 s28, s28, 0x100
	s_addc_u32 s29, s29, 0
	s_cmp_gt_u32 s82, 13
	s_cbranch_scc0 .LBB0_1121
	v_lshl_add_u32 v159, s26, 8, v144
	v_lshl_or_b32 v158, s8, 8, v146
	v_lshlrev_b32_e32 v159, 11, v159
	v_lshl_add_u32 v159, v158, 1, v159
	v_add_u32_e32 v218, 0x8000, v159
	v_add_u32_e32 v219, 0x10000, v159
	v_add_u32_e32 v240, 0x18000, v159
	v_add_u32_e32 v241, 0x40000, v159
	v_add_u32_e32 v245, 0x48000, v159
	v_add_u32_e32 v246, 0x50000, v159
	v_add_u32_e32 v247, 0x58000, v159
	global_load_dwordx4 v[160:163], v159, s[12:13]
	global_load_dwordx4 v[164:167], v159, s[12:13] offset:256
	global_load_dwordx4 v[168:171], v218, s[12:13]
	global_load_dwordx4 v[172:175], v218, s[12:13] offset:256
	global_load_dwordx4 v[176:179], v219, s[12:13]
	global_load_dwordx4 v[180:183], v219, s[12:13] offset:256
	global_load_dwordx4 v[184:187], v240, s[12:13]
	global_load_dwordx4 v[188:191], v240, s[12:13] offset:256
	global_load_dwordx4 v[204:207], v241, s[12:13]
	global_load_dwordx4 v[208:211], v241, s[12:13] offset:256
	global_load_dwordx4 v[220:223], v245, s[12:13]
	global_load_dwordx4 v[224:227], v245, s[12:13] offset:256
	global_load_dwordx4 v[228:231], v246, s[12:13]
	global_load_dwordx4 v[232:235], v246, s[12:13] offset:256
	global_load_dwordx4 v[236:239], v247, s[12:13]
	global_load_dwordx4 v[248:251], v247, s[12:13] offset:256
	s_and_b64 vcc, exec, s[16:17]
	s_cbranch_vccz .LBB0_1124
	s_barrier

; #define PG8_STAGE(bufoff, gbase, voff) do { _Pragma("unroll") for (int _i = 0; _i < 2; ++_i) \
;         __builtin_amdgcn_global_load_lds((const unsigned*)((const char*)(gbase) + (voff)[_i]), (PG8_LAS unsigned*)(lds + (bufoff) + ldsw + _i * 8192), 16, 0, 0); } while (0)
; #define PG8_LDA(dst, b, h) do { _Pragma("unroll") for (int m = 0; m < 4; ++m) _Pragma("unroll") for (int k = 0; k < 2; ++k) dst[m][k] = *(const PG8_LAS bf16x8*)(lds + PG8_SA(b, h) + aoff + m * 2048 + k * 1024); } while (0)
; #define PG8_LDB(dst, b, h) do { _Pragma("unroll") for (int n = 0; n < 2; ++n) _Pragma("unroll") for (int k = 0; k < 2; ++k) dst[n][k] = *(const PG8_LAS bf16x8*)(lds + PG8_SB(b, h) + boff + n * 2048 + k * 1024); } while (0)
; #define PG8_MMA(ai, bj, At, Bt) do { __builtin_amdgcn_s_setprio(1); _Pragma("unroll") for (int m = 0; m < 4; ++m) _Pragma("unroll") for (int n = 0; n < 2; ++n) _Pragma("unroll") for (int k = 0; k < 2; ++k) \
;         acc[ai][bj][m][n] = __builtin_amdgcn_mfma_f32_16x16x32_bf16(Bt[n][k], At[m][k], acc[ai][bj][m][n], 0, 0, 0); __builtin_amdgcn_s_setprio(0); } while (0)
; #define PG8_WAIT_V(n) asm volatile("s_waitcnt vmcnt(" #n ")" ::: "memory")
; #define PG8_BAR __builtin_amdgcn_s_barrier()
; template <class Epi, class Sched, bool ALIGN_EPI = false, bool SP2 = false>
; __device__ __forceinline__ void gemm_phase(PG8_LAS unsigned char* lds, const Gemm g, const Sched& S, const Epi& E) {
;     ...
;         for (int t = 0; t < nt; t += 2) {
;             const bool last = (t == nt - 2);
;             const char* a1 = cA + (size_t)(t + 1) * kstep;
;             const char* a2 = last ? nA : cA + (size_t)(t + 2) * kstep; const char* b2 = last ? nB : cB + (size_t)(t + 2) * kstep;
;             const char* a3 = a2 + kstep; const char* b3 = b2 + kstep;
;             if (last && has_next) S.a_ready(nxt);
;             if constexpr (SP2) {
;             PG8_LDB(B0, 0, 0); PG8_LDB(B1, 0, 1); PG8_SCHED; PG8_LDA(At, 0, 0); PG8_STAGE(PG8_SA(1, 1), a1 + hstepA, voffA);
;             PG8_WAIT_V(8); PG8_WAIT_L(0); PG8_BAR; PG8_MMA(0, 0, At, B0); PG8_MMA(0, 1, At, B1); PG8_BAR; PG8_SCHED;
;             PG8_LDA(At, 0, 1); PG8_STAGE(PG8_SB(0, 0), b2, voffB); PG8_STAGE(PG8_SB(0, 1), b2 + hstepB, voffB); PG8_STAGE(PG8_SA(0, 0), a2, voffA);
;             PG8_WAIT_V(8); PG8_WAIT_L(0); PG8_BAR; PG8_MMA(1, 0, At, B0); PG8_MMA(1, 1, At, B1); PG8_BAR; PG8_SCHED;
.LBB0_1319:
	v_add_u32_e32 v142, s35, v145
	ds_read_b128 v[138:141], v142
	ds_read_b128 v[148:151], v142 offset:1024
	ds_read_b128 v[152:155], v142 offset:2048
	ds_read_b128 v[156:159], v142 offset:3072
	v_add_u32_e32 v142, s38, v145
	ds_read_b128 v[160:163], v142
	ds_read_b128 v[164:167], v142 offset:1024
	ds_read_b128 v[168:171], v142 offset:2048
	ds_read_b128 v[172:175], v142 offset:3072
	s_add_u32 s22, s20, 0x100
	s_addc_u32 s23, s21, 0
	s_cmp_eq_u32 s78, 40
	s_cselect_b32 s27, s9, s23
	s_cselect_b32 s26, s8, s22
	s_cselect_b32 s25, s19, s75
	s_cselect_b32 s24, s18, s74
	v_lshl_add_u64 v[142:143], s[20:21], 0, v[136:137]
	s_add_i32 m0, s41, 0xc000
	ds_read_b128 v[176:179], v147
	ds_read_b128 v[180:183], v147 offset:1024
	ds_read_b128 v[184:187], v147 offset:2048
	ds_read_b128 v[188:191], v147 offset:3072
	ds_read_b128 v[204:207], v147 offset:4096
	ds_read_b128 v[208:211], v147 offset:5120
	ds_read_b128 v[218:221], v147 offset:6144
	ds_read_b128 v[222:225], v147 offset:7168
	global_load_lds_dwordx4 v[142:143], off
	v_lshl_add_u64 v[142:143], s[20:21], 0, v[134:135]
	s_add_i32 m0, s41, 0xe000
	s_nop 0
	global_load_lds_dwordx4 v[142:143], off
	s_waitcnt vmcnt(8)
	s_waitcnt lgkmcnt(0)
	s_barrier
	s_setprio 1
	s_waitcnt lgkmcnt(0)
	v_mfma_f32_16x16x32_bf16 v[124:127], v[138:141], v[176:179], v[124:127]
	v_mfma_f32_16x16x32_bf16 v[120:123], v[152:155], v[176:179], v[120:123]
	v_mfma_f32_16x16x32_bf16 v[108:111], v[138:141], v[184:187], v[108:111]
	v_mfma_f32_16x16x32_bf16 v[104:107], v[152:155], v[184:187], v[104:107]
	v_mfma_f32_16x16x32_bf16 v[92:95], v[138:141], v[204:207], v[92:95]
	v_mfma_f32_16x16x32_bf16 v[88:91], v[152:155], v[204:207], v[88:91]
	v_mfma_f32_16x16x32_bf16 v[76:79], v[138:141], v[218:221], v[76:79]
	v_mfma_f32_16x16x32_bf16 v[72:75], v[152:155], v[218:221], v[72:75]
	v_mfma_f32_16x16x32_bf16 v[124:127], v[148:151], v[180:183], v[124:127]
	v_mfma_f32_16x16x32_bf16 v[120:123], v[156:159], v[180:183], v[120:123]
	v_mfma_f32_16x16x32_bf16 v[108:111], v[148:151], v[188:191], v[108:111]
	v_mfma_f32_16x16x32_bf16 v[104:107], v[156:159], v[188:191], v[104:107]
	v_mfma_f32_16x16x32_bf16 v[92:95], v[148:151], v[208:211], v[92:95]
	v_mfma_f32_16x16x32_bf16 v[88:91], v[156:159], v[208:211], v[88:91]
	v_mfma_f32_16x16x32_bf16 v[76:79], v[148:151], v[222:225], v[76:79]
	v_mfma_f32_16x16x32_bf16 v[72:75], v[156:159], v[222:225], v[72:75]
	s_setprio 0
	s_setprio 1
	v_mfma_f32_16x16x32_bf16 v[116:119], v[160:163], v[176:179], v[116:119]
	v_mfma_f32_16x16x32_bf16 v[112:115], v[168:171], v[176:179], v[112:115]
	v_mfma_f32_16x16x32_bf16 v[100:103], v[160:163], v[184:187], v[100:103]
	v_mfma_f32_16x16x32_bf16 v[96:99], v[168:171], v[184:187], v[96:99]
	v_mfma_f32_16x16x32_bf16 v[84:87], v[160:163], v[204:207], v[84:87]
	v_mfma_f32_16x16x32_bf16 v[80:83], v[168:171], v[204:207], v[80:83]
	v_mfma_f32_16x16x32_bf16 v[68:71], v[160:163], v[218:221], v[68:71]
	v_mfma_f32_16x16x32_bf16 v[64:67], v[168:171], v[218:221], v[64:67]
	v_mfma_f32_16x16x32_bf16 v[116:119], v[164:167], v[180:183], v[116:119]
	v_mfma_f32_16x16x32_bf16 v[112:115], v[172:175], v[180:183], v[112:115]
	v_mfma_f32_16x16x32_bf16 v[100:103], v[164:167], v[188:191], v[100:103]
	v_mfma_f32_16x16x32_bf16 v[96:99], v[172:175], v[188:191], v[96:99]
	v_mfma_f32_16x16x32_bf16 v[84:87], v[164:167], v[208:211], v[84:87]
	v_mfma_f32_16x16x32_bf16 v[80:83], v[172:175], v[208:211], v[80:83]
	v_mfma_f32_16x16x32_bf16 v[68:71], v[164:167], v[222:225], v[68:71]
	v_mfma_f32_16x16x32_bf16 v[64:67], v[172:175], v[222:225], v[64:67]
	s_setprio 0
	s_barrier
	s_mov_b32 m0, s36
	v_lshl_add_u64 v[142:143], s[24:25], 0, v[192:193]
	s_add_u32 s20, s24, 0xb0000
	ds_read_b128 v[176:179], v147 offset:16384
	ds_read_b128 v[180:183], v147 offset:17408
	ds_read_b128 v[184:187], v147 offset:18432
	ds_read_b128 v[188:191], v147 offset:19456
	ds_read_b128 v[204:207], v147 offset:20480
	ds_read_b128 v[208:211], v147 offset:21504
	ds_read_b128 v[218:221], v147 offset:22528
	ds_read_b128 v[222:225], v147 offset:23552
	global_load_lds_dwordx4 v[142:143], off
	v_lshl_add_u64 v[194:195], s[24:25], 0, v[132:133]
	s_mov_b32 m0, s37
	s_addc_u32 s21, s25, 0
	global_load_lds_dwordx4 v[194:195], off
	v_lshl_add_u64 v[226:227], s[20:21], 0, v[192:193]
	s_mov_b32 m0, s39
	v_lshl_add_u64 v[228:229], s[26:27], 0, v[130:131]
	global_load_lds_dwordx4 v[226:227], off
	v_lshl_add_u64 v[226:227], s[20:21], 0, v[132:133]
	s_mov_b32 m0, s40
	s_nop 0
	global_load_lds_dwordx4 v[226:227], off
	v_lshl_add_u64 v[226:227], s[26:27], 0, v[128:129]
	s_mov_b32 m0, s41
	s_nop 0
	global_load_lds_dwordx4 v[226:227], off
	s_mov_b32 m0, s42
	s_nop 0
	global_load_lds_dwordx4 v[228:229], off
	s_waitcnt vmcnt(8)
	s_waitcnt lgkmcnt(0)
	s_barrier
; #define PG8_STAGE(bufoff, gbase, voff) do { _Pragma("unroll") for (int _i = 0; _i < 2; ++_i) \
;         __builtin_amdgcn_global_load_lds((const unsigned*)((const char*)(gbase) + (voff)[_i]), (PG8_LAS unsigned*)(lds + (bufoff) + ldsw + _i * 8192), 16, 0, 0); } while (0)
; #define PG8_LDA(dst, b, h) do { _Pragma("unroll") for (int m = 0; m < 4; ++m) _Pragma("unroll") for (int k = 0; k < 2; ++k) dst[m][k] = *(const PG8_LAS bf16x8*)(lds + PG8_SA(b, h) + aoff + m * 2048 + k * 1024); } while (0)
; #define PG8_LDB(dst, b, h) do { _Pragma("unroll") for (int n = 0; n < 2; ++n) _Pragma("unroll") for (int k = 0; k < 2; ++k) dst[n][k] = *(const PG8_LAS bf16x8*)(lds + PG8_SB(b, h) + boff + n * 2048 + k * 1024); } while (0)
; #define PG8_MMA(ai, bj, At, Bt) do { __builtin_amdgcn_s_setprio(1); _Pragma("unroll") for (int m = 0; m < 4; ++m) _Pragma("unroll") for (int n = 0; n < 2; ++n) _Pragma("unroll") for (int k = 0; k < 2; ++k) \
;         acc[ai][bj][m][n] = __builtin_amdgcn_mfma_f32_16x16x32_bf16(Bt[n][k], At[m][k], acc[ai][bj][m][n], 0, 0, 0); __builtin_amdgcn_s_setprio(0); } while (0)
; #define PG8_WAIT_V(n) asm volatile("s_waitcnt vmcnt(" #n ")" ::: "memory")
; #define PG8_WAIT_L(n) asm volatile("s_waitcnt lgkmcnt(" #n ")" ::: "memory")
; #define PG8_BAR __builtin_amdgcn_s_barrier()
; #define PG8_SCHED __builtin_amdgcn_sched_barrier(0)
; template <class Epi, class Sched, bool ALIGN_EPI = false, bool SP2 = false>
; __device__ __forceinline__ void gemm_phase(PG8_LAS unsigned char* lds, const Gemm g, const Sched& S, const Epi& E) {
;     ...
;             PG8_WAIT_V(8); PG8_WAIT_L(0); PG8_BAR; PG8_MMA(1, 0, At, B0); PG8_MMA(1, 1, At, B1); PG8_BAR; PG8_SCHED;
;             PG8_LDB(B0, 1, 0); PG8_LDB(B1, 1, 1); PG8_SCHED; PG8_LDA(At, 1, 0); PG8_STAGE(PG8_SA(0, 1), a2 + hstepA, voffA);
;             PG8_WAIT_V(8); PG8_WAIT_L(0); PG8_BAR; PG8_MMA(0, 0, At, B0); PG8_MMA(0, 1, At, B1); PG8_BAR; PG8_SCHED;
	s_setprio 1
	s_waitcnt lgkmcnt(0)
	v_mfma_f32_16x16x32_bf16 v[60:63], v[138:141], v[176:179], v[60:63]
	v_mfma_f32_16x16x32_bf16 v[56:59], v[152:155], v[176:179], v[56:59]
	v_mfma_f32_16x16x32_bf16 v[44:47], v[138:141], v[184:187], v[44:47]
	v_mfma_f32_16x16x32_bf16 v[40:43], v[152:155], v[184:187], v[40:43]
	v_mfma_f32_16x16x32_bf16 v[28:31], v[138:141], v[204:207], v[28:31]
	v_mfma_f32_16x16x32_bf16 v[24:27], v[152:155], v[204:207], v[24:27]
	v_mfma_f32_16x16x32_bf16 v[12:15], v[138:141], v[218:221], v[12:15]
	v_mfma_f32_16x16x32_bf16 v[8:11], v[152:155], v[218:221], v[8:11]
	v_mfma_f32_16x16x32_bf16 v[60:63], v[148:151], v[180:183], v[60:63]
	v_mfma_f32_16x16x32_bf16 v[56:59], v[156:159], v[180:183], v[56:59]
	v_mfma_f32_16x16x32_bf16 v[44:47], v[148:151], v[188:191], v[44:47]
	v_mfma_f32_16x16x32_bf16 v[40:43], v[156:159], v[188:191], v[40:43]
	v_mfma_f32_16x16x32_bf16 v[28:31], v[148:151], v[208:211], v[28:31]
	v_mfma_f32_16x16x32_bf16 v[24:27], v[156:159], v[208:211], v[24:27]
	v_mfma_f32_16x16x32_bf16 v[12:15], v[148:151], v[222:225], v[12:15]
	v_mfma_f32_16x16x32_bf16 v[8:11], v[156:159], v[222:225], v[8:11]
	s_setprio 0
	s_setprio 1
	v_mfma_f32_16x16x32_bf16 v[52:55], v[160:163], v[176:179], v[52:55]
	v_mfma_f32_16x16x32_bf16 v[48:51], v[168:171], v[176:179], v[48:51]
	v_mfma_f32_16x16x32_bf16 v[36:39], v[160:163], v[184:187], v[36:39]
	v_mfma_f32_16x16x32_bf16 v[32:35], v[168:171], v[184:187], v[32:35]
	v_mfma_f32_16x16x32_bf16 v[20:23], v[160:163], v[204:207], v[20:23]
	v_mfma_f32_16x16x32_bf16 v[16:19], v[168:171], v[204:207], v[16:19]
	v_mfma_f32_16x16x32_bf16 v[4:7], v[160:163], v[218:221], v[4:7]
	v_mfma_f32_16x16x32_bf16 v[0:3], v[168:171], v[218:221], v[0:3]
	v_mfma_f32_16x16x32_bf16 v[52:55], v[164:167], v[180:183], v[52:55]
	v_mfma_f32_16x16x32_bf16 v[48:51], v[172:175], v[180:183], v[48:51]
	v_mfma_f32_16x16x32_bf16 v[36:39], v[164:167], v[188:191], v[36:39]
	v_mfma_f32_16x16x32_bf16 v[32:35], v[172:175], v[188:191], v[32:35]
	v_mfma_f32_16x16x32_bf16 v[20:23], v[164:167], v[208:211], v[20:23]
	v_mfma_f32_16x16x32_bf16 v[16:19], v[172:175], v[208:211], v[16:19]
	v_mfma_f32_16x16x32_bf16 v[4:7], v[164:167], v[222:225], v[4:7]
	v_mfma_f32_16x16x32_bf16 v[0:3], v[172:175], v[222:225], v[0:3]
	s_setprio 0
	s_barrier
	v_add_u32_e32 v156, s48, v145
	v_add_u32_e32 v172, s61, v145
	ds_read_b128 v[138:141], v156
	ds_read_b128 v[148:151], v156 offset:1024
	ds_read_b128 v[152:155], v156 offset:2048
	ds_read_b128 v[156:159], v156 offset:3072
	ds_read_b128 v[160:163], v172
	ds_read_b128 v[164:167], v172 offset:1024
	ds_read_b128 v[168:171], v172 offset:2048
	ds_read_b128 v[172:175], v172 offset:3072
	s_add_u32 s20, s26, 0xb0000
	s_addc_u32 s21, s27, 0
	s_mov_b32 m0, s43
	v_lshl_add_u64 v[230:231], s[20:21], 0, v[128:129]
	ds_read_b128 v[176:179], v147 offset:32768
	ds_read_b128 v[180:183], v147 offset:33792
	ds_read_b128 v[184:187], v147 offset:34816
	ds_read_b128 v[188:191], v147 offset:35840
	ds_read_b128 v[204:207], v147 offset:36864
	ds_read_b128 v[208:211], v147 offset:37888
	ds_read_b128 v[218:221], v147 offset:38912
	ds_read_b128 v[222:225], v147 offset:39936
	global_load_lds_dwordx4 v[230:231], off
	v_lshl_add_u64 v[230:231], s[20:21], 0, v[130:131]
	s_mov_b32 m0, s44
	s_nop 0
	global_load_lds_dwordx4 v[230:231], off
	s_waitcnt vmcnt(8)
	s_waitcnt lgkmcnt(0)
	s_barrier
	s_setprio 1
	s_waitcnt lgkmcnt(0)
	v_mfma_f32_16x16x32_bf16 v[124:127], v[138:141], v[176:179], v[124:127]
	v_mfma_f32_16x16x32_bf16 v[120:123], v[152:155], v[176:179], v[120:123]
	v_mfma_f32_16x16x32_bf16 v[108:111], v[138:141], v[184:187], v[108:111]
	v_mfma_f32_16x16x32_bf16 v[104:107], v[152:155], v[184:187], v[104:107]
	v_mfma_f32_16x16x32_bf16 v[92:95], v[138:141], v[204:207], v[92:95]
	v_mfma_f32_16x16x32_bf16 v[88:91], v[152:155], v[204:207], v[88:91]
	v_mfma_f32_16x16x32_bf16 v[76:79], v[138:141], v[218:221], v[76:79]
	v_mfma_f32_16x16x32_bf16 v[72:75], v[152:155], v[218:221], v[72:75]
	v_mfma_f32_16x16x32_bf16 v[124:127], v[148:151], v[180:183], v[124:127]
	v_mfma_f32_16x16x32_bf16 v[120:123], v[156:159], v[180:183], v[120:123]
	v_mfma_f32_16x16x32_bf16 v[108:111], v[148:151], v[188:191], v[108:111]
	v_mfma_f32_16x16x32_bf16 v[104:107], v[156:159], v[188:191], v[104:107]
	v_mfma_f32_16x16x32_bf16 v[92:95], v[148:151], v[208:211], v[92:95]
	v_mfma_f32_16x16x32_bf16 v[88:91], v[156:159], v[208:211], v[88:91]
	v_mfma_f32_16x16x32_bf16 v[76:79], v[148:151], v[222:225], v[76:79]
	v_mfma_f32_16x16x32_bf16 v[72:75], v[156:159], v[222:225], v[72:75]
	s_setprio 0
	s_setprio 1
	v_mfma_f32_16x16x32_bf16 v[116:119], v[160:163], v[176:179], v[116:119]
	v_mfma_f32_16x16x32_bf16 v[112:115], v[168:171], v[176:179], v[112:115]
	v_mfma_f32_16x16x32_bf16 v[100:103], v[160:163], v[184:187], v[100:103]
	v_mfma_f32_16x16x32_bf16 v[96:99], v[168:171], v[184:187], v[96:99]
	v_mfma_f32_16x16x32_bf16 v[84:87], v[160:163], v[204:207], v[84:87]
	v_mfma_f32_16x16x32_bf16 v[80:83], v[168:171], v[204:207], v[80:83]
	v_mfma_f32_16x16x32_bf16 v[68:71], v[160:163], v[218:221], v[68:71]
	v_mfma_f32_16x16x32_bf16 v[64:67], v[168:171], v[218:221], v[64:67]
	v_mfma_f32_16x16x32_bf16 v[116:119], v[164:167], v[180:183], v[116:119]
	v_mfma_f32_16x16x32_bf16 v[112:115], v[172:175], v[180:183], v[112:115]
	v_mfma_f32_16x16x32_bf16 v[100:103], v[164:167], v[188:191], v[100:103]
	v_mfma_f32_16x16x32_bf16 v[96:99], v[172:175], v[188:191], v[96:99]
	v_mfma_f32_16x16x32_bf16 v[84:87], v[164:167], v[208:211], v[84:87]
	v_mfma_f32_16x16x32_bf16 v[80:83], v[172:175], v[208:211], v[80:83]
	v_mfma_f32_16x16x32_bf16 v[68:71], v[164:167], v[222:225], v[68:71]
	v_mfma_f32_16x16x32_bf16 v[64:67], v[172:175], v[222:225], v[64:67]
	s_setprio 0
	s_barrier
; #define PG8_STAGE(bufoff, gbase, voff) do { _Pragma("unroll") for (int _i = 0; _i < 2; ++_i) \
;         __builtin_amdgcn_global_load_lds((const unsigned*)((const char*)(gbase) + (voff)[_i]), (PG8_LAS unsigned*)(lds + (bufoff) + ldsw + _i * 8192), 16, 0, 0); } while (0)
; #define PG8_LDA(dst, b, h) do { _Pragma("unroll") for (int m = 0; m < 4; ++m) _Pragma("unroll") for (int k = 0; k < 2; ++k) dst[m][k] = *(const PG8_LAS bf16x8*)(lds + PG8_SA(b, h) + aoff + m * 2048 + k * 1024); } while (0)
; #define PG8_LDB(dst, b, h) do { _Pragma("unroll") for (int n = 0; n < 2; ++n) _Pragma("unroll") for (int k = 0; k < 2; ++k) dst[n][k] = *(const PG8_LAS bf16x8*)(lds + PG8_SB(b, h) + boff + n * 2048 + k * 1024); } while (0)
; #define PG8_WAIT_V(n) asm volatile("s_waitcnt vmcnt(" #n ")" ::: "memory")
; #define PG8_WAIT_L(n) asm volatile("s_waitcnt lgkmcnt(" #n ")" ::: "memory")
; #define PG8_BAR __builtin_amdgcn_s_barrier()
; #define PG8_SCHED __builtin_amdgcn_sched_barrier(0)
; template <class Epi, class Sched, bool ALIGN_EPI = false, bool SP2 = false>
; __device__ __forceinline__ void gemm_phase(PG8_LAS unsigned char* lds, const Gemm g, const Sched& S, const Epi& E) {
;     ...
;             PG8_LDB(B0, 1, 0); PG8_LDB(B1, 1, 1); PG8_SCHED; PG8_LDA(At, 1, 0); PG8_STAGE(PG8_SA(0, 1), a2 + hstepA, voffA);
;             PG8_WAIT_V(8); PG8_WAIT_L(0); PG8_BAR; PG8_MMA(0, 0, At, B0); PG8_MMA(0, 1, At, B1); PG8_BAR; PG8_SCHED;
;             PG8_LDA(At, 1, 1); PG8_STAGE(PG8_SB(1, 0), b3, voffB); PG8_STAGE(PG8_SB(1, 1), b3 + hstepB, voffB); PG8_STAGE(PG8_SA(1, 0), a3, voffA);
;             PG8_WAIT_V(8); PG8_WAIT_L(0); PG8_BAR; PG8_MMA(1, 0, At, B0); PG8_MMA(1, 1, At, B1); PG8_BAR; PG8_SCHED;
;     __device__ __forceinline__ void operator()(const f32x4 (&acc)[2][2][4][2], const pg8::Unit& u, int wr, int wc, int fr, int fq) const {
;         const int row0 = u.pm * 256 + wr * 64 + fr, col0 = u.pn * 256 + wc * 32 + 8 * fq;
; #pragma unroll
;         for (int ai = 0; ai < 2; ++ai)
; #pragma unroll
;             for (int m = 0; m < 4; ++m) {
;                 const int row = row0 + ai * 128 + m * 16; float ss = 0.f;
; #pragma unroll
;                 for (int bj = 0; bj < 2; ++bj) {
;                     const size_t off = (size_t)row * DM + col0 + bj * 128;
;                     const v4u b = *(const v4u*)(xb + off);
	s_mov_b32 m0, s49
	v_lshl_add_u64 v[142:143], v[142:143], 0, s[76:77]
	s_add_u32 s20, s24, 0xb0080
	ds_read_b128 v[176:179], v147 offset:49152
	ds_read_b128 v[180:183], v147 offset:50176
	ds_read_b128 v[184:187], v147 offset:51200
	ds_read_b128 v[188:191], v147 offset:52224
	ds_read_b128 v[204:207], v147 offset:53248
	ds_read_b128 v[208:211], v147 offset:54272
	ds_read_b128 v[218:221], v147 offset:55296
	ds_read_b128 v[222:225], v147 offset:56320
	global_load_lds_dwordx4 v[142:143], off
	v_lshl_add_u64 v[142:143], v[194:195], 0, s[76:77]
	s_mov_b32 m0, s50
	s_addc_u32 s21, s25, 0
	global_load_lds_dwordx4 v[142:143], off
	v_lshl_add_u64 v[142:143], s[20:21], 0, v[192:193]
	s_mov_b32 m0, s64
	s_nop 0
	global_load_lds_dwordx4 v[142:143], off
	v_lshl_add_u64 v[142:143], s[20:21], 0, v[132:133]
	s_mov_b32 m0, s65
	s_nop 0
	global_load_lds_dwordx4 v[142:143], off
	v_lshl_add_u64 v[142:143], v[226:227], 0, s[76:77]
	s_mov_b32 m0, s51
	s_nop 0
	global_load_lds_dwordx4 v[142:143], off
	v_lshl_add_u64 v[142:143], v[228:229], 0, s[76:77]
	s_mov_b32 m0, s60
	s_nop 0
	global_load_lds_dwordx4 v[142:143], off
	s_waitcnt vmcnt(8)
	s_waitcnt lgkmcnt(0)
	s_barrier
	s_setprio 1
	s_waitcnt lgkmcnt(0)
	v_mfma_f32_16x16x32_bf16 v[60:63], v[138:141], v[176:179], v[60:63]
	v_mfma_f32_16x16x32_bf16 v[56:59], v[152:155], v[176:179], v[56:59]
	v_mfma_f32_16x16x32_bf16 v[44:47], v[138:141], v[184:187], v[44:47]
	v_mfma_f32_16x16x32_bf16 v[40:43], v[152:155], v[184:187], v[40:43]
	v_mfma_f32_16x16x32_bf16 v[28:31], v[138:141], v[204:207], v[28:31]
	v_mfma_f32_16x16x32_bf16 v[24:27], v[152:155], v[204:207], v[24:27]
	v_mfma_f32_16x16x32_bf16 v[12:15], v[138:141], v[218:221], v[12:15]
	v_mfma_f32_16x16x32_bf16 v[8:11], v[152:155], v[218:221], v[8:11]
	v_mfma_f32_16x16x32_bf16 v[60:63], v[148:151], v[180:183], v[60:63]
	v_mfma_f32_16x16x32_bf16 v[56:59], v[156:159], v[180:183], v[56:59]
	v_mfma_f32_16x16x32_bf16 v[44:47], v[148:151], v[188:191], v[44:47]
	v_mfma_f32_16x16x32_bf16 v[40:43], v[156:159], v[188:191], v[40:43]
	v_mfma_f32_16x16x32_bf16 v[28:31], v[148:151], v[208:211], v[28:31]
	v_mfma_f32_16x16x32_bf16 v[24:27], v[156:159], v[208:211], v[24:27]
	v_mfma_f32_16x16x32_bf16 v[12:15], v[148:151], v[222:225], v[12:15]
	v_mfma_f32_16x16x32_bf16 v[8:11], v[156:159], v[222:225], v[8:11]
	s_setprio 0
	s_setprio 1
	v_mfma_f32_16x16x32_bf16 v[52:55], v[160:163], v[176:179], v[52:55]
	v_mfma_f32_16x16x32_bf16 v[48:51], v[168:171], v[176:179], v[48:51]
	v_mfma_f32_16x16x32_bf16 v[36:39], v[160:163], v[184:187], v[36:39]
	v_mfma_f32_16x16x32_bf16 v[32:35], v[168:171], v[184:187], v[32:35]
	v_mfma_f32_16x16x32_bf16 v[20:23], v[160:163], v[204:207], v[20:23]
	v_mfma_f32_16x16x32_bf16 v[16:19], v[168:171], v[204:207], v[16:19]
	v_mfma_f32_16x16x32_bf16 v[4:7], v[160:163], v[218:221], v[4:7]
	v_mfma_f32_16x16x32_bf16 v[0:3], v[168:171], v[218:221], v[0:3]
	v_mfma_f32_16x16x32_bf16 v[52:55], v[164:167], v[180:183], v[52:55]
	v_mfma_f32_16x16x32_bf16 v[48:51], v[172:175], v[180:183], v[48:51]
	v_mfma_f32_16x16x32_bf16 v[36:39], v[164:167], v[188:191], v[36:39]
	v_mfma_f32_16x16x32_bf16 v[32:35], v[172:175], v[188:191], v[32:35]
	v_mfma_f32_16x16x32_bf16 v[20:23], v[164:167], v[208:211], v[20:23]
	v_mfma_f32_16x16x32_bf16 v[16:19], v[172:175], v[208:211], v[16:19]
	v_mfma_f32_16x16x32_bf16 v[4:7], v[164:167], v[222:225], v[4:7]
	v_mfma_f32_16x16x32_bf16 v[0:3], v[172:175], v[222:225], v[0:3]
	s_setprio 0
	s_barrier
	s_add_i32 s78, s78, 2
	s_add_u32 s74, s74, 0x100
	s_addc_u32 s75, s75, 0
	s_cmp_gt_u32 s78, 41
	s_mov_b64 s[20:21], s[22:23]
	s_cbranch_scc0 .LBB0_1319
	v_lshl_add_u32 v159, s68, 8, v144
	v_lshl_or_b32 v158, s34, 8, v146
	v_lshlrev_b32_e32 v159, 11, v159
	v_lshl_add_u32 v159, v158, 1, v159
	v_add_u32_e32 v218, 0x8000, v159
	v_add_u32_e32 v219, 0x10000, v159
	v_add_u32_e32 v240, 0x18000, v159
	v_add_u32_e32 v241, 0x40000, v159
	v_add_u32_e32 v245, 0x48000, v159
	v_add_u32_e32 v246, 0x50000, v159
	v_add_u32_e32 v247, 0x58000, v159
	global_load_dwordx4 v[160:163], v159, s[12:13]
	global_load_dwordx4 v[164:167], v159, s[12:13] offset:256
	global_load_dwordx4 v[168:171], v218, s[12:13]
	global_load_dwordx4 v[172:175], v218, s[12:13] offset:256
	global_load_dwordx4 v[176:179], v219, s[12:13]
	global_load_dwordx4 v[180:183], v219, s[12:13] offset:256
	global_load_dwordx4 v[184:187], v240, s[12:13]
	global_load_dwordx4 v[188:191], v240, s[12:13] offset:256
	global_load_dwordx4 v[204:207], v241, s[12:13]
	global_load_dwordx4 v[208:211], v241, s[12:13] offset:256
	global_load_dwordx4 v[220:223], v245, s[12:13]
	global_load_dwordx4 v[224:227], v245, s[12:13] offset:256
	global_load_dwordx4 v[228:231], v246, s[12:13]
	global_load_dwordx4 v[232:235], v246, s[12:13] offset:256
	global_load_dwordx4 v[236:239], v247, s[12:13]
	global_load_dwordx4 v[248:251], v247, s[12:13] offset:256
	s_and_b64 vcc, exec, s[16:17]
	s_cbranch_vccz .LBB0_1322
	s_barrier
